# speedup vs baseline: 1.0048x; 1.0048x over previous
; #define PG8_STAGE(bufoff, gbase, voff) do { _Pragma("unroll") for (int _i = 0; _i < 2; ++_i) \
;         __builtin_amdgcn_global_load_lds((const unsigned*)((const char*)(gbase) + (voff)[_i]), (PG8_LAS unsigned*)(lds + (bufoff) + ldsw + _i * 8192), 16, 0, 0); } while (0)
; #define PG8_LDA(dst, b, h) do { _Pragma("unroll") for (int m = 0; m < 4; ++m) _Pragma("unroll") for (int k = 0; k < 2; ++k) dst[m][k] = *(const PG8_LAS bf16x8*)(lds + PG8_SA(b, h) + aoff + m * 2048 + k * 1024); } while (0)
; #define PG8_LDB(dst, b, h) do { _Pragma("unroll") for (int n = 0; n < 2; ++n) _Pragma("unroll") for (int k = 0; k < 2; ++k) dst[n][k] = *(const PG8_LAS bf16x8*)(lds + PG8_SB(b, h) + boff + n * 2048 + k * 1024); } while (0)
; #define PG8_WAIT_V(n) asm volatile("s_waitcnt vmcnt(" #n ")" ::: "memory")
; #define PG8_WAIT_L(n) asm volatile("s_waitcnt lgkmcnt(" #n ")" ::: "memory")
; #define PG8_BAR __builtin_amdgcn_s_barrier()
; #define PG8_SCHED __builtin_amdgcn_sched_barrier(0)
; template <class Epi, class Sched, bool ALIGN_EPI = false, bool SP2 = false>
; __device__ __forceinline__ void gemm_phase(PG8_LAS unsigned char* lds, const Gemm g, const Sched& S, const Epi& E, const int tid) {
;     ...
;         const bool has_next = S.next(ui + 1, nxt);
;         const char* nA = has_next ? (const char*)g.A + (size_t)nxt.pm * tstep : cA; const char* nB = has_next ? (const char*)g.Bt + (size_t)nxt.pn * tstep : cB;
;         for (int t = 0; t < nt; t += 2) {
;             const bool last = (t == nt - 2);
;             const char* a1 = cA + (size_t)(t + 1) * kstep;
;             const char* a2 = last ? nA : cA + (size_t)(t + 2) * kstep; const char* b2 = last ? nB : cB + (size_t)(t + 2) * kstep;
;             const char* a3 = a2 + kstep; const char* b3 = b2 + kstep;
;             if (last && has_next) S.a_ready(nxt);
;             if constexpr (SP2) {
;             PG8_LDB(B0, 0, 0); PG8_LDB(B1, 0, 1); PG8_SCHED; PG8_LDA(At, 0, 0); PG8_STAGE(PG8_SA(1, 1), a1 + hstep, voffA);
;             PG8_WAIT_V(8); PG8_WAIT_L(0); PG8_BAR; PG8_MMA(0, 0, At, B0); PG8_MMA(0, 1, At, B1); PG8_BAR; PG8_SCHED;
;             PG8_LDA(At, 0, 1); PG8_STAGE(PG8_SB(0, 0), b2, voffB); PG8_STAGE(PG8_SB(0, 1), b2 + hstep, voffB); PG8_STAGE(PG8_SA(0, 0), a2, voffA);
;             PG8_WAIT_V(8); PG8_WAIT_L(0); PG8_BAR; PG8_MMA(1, 0, At, B0); PG8_MMA(1, 1, At, B1); PG8_BAR; PG8_SCHED;
.LBB0_59:
	s_add_u32 s26, s26, 0x80
	s_addc_u32 s27, s27, 0
	s_add_u32 s36, s30, 0x100
	s_addc_u32 s37, s31, 0
	s_mov_b32 s30, 0
	s_add_i32 s44, s30, 2
	s_add_u32 s45, s26, 0x80
	s_addc_u32 s31, s27, 0
	s_add_i32 s63, 0, 0x10000
	s_cmp_eq_u32 s58, s30
	s_cselect_b32 s31, s21, s31
	s_cselect_b32 s30, s20, s45
	s_cselect_b32 s65, s23, s37
	s_cselect_b32 s64, s22, s36
	s_add_i32 s45, 0, 0x14000
	v_add_u32_e32 v154, s63, v143
	v_add_u32_e32 v158, s45, v143
	ds_read_b128 v[138:141], v154
	ds_read_b128 v[146:149], v154 offset:1024
	ds_read_b128 v[150:153], v154 offset:2048
	ds_read_b128 v[154:157], v154 offset:3072
	ds_read_b128 v[162:165], v158
	ds_read_b128 v[166:169], v158 offset:1024
	ds_read_b128 v[170:173], v158 offset:2048
	ds_read_b128 v[184:187], v158 offset:3072
	v_lshl_add_u64 v[158:159], s[26:27], 0, v[134:135]
	s_add_i32 m0, s47, 0xc000
	ds_read_b128 v[188:191], v145
	ds_read_b128 v[192:195], v145 offset:1024
	ds_read_b128 v[208:211], v145 offset:2048
	ds_read_b128 v[214:217], v145 offset:3072
	ds_read_b128 v[218:221], v145 offset:4096
	ds_read_b128 v[222:225], v145 offset:5120
	ds_read_b128 v[226:229], v145 offset:6144
	ds_read_b128 v[230:233], v145 offset:7168
	global_load_lds_dwordx4 v[158:159], off
	v_lshl_add_u64 v[158:159], s[26:27], 0, v[136:137]
	s_add_i32 m0, s47, 0xe000
	s_nop 0
	global_load_lds_dwordx4 v[158:159], off
	s_waitcnt vmcnt(24)
	s_waitcnt lgkmcnt(0)
	s_barrier
	s_setprio 1
	s_waitcnt lgkmcnt(0)
	v_mfma_f32_16x16x32_bf16 v[124:127], v[138:141], v[188:191], 0
	v_mfma_f32_16x16x32_bf16 v[120:123], v[150:153], v[188:191], 0
	v_mfma_f32_16x16x32_bf16 v[108:111], v[138:141], v[208:211], 0
	v_mfma_f32_16x16x32_bf16 v[104:107], v[150:153], v[208:211], 0
	v_mfma_f32_16x16x32_bf16 v[92:95], v[138:141], v[218:221], 0
	v_mfma_f32_16x16x32_bf16 v[88:91], v[150:153], v[218:221], 0
	v_mfma_f32_16x16x32_bf16 v[76:79], v[138:141], v[226:229], 0
	v_mfma_f32_16x16x32_bf16 v[72:75], v[150:153], v[226:229], 0
	v_mfma_f32_16x16x32_bf16 v[124:127], v[146:149], v[192:195], v[124:127]
	v_mfma_f32_16x16x32_bf16 v[120:123], v[154:157], v[192:195], v[120:123]
	v_mfma_f32_16x16x32_bf16 v[108:111], v[146:149], v[214:217], v[108:111]
	v_mfma_f32_16x16x32_bf16 v[104:107], v[154:157], v[214:217], v[104:107]
	v_mfma_f32_16x16x32_bf16 v[92:95], v[146:149], v[222:225], v[92:95]
	v_mfma_f32_16x16x32_bf16 v[88:91], v[154:157], v[222:225], v[88:91]
	v_mfma_f32_16x16x32_bf16 v[76:79], v[146:149], v[230:233], v[76:79]
	v_mfma_f32_16x16x32_bf16 v[72:75], v[154:157], v[230:233], v[72:75]
	v_mfma_f32_16x16x32_bf16 v[116:119], v[162:165], v[188:191], 0
	v_mfma_f32_16x16x32_bf16 v[112:115], v[170:173], v[188:191], 0
	v_mfma_f32_16x16x32_bf16 v[100:103], v[162:165], v[208:211], 0
	v_mfma_f32_16x16x32_bf16 v[96:99], v[170:173], v[208:211], 0
	v_mfma_f32_16x16x32_bf16 v[84:87], v[162:165], v[218:221], 0
	v_mfma_f32_16x16x32_bf16 v[80:83], v[170:173], v[218:221], 0
	v_mfma_f32_16x16x32_bf16 v[68:71], v[162:165], v[226:229], 0
	v_mfma_f32_16x16x32_bf16 v[64:67], v[170:173], v[226:229], 0
	v_mfma_f32_16x16x32_bf16 v[116:119], v[166:169], v[192:195], v[116:119]
	v_mfma_f32_16x16x32_bf16 v[112:115], v[184:187], v[192:195], v[112:115]
	v_mfma_f32_16x16x32_bf16 v[100:103], v[166:169], v[214:217], v[100:103]
	v_mfma_f32_16x16x32_bf16 v[96:99], v[184:187], v[214:217], v[96:99]
	v_mfma_f32_16x16x32_bf16 v[84:87], v[166:169], v[222:225], v[84:87]
	v_mfma_f32_16x16x32_bf16 v[80:83], v[184:187], v[222:225], v[80:83]
	v_mfma_f32_16x16x32_bf16 v[68:71], v[166:169], v[230:233], v[68:71]
	v_mfma_f32_16x16x32_bf16 v[64:67], v[184:187], v[230:233], v[64:67]
	s_setprio 0
	s_barrier
	s_add_i32 s63, s63, s46
	v_lshl_add_u64 v[158:159], s[64:65], 0, v[160:161]
	s_mov_b32 m0, s63
	ds_read_b128 v[188:191], v145 offset:16384
	ds_read_b128 v[192:195], v145 offset:17408
	ds_read_b128 v[208:211], v145 offset:18432
	ds_read_b128 v[214:217], v145 offset:19456
	ds_read_b128 v[218:221], v145 offset:20480
	ds_read_b128 v[222:225], v145 offset:21504
	ds_read_b128 v[226:229], v145 offset:22528
	ds_read_b128 v[230:233], v145 offset:23552
	global_load_lds_dwordx4 v[158:159], off
	s_add_i32 m0, s63, 0x2000
	v_lshl_add_u64 v[174:175], s[64:65], 0, v[132:133]
	s_add_u32 s64, s64, s12
	s_addc_u32 s65, s65, 0
	s_add_i32 s45, s45, s46
	global_load_lds_dwordx4 v[174:175], off
	v_lshl_add_u64 v[178:179], s[64:65], 0, v[160:161]
	s_mov_b32 m0, s45
	v_lshl_add_u64 v[180:181], s[64:65], 0, v[132:133]
	global_load_lds_dwordx4 v[178:179], off
	s_add_i32 m0, s45, 0x2000
	v_lshl_add_u64 v[196:197], s[30:31], 0, v[128:129]
	global_load_lds_dwordx4 v[180:181], off
	s_mov_b32 m0, s47
	v_lshl_add_u64 v[198:199], s[30:31], 0, v[130:131]
	global_load_lds_dwordx4 v[196:197], off
	s_mov_b32 m0, s48
	s_nop 0
	global_load_lds_dwordx4 v[198:199], off
	s_cmp_lt_u32 s59, 2
	s_cbranch_scc1 .Lmy_w8_0
	s_waitcnt vmcnt(24)
	s_branch .Lmy_wj_0

; #define PG8_STAGE(bufoff, gbase, voff) do { _Pragma("unroll") for (int _i = 0; _i < 2; ++_i) \
;         __builtin_amdgcn_global_load_lds((const unsigned*)((const char*)(gbase) + (voff)[_i]), (PG8_LAS unsigned*)(lds + (bufoff) + ldsw + _i * 8192), 16, 0, 0); } while (0)
; #define PG8_LDA(dst, b, h) do { _Pragma("unroll") for (int m = 0; m < 4; ++m) _Pragma("unroll") for (int k = 0; k < 2; ++k) dst[m][k] = *(const PG8_LAS bf16x8*)(lds + PG8_SA(b, h) + aoff + m * 2048 + k * 1024); } while (0)
; #define PG8_LDB(dst, b, h) do { _Pragma("unroll") for (int n = 0; n < 2; ++n) _Pragma("unroll") for (int k = 0; k < 2; ++k) dst[n][k] = *(const PG8_LAS bf16x8*)(lds + PG8_SB(b, h) + boff + n * 2048 + k * 1024); } while (0)
; #define PG8_MMA(ai, bj, At, Bt) do { __builtin_amdgcn_s_setprio(1); _Pragma("unroll") for (int m = 0; m < 4; ++m) _Pragma("unroll") for (int n = 0; n < 2; ++n) _Pragma("unroll") for (int k = 0; k < 2; ++k) \
;         acc[ai][bj][m][n] = __builtin_amdgcn_mfma_f32_16x16x32_bf16(Bt[n][k], At[m][k], acc[ai][bj][m][n], 0, 0, 0); __builtin_amdgcn_s_setprio(0); } while (0)
; #define PG8_WAIT_V(n) asm volatile("s_waitcnt vmcnt(" #n ")" ::: "memory")
; #define PG8_WAIT_L(n) asm volatile("s_waitcnt lgkmcnt(" #n ")" ::: "memory")
; #define PG8_BAR __builtin_amdgcn_s_barrier()
; #define PG8_SCHED __builtin_amdgcn_sched_barrier(0)
; template <class Epi, class Sched, bool ALIGN_EPI = false, bool SP2 = false>
; __device__ __forceinline__ void gemm_phase(PG8_LAS unsigned char* lds, const Gemm g, const Sched& S, const Epi& E, const int tid) {
;     ...
;             PG8_WAIT_V(8); PG8_WAIT_L(0); PG8_BAR; PG8_MMA(1, 0, At, B0); PG8_MMA(1, 1, At, B1); PG8_BAR; PG8_SCHED;
;             PG8_LDB(B0, 1, 0); PG8_LDB(B1, 1, 1); PG8_SCHED; PG8_LDA(At, 1, 0); PG8_STAGE(PG8_SA(0, 1), a2 + hstep, voffA);
;             PG8_WAIT_V(8); PG8_WAIT_L(0); PG8_BAR; PG8_MMA(0, 0, At, B0); PG8_MMA(0, 1, At, B1); PG8_BAR; PG8_SCHED;
.Lmy_wj_0:
	s_waitcnt lgkmcnt(0)
	s_barrier
	s_setprio 1
	s_waitcnt lgkmcnt(0)
	v_mfma_f32_16x16x32_bf16 v[60:63], v[138:141], v[188:191], 0
	v_mfma_f32_16x16x32_bf16 v[56:59], v[150:153], v[188:191], 0
	v_mfma_f32_16x16x32_bf16 v[44:47], v[138:141], v[208:211], 0
	v_mfma_f32_16x16x32_bf16 v[40:43], v[150:153], v[208:211], 0
	v_mfma_f32_16x16x32_bf16 v[28:31], v[138:141], v[218:221], 0
	v_mfma_f32_16x16x32_bf16 v[24:27], v[150:153], v[218:221], 0
	v_mfma_f32_16x16x32_bf16 v[12:15], v[138:141], v[226:229], 0
	v_mfma_f32_16x16x32_bf16 v[8:11], v[150:153], v[226:229], 0
	v_mfma_f32_16x16x32_bf16 v[60:63], v[146:149], v[192:195], v[60:63]
	v_mfma_f32_16x16x32_bf16 v[56:59], v[154:157], v[192:195], v[56:59]
	v_mfma_f32_16x16x32_bf16 v[44:47], v[146:149], v[214:217], v[44:47]
	v_mfma_f32_16x16x32_bf16 v[40:43], v[154:157], v[214:217], v[40:43]
	v_mfma_f32_16x16x32_bf16 v[28:31], v[146:149], v[222:225], v[28:31]
	v_mfma_f32_16x16x32_bf16 v[24:27], v[154:157], v[222:225], v[24:27]
	v_mfma_f32_16x16x32_bf16 v[12:15], v[146:149], v[230:233], v[12:15]
	v_mfma_f32_16x16x32_bf16 v[8:11], v[154:157], v[230:233], v[8:11]
	v_mfma_f32_16x16x32_bf16 v[52:55], v[162:165], v[188:191], 0
	v_mfma_f32_16x16x32_bf16 v[48:51], v[170:173], v[188:191], 0
	v_mfma_f32_16x16x32_bf16 v[36:39], v[162:165], v[208:211], 0
	v_mfma_f32_16x16x32_bf16 v[32:35], v[170:173], v[208:211], 0
	v_mfma_f32_16x16x32_bf16 v[20:23], v[162:165], v[218:221], 0
	v_mfma_f32_16x16x32_bf16 v[16:19], v[170:173], v[218:221], 0
	v_mfma_f32_16x16x32_bf16 v[4:7], v[162:165], v[226:229], 0
	v_mfma_f32_16x16x32_bf16 v[0:3], v[170:173], v[226:229], 0
	v_mfma_f32_16x16x32_bf16 v[52:55], v[166:169], v[192:195], v[52:55]
	v_mfma_f32_16x16x32_bf16 v[48:51], v[184:187], v[192:195], v[48:51]
	v_mfma_f32_16x16x32_bf16 v[36:39], v[166:169], v[214:217], v[36:39]
	v_mfma_f32_16x16x32_bf16 v[32:35], v[184:187], v[214:217], v[32:35]
	v_mfma_f32_16x16x32_bf16 v[20:23], v[166:169], v[222:225], v[20:23]
	v_mfma_f32_16x16x32_bf16 v[16:19], v[184:187], v[222:225], v[16:19]
	v_mfma_f32_16x16x32_bf16 v[4:7], v[166:169], v[230:233], v[4:7]
	v_mfma_f32_16x16x32_bf16 v[0:3], v[184:187], v[230:233], v[0:3]
	s_setprio 0
	s_barrier
	s_add_i32 s45, 0, 0x18000
	s_add_i32 s63, 0, 0x1c000
	v_add_u32_e32 v154, s45, v143
	v_add_u32_e32 v183, s63, v143
	ds_read_b128 v[138:141], v154
	ds_read_b128 v[146:149], v154 offset:1024
	ds_read_b128 v[150:153], v154 offset:2048
	ds_read_b128 v[154:157], v154 offset:3072
	ds_read_b128 v[162:165], v183
	ds_read_b128 v[166:169], v183 offset:1024
	ds_read_b128 v[170:173], v183 offset:2048
	ds_read_b128 v[184:187], v183 offset:3072
	s_add_u32 s30, s30, s12
	s_addc_u32 s31, s31, 0
	s_mov_b32 m0, s49
	v_lshl_add_u64 v[204:205], s[30:31], 0, v[128:129]
	ds_read_b128 v[188:191], v145 offset:32768
	ds_read_b128 v[192:195], v145 offset:33792
	ds_read_b128 v[208:211], v145 offset:34816
	ds_read_b128 v[214:217], v145 offset:35840
	ds_read_b128 v[218:221], v145 offset:36864
	ds_read_b128 v[222:225], v145 offset:37888
	ds_read_b128 v[226:229], v145 offset:38912
	ds_read_b128 v[230:233], v145 offset:39936
	global_load_lds_dwordx4 v[204:205], off
	v_lshl_add_u64 v[204:205], s[30:31], 0, v[130:131]
	s_mov_b32 m0, s50
	s_nop 0
	global_load_lds_dwordx4 v[204:205], off
	s_waitcnt vmcnt(8)
	s_waitcnt lgkmcnt(0)
	s_barrier
	s_setprio 1
	s_waitcnt lgkmcnt(0)
	v_mfma_f32_16x16x32_bf16 v[124:127], v[138:141], v[188:191], v[124:127]
	v_mfma_f32_16x16x32_bf16 v[120:123], v[150:153], v[188:191], v[120:123]
	v_mfma_f32_16x16x32_bf16 v[108:111], v[138:141], v[208:211], v[108:111]
	v_mfma_f32_16x16x32_bf16 v[104:107], v[150:153], v[208:211], v[104:107]
	v_mfma_f32_16x16x32_bf16 v[92:95], v[138:141], v[218:221], v[92:95]
	v_mfma_f32_16x16x32_bf16 v[88:91], v[150:153], v[218:221], v[88:91]
	v_mfma_f32_16x16x32_bf16 v[76:79], v[138:141], v[226:229], v[76:79]
	v_mfma_f32_16x16x32_bf16 v[72:75], v[150:153], v[226:229], v[72:75]
	v_mfma_f32_16x16x32_bf16 v[124:127], v[146:149], v[192:195], v[124:127]
	v_mfma_f32_16x16x32_bf16 v[120:123], v[154:157], v[192:195], v[120:123]
	v_mfma_f32_16x16x32_bf16 v[108:111], v[146:149], v[214:217], v[108:111]
	v_mfma_f32_16x16x32_bf16 v[104:107], v[154:157], v[214:217], v[104:107]
	v_mfma_f32_16x16x32_bf16 v[92:95], v[146:149], v[222:225], v[92:95]
	v_mfma_f32_16x16x32_bf16 v[88:91], v[154:157], v[222:225], v[88:91]
	v_mfma_f32_16x16x32_bf16 v[76:79], v[146:149], v[230:233], v[76:79]
	v_mfma_f32_16x16x32_bf16 v[72:75], v[154:157], v[230:233], v[72:75]
	v_mfma_f32_16x16x32_bf16 v[116:119], v[162:165], v[188:191], v[116:119]
	v_mfma_f32_16x16x32_bf16 v[112:115], v[170:173], v[188:191], v[112:115]
	v_mfma_f32_16x16x32_bf16 v[100:103], v[162:165], v[208:211], v[100:103]
	v_mfma_f32_16x16x32_bf16 v[96:99], v[170:173], v[208:211], v[96:99]
	v_mfma_f32_16x16x32_bf16 v[84:87], v[162:165], v[218:221], v[84:87]
	v_mfma_f32_16x16x32_bf16 v[80:83], v[170:173], v[218:221], v[80:83]
	v_mfma_f32_16x16x32_bf16 v[68:71], v[162:165], v[226:229], v[68:71]
	v_mfma_f32_16x16x32_bf16 v[64:67], v[170:173], v[226:229], v[64:67]
	v_mfma_f32_16x16x32_bf16 v[116:119], v[166:169], v[192:195], v[116:119]
	v_mfma_f32_16x16x32_bf16 v[112:115], v[184:187], v[192:195], v[112:115]
	v_mfma_f32_16x16x32_bf16 v[100:103], v[166:169], v[214:217], v[100:103]
	v_mfma_f32_16x16x32_bf16 v[96:99], v[184:187], v[214:217], v[96:99]
	v_mfma_f32_16x16x32_bf16 v[84:87], v[166:169], v[222:225], v[84:87]
	v_mfma_f32_16x16x32_bf16 v[80:83], v[184:187], v[222:225], v[80:83]
	v_mfma_f32_16x16x32_bf16 v[68:71], v[166:169], v[230:233], v[68:71]
	v_mfma_f32_16x16x32_bf16 v[64:67], v[184:187], v[230:233], v[64:67]
	s_setprio 0
	s_barrier
; #define PG8_STAGE(bufoff, gbase, voff) do { _Pragma("unroll") for (int _i = 0; _i < 2; ++_i) \
;         __builtin_amdgcn_global_load_lds((const unsigned*)((const char*)(gbase) + (voff)[_i]), (PG8_LAS unsigned*)(lds + (bufoff) + ldsw + _i * 8192), 16, 0, 0); } while (0)
; #define PG8_LDA(dst, b, h) do { _Pragma("unroll") for (int m = 0; m < 4; ++m) _Pragma("unroll") for (int k = 0; k < 2; ++k) dst[m][k] = *(const PG8_LAS bf16x8*)(lds + PG8_SA(b, h) + aoff + m * 2048 + k * 1024); } while (0)
; #define PG8_LDB(dst, b, h) do { _Pragma("unroll") for (int n = 0; n < 2; ++n) _Pragma("unroll") for (int k = 0; k < 2; ++k) dst[n][k] = *(const PG8_LAS bf16x8*)(lds + PG8_SB(b, h) + boff + n * 2048 + k * 1024); } while (0)
; #define PG8_MMA(ai, bj, At, Bt) do { __builtin_amdgcn_s_setprio(1); _Pragma("unroll") for (int m = 0; m < 4; ++m) _Pragma("unroll") for (int n = 0; n < 2; ++n) _Pragma("unroll") for (int k = 0; k < 2; ++k) \
;         acc[ai][bj][m][n] = __builtin_amdgcn_mfma_f32_16x16x32_bf16(Bt[n][k], At[m][k], acc[ai][bj][m][n], 0, 0, 0); __builtin_amdgcn_s_setprio(0); } while (0)
; #define PG8_BAR __builtin_amdgcn_s_barrier()
; template <class Epi, class Sched, bool ALIGN_EPI = false, bool SP2 = false>
; __device__ __forceinline__ void gemm_phase(PG8_LAS unsigned char* lds, const Gemm g, const Sched& S, const Epi& E, const int tid) {
;     ...
;             PG8_LDB(B0, 0, 0); PG8_LDB(B1, 0, 1); PG8_SCHED; PG8_LDA(At, 0, 0); PG8_STAGE(PG8_SA(1, 1), a1 + hstep, voffA);
;             PG8_WAIT_V(8); PG8_WAIT_L(0); PG8_BAR; PG8_MMA(0, 0, At, B0); PG8_MMA(0, 1, At, B1); PG8_BAR; PG8_SCHED;
;             PG8_LDA(At, 0, 1); PG8_STAGE(PG8_SB(0, 0), b2, voffB); PG8_STAGE(PG8_SB(0, 1), b2 + hstep, voffB); PG8_STAGE(PG8_SA(0, 0), a2, voffA);
;             PG8_WAIT_V(8); PG8_WAIT_L(0); PG8_BAR; PG8_MMA(1, 0, At, B0); PG8_MMA(1, 1, At, B1); PG8_BAR; PG8_SCHED;
;             PG8_LDB(B0, 1, 0); PG8_LDB(B1, 1, 1); PG8_SCHED; PG8_LDA(At, 1, 0); PG8_STAGE(PG8_SA(0, 1), a2 + hstep, voffA);
;             PG8_WAIT_V(8); PG8_WAIT_L(0); PG8_BAR; PG8_MMA(0, 0, At, B0); PG8_MMA(0, 1, At, B1); PG8_BAR; PG8_SCHED;
;             PG8_LDA(At, 1, 1); PG8_STAGE(PG8_SB(1, 0), b3, voffB); PG8_STAGE(PG8_SB(1, 1), b3 + hstep, voffB); PG8_STAGE(PG8_SA(1, 0), a3, voffA);
;             PG8_WAIT_V(8); PG8_WAIT_L(0); PG8_BAR; PG8_MMA(1, 0, At, B0); PG8_MMA(1, 1, At, B1); PG8_BAR; PG8_SCHED;
	s_add_i32 s30, s45, s46
	v_lshl_add_u64 v[158:159], v[158:159], 0, s[28:29]
	s_mov_b32 m0, s30
	ds_read_b128 v[188:191], v145 offset:49152
	ds_read_b128 v[192:195], v145 offset:50176
	ds_read_b128 v[208:211], v145 offset:51200
	ds_read_b128 v[214:217], v145 offset:52224
	ds_read_b128 v[218:221], v145 offset:53248
	ds_read_b128 v[222:225], v145 offset:54272
	ds_read_b128 v[226:229], v145 offset:55296
	ds_read_b128 v[230:233], v145 offset:56320
	global_load_lds_dwordx4 v[158:159], off
	v_lshl_add_u64 v[158:159], v[174:175], 0, s[28:29]
	s_add_i32 m0, s30, 0x2000
	s_add_i32 s30, s63, s46
	global_load_lds_dwordx4 v[158:159], off
	v_lshl_add_u64 v[158:159], v[178:179], 0, s[28:29]
	s_mov_b32 m0, s30
	s_nop 0
	global_load_lds_dwordx4 v[158:159], off
	v_lshl_add_u64 v[158:159], v[180:181], 0, s[28:29]
	s_add_i32 m0, s30, 0x2000
	s_nop 0
	global_load_lds_dwordx4 v[158:159], off
	v_lshl_add_u64 v[158:159], v[196:197], 0, s[28:29]
	s_mov_b32 m0, s51
	s_nop 0
	global_load_lds_dwordx4 v[158:159], off
	v_lshl_add_u64 v[158:159], v[198:199], 0, s[28:29]
	s_mov_b32 m0, s52
	s_nop 0
	global_load_lds_dwordx4 v[158:159], off
	s_waitcnt vmcnt(8)
	s_waitcnt lgkmcnt(0)
	s_barrier
	s_setprio 1
	s_waitcnt lgkmcnt(0)
	v_mfma_f32_16x16x32_bf16 v[60:63], v[138:141], v[188:191], v[60:63]
	v_mfma_f32_16x16x32_bf16 v[56:59], v[150:153], v[188:191], v[56:59]
	v_mfma_f32_16x16x32_bf16 v[44:47], v[138:141], v[208:211], v[44:47]
	v_mfma_f32_16x16x32_bf16 v[40:43], v[150:153], v[208:211], v[40:43]
	v_mfma_f32_16x16x32_bf16 v[28:31], v[138:141], v[218:221], v[28:31]
	v_mfma_f32_16x16x32_bf16 v[24:27], v[150:153], v[218:221], v[24:27]
	v_mfma_f32_16x16x32_bf16 v[12:15], v[138:141], v[226:229], v[12:15]
	v_mfma_f32_16x16x32_bf16 v[8:11], v[150:153], v[226:229], v[8:11]
	v_mfma_f32_16x16x32_bf16 v[60:63], v[146:149], v[192:195], v[60:63]
	v_mfma_f32_16x16x32_bf16 v[56:59], v[154:157], v[192:195], v[56:59]
	v_mfma_f32_16x16x32_bf16 v[44:47], v[146:149], v[214:217], v[44:47]
	v_mfma_f32_16x16x32_bf16 v[40:43], v[154:157], v[214:217], v[40:43]
	v_mfma_f32_16x16x32_bf16 v[28:31], v[146:149], v[222:225], v[28:31]
	v_mfma_f32_16x16x32_bf16 v[24:27], v[154:157], v[222:225], v[24:27]
	v_mfma_f32_16x16x32_bf16 v[12:15], v[146:149], v[230:233], v[12:15]
	v_mfma_f32_16x16x32_bf16 v[8:11], v[154:157], v[230:233], v[8:11]
	v_mfma_f32_16x16x32_bf16 v[52:55], v[162:165], v[188:191], v[52:55]
	v_mfma_f32_16x16x32_bf16 v[48:51], v[170:173], v[188:191], v[48:51]
	v_mfma_f32_16x16x32_bf16 v[36:39], v[162:165], v[208:211], v[36:39]
	v_mfma_f32_16x16x32_bf16 v[32:35], v[170:173], v[208:211], v[32:35]
	v_mfma_f32_16x16x32_bf16 v[20:23], v[162:165], v[218:221], v[20:23]
	v_mfma_f32_16x16x32_bf16 v[16:19], v[170:173], v[218:221], v[16:19]
	v_mfma_f32_16x16x32_bf16 v[4:7], v[162:165], v[226:229], v[4:7]
	v_mfma_f32_16x16x32_bf16 v[0:3], v[170:173], v[226:229], v[0:3]
	v_mfma_f32_16x16x32_bf16 v[52:55], v[166:169], v[192:195], v[52:55]
	v_mfma_f32_16x16x32_bf16 v[48:51], v[184:187], v[192:195], v[48:51]
	v_mfma_f32_16x16x32_bf16 v[36:39], v[166:169], v[214:217], v[36:39]
	v_mfma_f32_16x16x32_bf16 v[32:35], v[184:187], v[214:217], v[32:35]
	v_mfma_f32_16x16x32_bf16 v[20:23], v[166:169], v[222:225], v[20:23]
	v_mfma_f32_16x16x32_bf16 v[16:19], v[184:187], v[222:225], v[16:19]
	v_mfma_f32_16x16x32_bf16 v[4:7], v[166:169], v[230:233], v[4:7]
	v_mfma_f32_16x16x32_bf16 v[0:3], v[184:187], v[230:233], v[0:3]
	s_setprio 0
	s_barrier
	s_add_u32 s26, s26, 0x100
	s_addc_u32 s27, s27, 0
	s_add_u32 s36, s36, 0x100
	s_addc_u32 s37, s37, 0
	s_cmp_ge_u32 s44, s57
	s_mov_b32 s30, s44
	s_cbranch_scc1 .Lmy_kdone_0
.LBB0_60:
	s_add_i32 s44, s30, 2
	s_add_u32 s45, s26, 0x80
	s_addc_u32 s31, s27, 0
	s_add_i32 s63, 0, 0x10000
	s_cmp_eq_u32 s58, s30
	s_cselect_b32 s31, s21, s31
	s_cselect_b32 s30, s20, s45
	s_cselect_b32 s65, s23, s37
	s_cselect_b32 s64, s22, s36
	s_add_i32 s45, 0, 0x14000
	v_add_u32_e32 v154, s63, v143
	v_add_u32_e32 v158, s45, v143
	ds_read_b128 v[138:141], v154
	ds_read_b128 v[146:149], v154 offset:1024
	ds_read_b128 v[150:153], v154 offset:2048
	ds_read_b128 v[154:157], v154 offset:3072
	ds_read_b128 v[162:165], v158
	ds_read_b128 v[166:169], v158 offset:1024
	ds_read_b128 v[170:173], v158 offset:2048
	ds_read_b128 v[184:187], v158 offset:3072
	v_lshl_add_u64 v[158:159], s[26:27], 0, v[134:135]
	s_add_i32 m0, s47, 0xc000
	ds_read_b128 v[188:191], v145
	ds_read_b128 v[192:195], v145 offset:1024
	ds_read_b128 v[208:211], v145 offset:2048
	ds_read_b128 v[214:217], v145 offset:3072
	ds_read_b128 v[218:221], v145 offset:4096
	ds_read_b128 v[222:225], v145 offset:5120
	ds_read_b128 v[226:229], v145 offset:6144
	ds_read_b128 v[230:233], v145 offset:7168
	global_load_lds_dwordx4 v[158:159], off
	v_lshl_add_u64 v[158:159], s[26:27], 0, v[136:137]
	s_add_i32 m0, s47, 0xe000
	s_nop 0
	global_load_lds_dwordx4 v[158:159], off
	s_waitcnt vmcnt(8)
	s_waitcnt lgkmcnt(0)
	s_barrier
; #define PG8_STAGE(bufoff, gbase, voff) do { _Pragma("unroll") for (int _i = 0; _i < 2; ++_i) \
;         __builtin_amdgcn_global_load_lds((const unsigned*)((const char*)(gbase) + (voff)[_i]), (PG8_LAS unsigned*)(lds + (bufoff) + ldsw + _i * 8192), 16, 0, 0); } while (0)
; #define PG8_LDA(dst, b, h) do { _Pragma("unroll") for (int m = 0; m < 4; ++m) _Pragma("unroll") for (int k = 0; k < 2; ++k) dst[m][k] = *(const PG8_LAS bf16x8*)(lds + PG8_SA(b, h) + aoff + m * 2048 + k * 1024); } while (0)
; #define PG8_MMA(ai, bj, At, Bt) do { __builtin_amdgcn_s_setprio(1); _Pragma("unroll") for (int m = 0; m < 4; ++m) _Pragma("unroll") for (int n = 0; n < 2; ++n) _Pragma("unroll") for (int k = 0; k < 2; ++k) \
;         acc[ai][bj][m][n] = __builtin_amdgcn_mfma_f32_16x16x32_bf16(Bt[n][k], At[m][k], acc[ai][bj][m][n], 0, 0, 0); __builtin_amdgcn_s_setprio(0); } while (0)
; #define PG8_WAIT_V(n) asm volatile("s_waitcnt vmcnt(" #n ")" ::: "memory")
; #define PG8_WAIT_L(n) asm volatile("s_waitcnt lgkmcnt(" #n ")" ::: "memory")
; #define PG8_BAR __builtin_amdgcn_s_barrier()
; #define PG8_SCHED __builtin_amdgcn_sched_barrier(0)
; template <class Epi, class Sched, bool ALIGN_EPI = false, bool SP2 = false>
; __device__ __forceinline__ void gemm_phase(PG8_LAS unsigned char* lds, const Gemm g, const Sched& S, const Epi& E, const int tid) {
;     ...
;             PG8_WAIT_V(8); PG8_WAIT_L(0); PG8_BAR; PG8_MMA(0, 0, At, B0); PG8_MMA(0, 1, At, B1); PG8_BAR; PG8_SCHED;
;             PG8_LDA(At, 0, 1); PG8_STAGE(PG8_SB(0, 0), b2, voffB); PG8_STAGE(PG8_SB(0, 1), b2 + hstep, voffB); PG8_STAGE(PG8_SA(0, 0), a2, voffA);
;             PG8_WAIT_V(8); PG8_WAIT_L(0); PG8_BAR; PG8_MMA(1, 0, At, B0); PG8_MMA(1, 1, At, B1); PG8_BAR; PG8_SCHED;
	s_setprio 1
	s_waitcnt lgkmcnt(0)
	v_mfma_f32_16x16x32_bf16 v[124:127], v[138:141], v[188:191], v[124:127]
	v_mfma_f32_16x16x32_bf16 v[120:123], v[150:153], v[188:191], v[120:123]
	v_mfma_f32_16x16x32_bf16 v[108:111], v[138:141], v[208:211], v[108:111]
	v_mfma_f32_16x16x32_bf16 v[104:107], v[150:153], v[208:211], v[104:107]
	v_mfma_f32_16x16x32_bf16 v[92:95], v[138:141], v[218:221], v[92:95]
	v_mfma_f32_16x16x32_bf16 v[88:91], v[150:153], v[218:221], v[88:91]
	v_mfma_f32_16x16x32_bf16 v[76:79], v[138:141], v[226:229], v[76:79]
	v_mfma_f32_16x16x32_bf16 v[72:75], v[150:153], v[226:229], v[72:75]
	v_mfma_f32_16x16x32_bf16 v[124:127], v[146:149], v[192:195], v[124:127]
	v_mfma_f32_16x16x32_bf16 v[120:123], v[154:157], v[192:195], v[120:123]
	v_mfma_f32_16x16x32_bf16 v[108:111], v[146:149], v[214:217], v[108:111]
	v_mfma_f32_16x16x32_bf16 v[104:107], v[154:157], v[214:217], v[104:107]
	v_mfma_f32_16x16x32_bf16 v[92:95], v[146:149], v[222:225], v[92:95]
	v_mfma_f32_16x16x32_bf16 v[88:91], v[154:157], v[222:225], v[88:91]
	v_mfma_f32_16x16x32_bf16 v[76:79], v[146:149], v[230:233], v[76:79]
	v_mfma_f32_16x16x32_bf16 v[72:75], v[154:157], v[230:233], v[72:75]
	v_mfma_f32_16x16x32_bf16 v[116:119], v[162:165], v[188:191], v[116:119]
	v_mfma_f32_16x16x32_bf16 v[112:115], v[170:173], v[188:191], v[112:115]
	v_mfma_f32_16x16x32_bf16 v[100:103], v[162:165], v[208:211], v[100:103]
	v_mfma_f32_16x16x32_bf16 v[96:99], v[170:173], v[208:211], v[96:99]
	v_mfma_f32_16x16x32_bf16 v[84:87], v[162:165], v[218:221], v[84:87]
	v_mfma_f32_16x16x32_bf16 v[80:83], v[170:173], v[218:221], v[80:83]
	v_mfma_f32_16x16x32_bf16 v[68:71], v[162:165], v[226:229], v[68:71]
	v_mfma_f32_16x16x32_bf16 v[64:67], v[170:173], v[226:229], v[64:67]
	v_mfma_f32_16x16x32_bf16 v[116:119], v[166:169], v[192:195], v[116:119]
	v_mfma_f32_16x16x32_bf16 v[112:115], v[184:187], v[192:195], v[112:115]
	v_mfma_f32_16x16x32_bf16 v[100:103], v[166:169], v[214:217], v[100:103]
	v_mfma_f32_16x16x32_bf16 v[96:99], v[184:187], v[214:217], v[96:99]
	v_mfma_f32_16x16x32_bf16 v[84:87], v[166:169], v[222:225], v[84:87]
	v_mfma_f32_16x16x32_bf16 v[80:83], v[184:187], v[222:225], v[80:83]
	v_mfma_f32_16x16x32_bf16 v[68:71], v[166:169], v[230:233], v[68:71]
	v_mfma_f32_16x16x32_bf16 v[64:67], v[184:187], v[230:233], v[64:67]
	s_setprio 0
	s_barrier
	s_add_i32 s63, s63, s46
	v_lshl_add_u64 v[158:159], s[64:65], 0, v[160:161]
	s_mov_b32 m0, s63
	ds_read_b128 v[188:191], v145 offset:16384
	ds_read_b128 v[192:195], v145 offset:17408
	ds_read_b128 v[208:211], v145 offset:18432
	ds_read_b128 v[214:217], v145 offset:19456
	ds_read_b128 v[218:221], v145 offset:20480
	ds_read_b128 v[222:225], v145 offset:21504
	ds_read_b128 v[226:229], v145 offset:22528
	ds_read_b128 v[230:233], v145 offset:23552
	global_load_lds_dwordx4 v[158:159], off
	s_add_i32 m0, s63, 0x2000
	v_lshl_add_u64 v[174:175], s[64:65], 0, v[132:133]
	s_add_u32 s64, s64, s12
	s_addc_u32 s65, s65, 0
	s_add_i32 s45, s45, s46
	global_load_lds_dwordx4 v[174:175], off
	v_lshl_add_u64 v[178:179], s[64:65], 0, v[160:161]
	s_mov_b32 m0, s45
	v_lshl_add_u64 v[180:181], s[64:65], 0, v[132:133]
	global_load_lds_dwordx4 v[178:179], off
	s_add_i32 m0, s45, 0x2000
	v_lshl_add_u64 v[196:197], s[30:31], 0, v[128:129]
	global_load_lds_dwordx4 v[180:181], off
	s_mov_b32 m0, s47
	v_lshl_add_u64 v[198:199], s[30:31], 0, v[130:131]
	global_load_lds_dwordx4 v[196:197], off
	s_mov_b32 m0, s48
	s_nop 0
	global_load_lds_dwordx4 v[198:199], off
	s_waitcnt vmcnt(8)
	s_waitcnt lgkmcnt(0)
	s_barrier
	s_setprio 1
	s_waitcnt lgkmcnt(0)
	v_mfma_f32_16x16x32_bf16 v[60:63], v[138:141], v[188:191], v[60:63]
	v_mfma_f32_16x16x32_bf16 v[56:59], v[150:153], v[188:191], v[56:59]
	v_mfma_f32_16x16x32_bf16 v[44:47], v[138:141], v[208:211], v[44:47]
	v_mfma_f32_16x16x32_bf16 v[40:43], v[150:153], v[208:211], v[40:43]
	v_mfma_f32_16x16x32_bf16 v[28:31], v[138:141], v[218:221], v[28:31]
	v_mfma_f32_16x16x32_bf16 v[24:27], v[150:153], v[218:221], v[24:27]
	v_mfma_f32_16x16x32_bf16 v[12:15], v[138:141], v[226:229], v[12:15]
	v_mfma_f32_16x16x32_bf16 v[8:11], v[150:153], v[226:229], v[8:11]
	v_mfma_f32_16x16x32_bf16 v[60:63], v[146:149], v[192:195], v[60:63]
	v_mfma_f32_16x16x32_bf16 v[56:59], v[154:157], v[192:195], v[56:59]
	v_mfma_f32_16x16x32_bf16 v[44:47], v[146:149], v[214:217], v[44:47]
	v_mfma_f32_16x16x32_bf16 v[40:43], v[154:157], v[214:217], v[40:43]
	v_mfma_f32_16x16x32_bf16 v[28:31], v[146:149], v[222:225], v[28:31]
	v_mfma_f32_16x16x32_bf16 v[24:27], v[154:157], v[222:225], v[24:27]
	v_mfma_f32_16x16x32_bf16 v[12:15], v[146:149], v[230:233], v[12:15]
	v_mfma_f32_16x16x32_bf16 v[8:11], v[154:157], v[230:233], v[8:11]
	v_mfma_f32_16x16x32_bf16 v[52:55], v[162:165], v[188:191], v[52:55]
	v_mfma_f32_16x16x32_bf16 v[48:51], v[170:173], v[188:191], v[48:51]
	v_mfma_f32_16x16x32_bf16 v[36:39], v[162:165], v[208:211], v[36:39]
	v_mfma_f32_16x16x32_bf16 v[32:35], v[170:173], v[208:211], v[32:35]
	v_mfma_f32_16x16x32_bf16 v[20:23], v[162:165], v[218:221], v[20:23]
	v_mfma_f32_16x16x32_bf16 v[16:19], v[170:173], v[218:221], v[16:19]
	v_mfma_f32_16x16x32_bf16 v[4:7], v[162:165], v[226:229], v[4:7]
	v_mfma_f32_16x16x32_bf16 v[0:3], v[170:173], v[226:229], v[0:3]
	v_mfma_f32_16x16x32_bf16 v[52:55], v[166:169], v[192:195], v[52:55]
	v_mfma_f32_16x16x32_bf16 v[48:51], v[184:187], v[192:195], v[48:51]
	v_mfma_f32_16x16x32_bf16 v[36:39], v[166:169], v[214:217], v[36:39]
	v_mfma_f32_16x16x32_bf16 v[32:35], v[184:187], v[214:217], v[32:35]
	v_mfma_f32_16x16x32_bf16 v[20:23], v[166:169], v[222:225], v[20:23]
	v_mfma_f32_16x16x32_bf16 v[16:19], v[184:187], v[222:225], v[16:19]
	v_mfma_f32_16x16x32_bf16 v[4:7], v[166:169], v[230:233], v[4:7]
	v_mfma_f32_16x16x32_bf16 v[0:3], v[184:187], v[230:233], v[0:3]
	s_setprio 0
	s_barrier
; #define PG8_STAGE(bufoff, gbase, voff) do { _Pragma("unroll") for (int _i = 0; _i < 2; ++_i) \
;         __builtin_amdgcn_global_load_lds((const unsigned*)((const char*)(gbase) + (voff)[_i]), (PG8_LAS unsigned*)(lds + (bufoff) + ldsw + _i * 8192), 16, 0, 0); } while (0)
; #define PG8_LDA(dst, b, h) do { _Pragma("unroll") for (int m = 0; m < 4; ++m) _Pragma("unroll") for (int k = 0; k < 2; ++k) dst[m][k] = *(const PG8_LAS bf16x8*)(lds + PG8_SA(b, h) + aoff + m * 2048 + k * 1024); } while (0)
; #define PG8_LDB(dst, b, h) do { _Pragma("unroll") for (int n = 0; n < 2; ++n) _Pragma("unroll") for (int k = 0; k < 2; ++k) dst[n][k] = *(const PG8_LAS bf16x8*)(lds + PG8_SB(b, h) + boff + n * 2048 + k * 1024); } while (0)
; #define PG8_MMA(ai, bj, At, Bt) do { __builtin_amdgcn_s_setprio(1); _Pragma("unroll") for (int m = 0; m < 4; ++m) _Pragma("unroll") for (int n = 0; n < 2; ++n) _Pragma("unroll") for (int k = 0; k < 2; ++k) \
;         acc[ai][bj][m][n] = __builtin_amdgcn_mfma_f32_16x16x32_bf16(Bt[n][k], At[m][k], acc[ai][bj][m][n], 0, 0, 0); __builtin_amdgcn_s_setprio(0); } while (0)
; #define PG8_WAIT_V(n) asm volatile("s_waitcnt vmcnt(" #n ")" ::: "memory")
; #define PG8_WAIT_L(n) asm volatile("s_waitcnt lgkmcnt(" #n ")" ::: "memory")
; #define PG8_BAR __builtin_amdgcn_s_barrier()
; #define PG8_SCHED __builtin_amdgcn_sched_barrier(0)
; template <class Epi, class Sched, bool ALIGN_EPI = false, bool SP2 = false>
; __device__ __forceinline__ void gemm_phase(PG8_LAS unsigned char* lds, const Gemm g, const Sched& S, const Epi& E, const int tid) {
;     ...
;             PG8_LDB(B0, 1, 0); PG8_LDB(B1, 1, 1); PG8_SCHED; PG8_LDA(At, 1, 0); PG8_STAGE(PG8_SA(0, 1), a2 + hstep, voffA);
;             PG8_WAIT_V(8); PG8_WAIT_L(0); PG8_BAR; PG8_MMA(0, 0, At, B0); PG8_MMA(0, 1, At, B1); PG8_BAR; PG8_SCHED;
;             PG8_LDA(At, 1, 1); PG8_STAGE(PG8_SB(1, 0), b3, voffB); PG8_STAGE(PG8_SB(1, 1), b3 + hstep, voffB); PG8_STAGE(PG8_SA(1, 0), a3, voffA);
;             PG8_WAIT_V(8); PG8_WAIT_L(0); PG8_BAR; PG8_MMA(1, 0, At, B0); PG8_MMA(1, 1, At, B1); PG8_BAR; PG8_SCHED;
	s_add_i32 s45, 0, 0x18000
	s_add_i32 s63, 0, 0x1c000
	v_add_u32_e32 v154, s45, v143
	v_add_u32_e32 v183, s63, v143
	ds_read_b128 v[138:141], v154
	ds_read_b128 v[146:149], v154 offset:1024
	ds_read_b128 v[150:153], v154 offset:2048
	ds_read_b128 v[154:157], v154 offset:3072
	ds_read_b128 v[162:165], v183
	ds_read_b128 v[166:169], v183 offset:1024
	ds_read_b128 v[170:173], v183 offset:2048
	ds_read_b128 v[184:187], v183 offset:3072
	s_add_u32 s30, s30, s12
	s_addc_u32 s31, s31, 0
	s_mov_b32 m0, s49
	v_lshl_add_u64 v[204:205], s[30:31], 0, v[128:129]
	ds_read_b128 v[188:191], v145 offset:32768
	ds_read_b128 v[192:195], v145 offset:33792
	ds_read_b128 v[208:211], v145 offset:34816
	ds_read_b128 v[214:217], v145 offset:35840
	ds_read_b128 v[218:221], v145 offset:36864
	ds_read_b128 v[222:225], v145 offset:37888
	ds_read_b128 v[226:229], v145 offset:38912
	ds_read_b128 v[230:233], v145 offset:39936
	global_load_lds_dwordx4 v[204:205], off
	v_lshl_add_u64 v[204:205], s[30:31], 0, v[130:131]
	s_mov_b32 m0, s50
	s_nop 0
	global_load_lds_dwordx4 v[204:205], off
	s_waitcnt vmcnt(8)
	s_waitcnt lgkmcnt(0)
	s_barrier
	s_setprio 1
	s_waitcnt lgkmcnt(0)
	v_mfma_f32_16x16x32_bf16 v[124:127], v[138:141], v[188:191], v[124:127]
	v_mfma_f32_16x16x32_bf16 v[120:123], v[150:153], v[188:191], v[120:123]
	v_mfma_f32_16x16x32_bf16 v[108:111], v[138:141], v[208:211], v[108:111]
	v_mfma_f32_16x16x32_bf16 v[104:107], v[150:153], v[208:211], v[104:107]
	v_mfma_f32_16x16x32_bf16 v[92:95], v[138:141], v[218:221], v[92:95]
	v_mfma_f32_16x16x32_bf16 v[88:91], v[150:153], v[218:221], v[88:91]
	v_mfma_f32_16x16x32_bf16 v[76:79], v[138:141], v[226:229], v[76:79]
	v_mfma_f32_16x16x32_bf16 v[72:75], v[150:153], v[226:229], v[72:75]
	v_mfma_f32_16x16x32_bf16 v[124:127], v[146:149], v[192:195], v[124:127]
	v_mfma_f32_16x16x32_bf16 v[120:123], v[154:157], v[192:195], v[120:123]
	v_mfma_f32_16x16x32_bf16 v[108:111], v[146:149], v[214:217], v[108:111]
	v_mfma_f32_16x16x32_bf16 v[104:107], v[154:157], v[214:217], v[104:107]
	v_mfma_f32_16x16x32_bf16 v[92:95], v[146:149], v[222:225], v[92:95]
	v_mfma_f32_16x16x32_bf16 v[88:91], v[154:157], v[222:225], v[88:91]
	v_mfma_f32_16x16x32_bf16 v[76:79], v[146:149], v[230:233], v[76:79]
	v_mfma_f32_16x16x32_bf16 v[72:75], v[154:157], v[230:233], v[72:75]
	v_mfma_f32_16x16x32_bf16 v[116:119], v[162:165], v[188:191], v[116:119]
	v_mfma_f32_16x16x32_bf16 v[112:115], v[170:173], v[188:191], v[112:115]
	v_mfma_f32_16x16x32_bf16 v[100:103], v[162:165], v[208:211], v[100:103]
	v_mfma_f32_16x16x32_bf16 v[96:99], v[170:173], v[208:211], v[96:99]
	v_mfma_f32_16x16x32_bf16 v[84:87], v[162:165], v[218:221], v[84:87]
	v_mfma_f32_16x16x32_bf16 v[80:83], v[170:173], v[218:221], v[80:83]
	v_mfma_f32_16x16x32_bf16 v[68:71], v[162:165], v[226:229], v[68:71]
	v_mfma_f32_16x16x32_bf16 v[64:67], v[170:173], v[226:229], v[64:67]
	v_mfma_f32_16x16x32_bf16 v[116:119], v[166:169], v[192:195], v[116:119]
	v_mfma_f32_16x16x32_bf16 v[112:115], v[184:187], v[192:195], v[112:115]
	v_mfma_f32_16x16x32_bf16 v[100:103], v[166:169], v[214:217], v[100:103]
	v_mfma_f32_16x16x32_bf16 v[96:99], v[184:187], v[214:217], v[96:99]
	v_mfma_f32_16x16x32_bf16 v[84:87], v[166:169], v[222:225], v[84:87]
	v_mfma_f32_16x16x32_bf16 v[80:83], v[184:187], v[222:225], v[80:83]
	v_mfma_f32_16x16x32_bf16 v[68:71], v[166:169], v[230:233], v[68:71]
	v_mfma_f32_16x16x32_bf16 v[64:67], v[184:187], v[230:233], v[64:67]
	s_setprio 0
	s_barrier
	s_add_i32 s30, s45, s46
	v_lshl_add_u64 v[158:159], v[158:159], 0, s[28:29]
	s_mov_b32 m0, s30
	ds_read_b128 v[188:191], v145 offset:49152
	ds_read_b128 v[192:195], v145 offset:50176
	ds_read_b128 v[208:211], v145 offset:51200
	ds_read_b128 v[214:217], v145 offset:52224
	ds_read_b128 v[218:221], v145 offset:53248
	ds_read_b128 v[222:225], v145 offset:54272
	ds_read_b128 v[226:229], v145 offset:55296
	ds_read_b128 v[230:233], v145 offset:56320
	global_load_lds_dwordx4 v[158:159], off
	v_lshl_add_u64 v[158:159], v[174:175], 0, s[28:29]
	s_add_i32 m0, s30, 0x2000
	s_add_i32 s30, s63, s46
	global_load_lds_dwordx4 v[158:159], off
	v_lshl_add_u64 v[158:159], v[178:179], 0, s[28:29]
	s_mov_b32 m0, s30
	s_nop 0
	global_load_lds_dwordx4 v[158:159], off
	v_lshl_add_u64 v[158:159], v[180:181], 0, s[28:29]
	s_add_i32 m0, s30, 0x2000
	s_nop 0
	global_load_lds_dwordx4 v[158:159], off
	v_lshl_add_u64 v[158:159], v[196:197], 0, s[28:29]
	s_mov_b32 m0, s51
	s_nop 0
	global_load_lds_dwordx4 v[158:159], off
	v_lshl_add_u64 v[158:159], v[198:199], 0, s[28:29]
	s_mov_b32 m0, s52
	s_nop 0
	global_load_lds_dwordx4 v[158:159], off
	s_waitcnt vmcnt(8)
	s_waitcnt lgkmcnt(0)
	s_barrier
	s_setprio 1
	s_waitcnt lgkmcnt(0)
	v_mfma_f32_16x16x32_bf16 v[60:63], v[138:141], v[188:191], v[60:63]
	v_mfma_f32_16x16x32_bf16 v[56:59], v[150:153], v[188:191], v[56:59]
	v_mfma_f32_16x16x32_bf16 v[44:47], v[138:141], v[208:211], v[44:47]
	v_mfma_f32_16x16x32_bf16 v[40:43], v[150:153], v[208:211], v[40:43]
	v_mfma_f32_16x16x32_bf16 v[28:31], v[138:141], v[218:221], v[28:31]
	v_mfma_f32_16x16x32_bf16 v[24:27], v[150:153], v[218:221], v[24:27]
	v_mfma_f32_16x16x32_bf16 v[12:15], v[138:141], v[226:229], v[12:15]
	v_mfma_f32_16x16x32_bf16 v[8:11], v[150:153], v[226:229], v[8:11]
	v_mfma_f32_16x16x32_bf16 v[60:63], v[146:149], v[192:195], v[60:63]
	v_mfma_f32_16x16x32_bf16 v[56:59], v[154:157], v[192:195], v[56:59]
	v_mfma_f32_16x16x32_bf16 v[44:47], v[146:149], v[214:217], v[44:47]
	v_mfma_f32_16x16x32_bf16 v[40:43], v[154:157], v[214:217], v[40:43]
	v_mfma_f32_16x16x32_bf16 v[28:31], v[146:149], v[222:225], v[28:31]
	v_mfma_f32_16x16x32_bf16 v[24:27], v[154:157], v[222:225], v[24:27]
	v_mfma_f32_16x16x32_bf16 v[12:15], v[146:149], v[230:233], v[12:15]
	v_mfma_f32_16x16x32_bf16 v[8:11], v[154:157], v[230:233], v[8:11]
	v_mfma_f32_16x16x32_bf16 v[52:55], v[162:165], v[188:191], v[52:55]
	v_mfma_f32_16x16x32_bf16 v[48:51], v[170:173], v[188:191], v[48:51]
	v_mfma_f32_16x16x32_bf16 v[36:39], v[162:165], v[208:211], v[36:39]
	v_mfma_f32_16x16x32_bf16 v[32:35], v[170:173], v[208:211], v[32:35]
	v_mfma_f32_16x16x32_bf16 v[20:23], v[162:165], v[218:221], v[20:23]
	v_mfma_f32_16x16x32_bf16 v[16:19], v[170:173], v[218:221], v[16:19]
	v_mfma_f32_16x16x32_bf16 v[4:7], v[162:165], v[226:229], v[4:7]
	v_mfma_f32_16x16x32_bf16 v[0:3], v[170:173], v[226:229], v[0:3]
	v_mfma_f32_16x16x32_bf16 v[52:55], v[166:169], v[192:195], v[52:55]
	v_mfma_f32_16x16x32_bf16 v[48:51], v[184:187], v[192:195], v[48:51]
	v_mfma_f32_16x16x32_bf16 v[36:39], v[166:169], v[214:217], v[36:39]
	v_mfma_f32_16x16x32_bf16 v[32:35], v[184:187], v[214:217], v[32:35]
	v_mfma_f32_16x16x32_bf16 v[20:23], v[166:169], v[222:225], v[20:23]
	v_mfma_f32_16x16x32_bf16 v[16:19], v[184:187], v[222:225], v[16:19]
	v_mfma_f32_16x16x32_bf16 v[4:7], v[166:169], v[230:233], v[4:7]
	v_mfma_f32_16x16x32_bf16 v[0:3], v[184:187], v[230:233], v[0:3]
	s_setprio 0
	s_barrier
	s_add_u32 s26, s26, 0x100
	s_addc_u32 s27, s27, 0
	s_add_u32 s36, s36, 0x100
	s_addc_u32 s37, s37, 0
	s_cmp_ge_u32 s44, s57
	s_mov_b32 s30, s44
	s_cbranch_scc0 .LBB0_60

; #define PG8_STAGE(bufoff, gbase, voff) do { _Pragma("unroll") for (int _i = 0; _i < 2; ++_i) \
;         __builtin_amdgcn_global_load_lds((const unsigned*)((const char*)(gbase) + (voff)[_i]), (PG8_LAS unsigned*)(lds + (bufoff) + ldsw + _i * 8192), 16, 0, 0); } while (0)
; #define PG8_LDA(dst, b, h) do { _Pragma("unroll") for (int m = 0; m < 4; ++m) _Pragma("unroll") for (int k = 0; k < 2; ++k) dst[m][k] = *(const PG8_LAS bf16x8*)(lds + PG8_SA(b, h) + aoff + m * 2048 + k * 1024); } while (0)
; #define PG8_LDB(dst, b, h) do { _Pragma("unroll") for (int n = 0; n < 2; ++n) _Pragma("unroll") for (int k = 0; k < 2; ++k) dst[n][k] = *(const PG8_LAS bf16x8*)(lds + PG8_SB(b, h) + boff + n * 2048 + k * 1024); } while (0)
; #define PG8_MMA(ai, bj, At, Bt) do { __builtin_amdgcn_s_setprio(1); _Pragma("unroll") for (int m = 0; m < 4; ++m) _Pragma("unroll") for (int n = 0; n < 2; ++n) _Pragma("unroll") for (int k = 0; k < 2; ++k) \
;         acc[ai][bj][m][n] = __builtin_amdgcn_mfma_f32_16x16x32_bf16(Bt[n][k], At[m][k], acc[ai][bj][m][n], 0, 0, 0); __builtin_amdgcn_s_setprio(0); } while (0)
; template <class Epi, class Sched, bool ALIGN_EPI = false, bool SP2 = false>
; __device__ __forceinline__ void gemm_phase(PG8_LAS unsigned char* lds, const Gemm g, const Sched& S, const Epi& E, const int tid) {
;     ...
;         const bool has_next = S.next(ui + 1, nxt);
;         const char* nA = has_next ? (const char*)g.A + (size_t)nxt.pm * tstep : cA; const char* nB = has_next ? (const char*)g.Bt + (size_t)nxt.pn * tstep : cB;
;         for (int t = 0; t < nt; t += 2) {
;             const bool last = (t == nt - 2);
;             const char* a1 = cA + (size_t)(t + 1) * kstep;
;             const char* a2 = last ? nA : cA + (size_t)(t + 2) * kstep; const char* b2 = last ? nB : cB + (size_t)(t + 2) * kstep;
;             const char* a3 = a2 + kstep; const char* b3 = b2 + kstep;
;             if (last && has_next) S.a_ready(nxt);
;             if constexpr (SP2) {
;             PG8_LDB(B0, 0, 0); PG8_LDB(B1, 0, 1); PG8_SCHED; PG8_LDA(At, 0, 0); PG8_STAGE(PG8_SA(1, 1), a1 + hstep, voffA);
;             PG8_WAIT_V(8); PG8_WAIT_L(0); PG8_BAR; PG8_MMA(0, 0, At, B0); PG8_MMA(0, 1, At, B1); PG8_BAR; PG8_SCHED;
;             PG8_LDA(At, 0, 1); PG8_STAGE(PG8_SB(0, 0), b2, voffB); PG8_STAGE(PG8_SB(0, 1), b2 + hstep, voffB); PG8_STAGE(PG8_SA(0, 0), a2, voffA);
.LBB0_466:
	s_ashr_i32 s51, s50, 31
	s_lshl_b64 s[20:21], s[50:51], 19
	s_add_u32 s52, s12, s20
	s_addc_u32 s53, s13, s21
	s_and_b64 s[20:21], s[40:41], exec
	s_cselect_b32 s1, s53, s15
	s_cselect_b32 s36, s52, s14
	s_ashr_i32 s49, s48, 31
	s_lshl_b64 s[20:21], s[48:49], 19
	s_add_u32 s68, s22, s20
	s_addc_u32 s69, s23, s21
	s_and_b64 s[20:21], s[40:41], exec
	s_cselect_b32 s37, s69, s17
	s_cselect_b32 s42, s68, s16
	s_add_u32 s14, s14, 0x40080
	s_addc_u32 s15, s15, 0
	s_add_u32 s43, s16, 0x100
	s_addc_u32 s49, s17, 0
	s_mov_b32 s51, -2
	s_add_u32 s16, s14, 0xfffc0080
	s_addc_u32 s17, s15, -1
	s_add_i32 s56, 0, 0x10000
	s_cmp_eq_u32 s51, 12
	s_cselect_b32 s21, s1, s17
	s_cselect_b32 s20, s36, s16
	v_add_u32_e32 v138, s56, v147
	s_cselect_b32 s17, s37, s49
	s_cselect_b32 s16, s42, s43
	s_add_i32 s58, 0, 0x14000
	ds_read_b128 v[140:143], v138
	ds_read_b128 v[154:157], v138 offset:1024
	ds_read_b128 v[162:165], v138 offset:2048
	ds_read_b128 v[166:169], v138 offset:3072
	v_add_u32_e32 v138, s58, v147
	ds_read_b128 v[170:173], v138
	ds_read_b128 v[184:187], v138 offset:1024
	ds_read_b128 v[188:191], v138 offset:2048
	ds_read_b128 v[192:195], v138 offset:3072
	v_lshl_add_u64 v[158:159], s[14:15], 0, v[134:135]
	s_add_i32 m0, s3, 0xc000
	ds_read_b128 v[208:211], v153
	ds_read_b128 v[214:217], v153 offset:1024
	ds_read_b128 v[218:221], v153 offset:2048
	ds_read_b128 v[222:225], v153 offset:3072
	ds_read_b128 v[226:229], v153 offset:4096
	ds_read_b128 v[230:233], v153 offset:5120
	ds_read_b128 v[234:237], v153 offset:6144
	ds_read_b128 v[238:241], v153 offset:7168
	global_load_lds_dwordx4 v[158:159], off
	v_lshl_add_u64 v[158:159], s[14:15], 0, v[136:137]
	s_add_i32 m0, s3, 0xe000
	s_nop 0
	global_load_lds_dwordx4 v[158:159], off
	s_waitcnt vmcnt(24)
	s_waitcnt lgkmcnt(0)
	s_barrier
	s_setprio 1
	s_waitcnt lgkmcnt(0)
	v_mfma_f32_16x16x32_bf16 v[124:127], v[140:143], v[208:211], 0
	v_mfma_f32_16x16x32_bf16 v[120:123], v[162:165], v[208:211], 0
	v_mfma_f32_16x16x32_bf16 v[108:111], v[140:143], v[218:221], 0
	v_mfma_f32_16x16x32_bf16 v[104:107], v[162:165], v[218:221], 0
	v_mfma_f32_16x16x32_bf16 v[92:95], v[140:143], v[226:229], 0
	v_mfma_f32_16x16x32_bf16 v[88:91], v[162:165], v[226:229], 0
	v_mfma_f32_16x16x32_bf16 v[76:79], v[140:143], v[234:237], 0
	v_mfma_f32_16x16x32_bf16 v[72:75], v[162:165], v[234:237], 0
	v_mfma_f32_16x16x32_bf16 v[124:127], v[154:157], v[214:217], v[124:127]
	v_mfma_f32_16x16x32_bf16 v[120:123], v[166:169], v[214:217], v[120:123]
	v_mfma_f32_16x16x32_bf16 v[108:111], v[154:157], v[222:225], v[108:111]
	v_mfma_f32_16x16x32_bf16 v[104:107], v[166:169], v[222:225], v[104:107]
	v_mfma_f32_16x16x32_bf16 v[92:95], v[154:157], v[230:233], v[92:95]
	v_mfma_f32_16x16x32_bf16 v[88:91], v[166:169], v[230:233], v[88:91]
	v_mfma_f32_16x16x32_bf16 v[76:79], v[154:157], v[238:241], v[76:79]
	v_mfma_f32_16x16x32_bf16 v[72:75], v[166:169], v[238:241], v[72:75]
	v_mfma_f32_16x16x32_bf16 v[116:119], v[170:173], v[208:211], 0
	v_mfma_f32_16x16x32_bf16 v[112:115], v[188:191], v[208:211], 0
	v_mfma_f32_16x16x32_bf16 v[100:103], v[170:173], v[218:221], 0
	v_mfma_f32_16x16x32_bf16 v[96:99], v[188:191], v[218:221], 0
	v_mfma_f32_16x16x32_bf16 v[84:87], v[170:173], v[226:229], 0
	v_mfma_f32_16x16x32_bf16 v[80:83], v[188:191], v[226:229], 0
	v_mfma_f32_16x16x32_bf16 v[68:71], v[170:173], v[234:237], 0
	v_mfma_f32_16x16x32_bf16 v[64:67], v[188:191], v[234:237], 0
	v_mfma_f32_16x16x32_bf16 v[116:119], v[184:187], v[214:217], v[116:119]
	v_mfma_f32_16x16x32_bf16 v[112:115], v[192:195], v[214:217], v[112:115]
	v_mfma_f32_16x16x32_bf16 v[100:103], v[184:187], v[222:225], v[100:103]
	v_mfma_f32_16x16x32_bf16 v[96:99], v[192:195], v[222:225], v[96:99]
	v_mfma_f32_16x16x32_bf16 v[84:87], v[184:187], v[230:233], v[84:87]
	v_mfma_f32_16x16x32_bf16 v[80:83], v[192:195], v[230:233], v[80:83]
	v_mfma_f32_16x16x32_bf16 v[68:71], v[184:187], v[238:241], v[68:71]
	v_mfma_f32_16x16x32_bf16 v[64:67], v[192:195], v[238:241], v[64:67]
	s_setprio 0
	s_barrier
	s_add_i32 s56, s56, s27
	v_lshl_add_u64 v[158:159], s[16:17], 0, v[160:161]
	s_mov_b32 m0, s56
	ds_read_b128 v[208:211], v153 offset:16384
	ds_read_b128 v[214:217], v153 offset:17408
	ds_read_b128 v[218:221], v153 offset:18432
	ds_read_b128 v[222:225], v153 offset:19456
	ds_read_b128 v[226:229], v153 offset:20480
	ds_read_b128 v[230:233], v153 offset:21504
	ds_read_b128 v[234:237], v153 offset:22528
	ds_read_b128 v[238:241], v153 offset:23552
	global_load_lds_dwordx4 v[158:159], off
	s_add_i32 m0, s56, 0x2000
	s_add_u32 s56, s16, 0x40000
	v_lshl_add_u64 v[174:175], s[16:17], 0, v[132:133]
	s_addc_u32 s57, s17, 0
	s_add_i32 s58, s58, s27
	global_load_lds_dwordx4 v[174:175], off
	v_lshl_add_u64 v[178:179], s[56:57], 0, v[160:161]
	s_mov_b32 m0, s58
	v_lshl_add_u64 v[180:181], s[20:21], 0, v[130:131]
	global_load_lds_dwordx4 v[178:179], off
	v_lshl_add_u64 v[178:179], s[56:57], 0, v[132:133]
	s_add_i32 m0, s58, 0x2000
	s_nop 0
	global_load_lds_dwordx4 v[178:179], off
	v_lshl_add_u64 v[178:179], s[20:21], 0, v[128:129]
	s_mov_b32 m0, s3
	s_nop 0
	global_load_lds_dwordx4 v[178:179], off
	s_mov_b32 m0, s30
	s_nop 0
	global_load_lds_dwordx4 v[180:181], off
	s_cmp_lt_u32 s83, 2
	s_cbranch_scc1 .Lmy_w8_1
	s_waitcnt vmcnt(24)
	s_branch .Lmy_wj_1

; #define PG8_STAGE(bufoff, gbase, voff) do { _Pragma("unroll") for (int _i = 0; _i < 2; ++_i) \
;         __builtin_amdgcn_global_load_lds((const unsigned*)((const char*)(gbase) + (voff)[_i]), (PG8_LAS unsigned*)(lds + (bufoff) + ldsw + _i * 8192), 16, 0, 0); } while (0)
; #define PG8_LDA(dst, b, h) do { _Pragma("unroll") for (int m = 0; m < 4; ++m) _Pragma("unroll") for (int k = 0; k < 2; ++k) dst[m][k] = *(const PG8_LAS bf16x8*)(lds + PG8_SA(b, h) + aoff + m * 2048 + k * 1024); } while (0)
; #define PG8_LDB(dst, b, h) do { _Pragma("unroll") for (int n = 0; n < 2; ++n) _Pragma("unroll") for (int k = 0; k < 2; ++k) dst[n][k] = *(const PG8_LAS bf16x8*)(lds + PG8_SB(b, h) + boff + n * 2048 + k * 1024); } while (0)
; #define PG8_MMA(ai, bj, At, Bt) do { __builtin_amdgcn_s_setprio(1); _Pragma("unroll") for (int m = 0; m < 4; ++m) _Pragma("unroll") for (int n = 0; n < 2; ++n) _Pragma("unroll") for (int k = 0; k < 2; ++k) \
;         acc[ai][bj][m][n] = __builtin_amdgcn_mfma_f32_16x16x32_bf16(Bt[n][k], At[m][k], acc[ai][bj][m][n], 0, 0, 0); __builtin_amdgcn_s_setprio(0); } while (0)
; #define PG8_WAIT_V(n) asm volatile("s_waitcnt vmcnt(" #n ")" ::: "memory")
; #define PG8_WAIT_L(n) asm volatile("s_waitcnt lgkmcnt(" #n ")" ::: "memory")
; #define PG8_BAR __builtin_amdgcn_s_barrier()
; #define PG8_SCHED __builtin_amdgcn_sched_barrier(0)
; template <class Epi, class Sched, bool ALIGN_EPI = false, bool SP2 = false>
; __device__ __forceinline__ void gemm_phase(PG8_LAS unsigned char* lds, const Gemm g, const Sched& S, const Epi& E, const int tid) {
;     ...
;             PG8_WAIT_V(8); PG8_WAIT_L(0); PG8_BAR; PG8_MMA(1, 0, At, B0); PG8_MMA(1, 1, At, B1); PG8_BAR; PG8_SCHED;
;             PG8_LDB(B0, 1, 0); PG8_LDB(B1, 1, 1); PG8_SCHED; PG8_LDA(At, 1, 0); PG8_STAGE(PG8_SA(0, 1), a2 + hstep, voffA);
;             PG8_WAIT_V(8); PG8_WAIT_L(0); PG8_BAR; PG8_MMA(0, 0, At, B0); PG8_MMA(0, 1, At, B1); PG8_BAR; PG8_SCHED;
.Lmy_wj_1:
	s_waitcnt lgkmcnt(0)
	s_barrier
	s_setprio 1
	s_waitcnt lgkmcnt(0)
	v_mfma_f32_16x16x32_bf16 v[60:63], v[140:143], v[208:211], 0
	v_mfma_f32_16x16x32_bf16 v[56:59], v[162:165], v[208:211], 0
	v_mfma_f32_16x16x32_bf16 v[44:47], v[140:143], v[218:221], 0
	v_mfma_f32_16x16x32_bf16 v[40:43], v[162:165], v[218:221], 0
	v_mfma_f32_16x16x32_bf16 v[28:31], v[140:143], v[226:229], 0
	v_mfma_f32_16x16x32_bf16 v[24:27], v[162:165], v[226:229], 0
	v_mfma_f32_16x16x32_bf16 v[12:15], v[140:143], v[234:237], 0
	v_mfma_f32_16x16x32_bf16 v[8:11], v[162:165], v[234:237], 0
	v_mfma_f32_16x16x32_bf16 v[60:63], v[154:157], v[214:217], v[60:63]
	v_mfma_f32_16x16x32_bf16 v[56:59], v[166:169], v[214:217], v[56:59]
	v_mfma_f32_16x16x32_bf16 v[44:47], v[154:157], v[222:225], v[44:47]
	v_mfma_f32_16x16x32_bf16 v[40:43], v[166:169], v[222:225], v[40:43]
	v_mfma_f32_16x16x32_bf16 v[28:31], v[154:157], v[230:233], v[28:31]
	v_mfma_f32_16x16x32_bf16 v[24:27], v[166:169], v[230:233], v[24:27]
	v_mfma_f32_16x16x32_bf16 v[12:15], v[154:157], v[238:241], v[12:15]
	v_mfma_f32_16x16x32_bf16 v[8:11], v[166:169], v[238:241], v[8:11]
	v_mfma_f32_16x16x32_bf16 v[52:55], v[170:173], v[208:211], 0
	v_mfma_f32_16x16x32_bf16 v[48:51], v[188:191], v[208:211], 0
	v_mfma_f32_16x16x32_bf16 v[36:39], v[170:173], v[218:221], 0
	v_mfma_f32_16x16x32_bf16 v[32:35], v[188:191], v[218:221], 0
	v_mfma_f32_16x16x32_bf16 v[20:23], v[170:173], v[226:229], 0
	v_mfma_f32_16x16x32_bf16 v[16:19], v[188:191], v[226:229], 0
	v_mfma_f32_16x16x32_bf16 v[4:7], v[170:173], v[234:237], 0
	v_mfma_f32_16x16x32_bf16 v[0:3], v[188:191], v[234:237], 0
	v_mfma_f32_16x16x32_bf16 v[52:55], v[184:187], v[214:217], v[52:55]
	v_mfma_f32_16x16x32_bf16 v[48:51], v[192:195], v[214:217], v[48:51]
	v_mfma_f32_16x16x32_bf16 v[36:39], v[184:187], v[222:225], v[36:39]
	v_mfma_f32_16x16x32_bf16 v[32:35], v[192:195], v[222:225], v[32:35]
	v_mfma_f32_16x16x32_bf16 v[20:23], v[184:187], v[230:233], v[20:23]
	v_mfma_f32_16x16x32_bf16 v[16:19], v[192:195], v[230:233], v[16:19]
	v_mfma_f32_16x16x32_bf16 v[4:7], v[184:187], v[238:241], v[4:7]
	v_mfma_f32_16x16x32_bf16 v[0:3], v[192:195], v[238:241], v[0:3]
	s_setprio 0
	s_barrier
	s_add_i32 s56, 0, 0x18000
	v_add_u32_e32 v138, s56, v147
	s_add_i32 s57, 0, 0x1c000
	ds_read_b128 v[140:143], v138
	ds_read_b128 v[154:157], v138 offset:1024
	ds_read_b128 v[162:165], v138 offset:2048
	ds_read_b128 v[166:169], v138 offset:3072
	v_add_u32_e32 v138, s57, v147
	ds_read_b128 v[170:173], v138
	ds_read_b128 v[184:187], v138 offset:1024
	ds_read_b128 v[188:191], v138 offset:2048
	ds_read_b128 v[192:195], v138 offset:3072
	s_add_u32 s20, s20, 0x40000
	s_addc_u32 s21, s21, 0
	s_mov_b32 m0, s31
	v_lshl_add_u64 v[196:197], s[20:21], 0, v[128:129]
	ds_read_b128 v[208:211], v153 offset:32768
	ds_read_b128 v[214:217], v153 offset:33792
	ds_read_b128 v[218:221], v153 offset:34816
	ds_read_b128 v[222:225], v153 offset:35840
	ds_read_b128 v[226:229], v153 offset:36864
	ds_read_b128 v[230:233], v153 offset:37888
	ds_read_b128 v[234:237], v153 offset:38912
	ds_read_b128 v[238:241], v153 offset:39936
	global_load_lds_dwordx4 v[196:197], off
	v_lshl_add_u64 v[196:197], s[20:21], 0, v[130:131]
	s_mov_b32 m0, s34
	s_nop 0
	global_load_lds_dwordx4 v[196:197], off
	s_waitcnt vmcnt(8)
	s_waitcnt lgkmcnt(0)
	s_barrier
	s_setprio 1
	s_waitcnt lgkmcnt(0)
	v_mfma_f32_16x16x32_bf16 v[124:127], v[140:143], v[208:211], v[124:127]
	v_mfma_f32_16x16x32_bf16 v[120:123], v[162:165], v[208:211], v[120:123]
	v_mfma_f32_16x16x32_bf16 v[108:111], v[140:143], v[218:221], v[108:111]
	v_mfma_f32_16x16x32_bf16 v[104:107], v[162:165], v[218:221], v[104:107]
	v_mfma_f32_16x16x32_bf16 v[92:95], v[140:143], v[226:229], v[92:95]
	v_mfma_f32_16x16x32_bf16 v[88:91], v[162:165], v[226:229], v[88:91]
	v_mfma_f32_16x16x32_bf16 v[76:79], v[140:143], v[234:237], v[76:79]
	v_mfma_f32_16x16x32_bf16 v[72:75], v[162:165], v[234:237], v[72:75]
	v_mfma_f32_16x16x32_bf16 v[124:127], v[154:157], v[214:217], v[124:127]
	v_mfma_f32_16x16x32_bf16 v[120:123], v[166:169], v[214:217], v[120:123]
	v_mfma_f32_16x16x32_bf16 v[108:111], v[154:157], v[222:225], v[108:111]
	v_mfma_f32_16x16x32_bf16 v[104:107], v[166:169], v[222:225], v[104:107]
	v_mfma_f32_16x16x32_bf16 v[92:95], v[154:157], v[230:233], v[92:95]
	v_mfma_f32_16x16x32_bf16 v[88:91], v[166:169], v[230:233], v[88:91]
	v_mfma_f32_16x16x32_bf16 v[76:79], v[154:157], v[238:241], v[76:79]
	v_mfma_f32_16x16x32_bf16 v[72:75], v[166:169], v[238:241], v[72:75]
	v_mfma_f32_16x16x32_bf16 v[116:119], v[170:173], v[208:211], v[116:119]
	v_mfma_f32_16x16x32_bf16 v[112:115], v[188:191], v[208:211], v[112:115]
	v_mfma_f32_16x16x32_bf16 v[100:103], v[170:173], v[218:221], v[100:103]
	v_mfma_f32_16x16x32_bf16 v[96:99], v[188:191], v[218:221], v[96:99]
	v_mfma_f32_16x16x32_bf16 v[84:87], v[170:173], v[226:229], v[84:87]
	v_mfma_f32_16x16x32_bf16 v[80:83], v[188:191], v[226:229], v[80:83]
	v_mfma_f32_16x16x32_bf16 v[68:71], v[170:173], v[234:237], v[68:71]
	v_mfma_f32_16x16x32_bf16 v[64:67], v[188:191], v[234:237], v[64:67]
	v_mfma_f32_16x16x32_bf16 v[116:119], v[184:187], v[214:217], v[116:119]
	v_mfma_f32_16x16x32_bf16 v[112:115], v[192:195], v[214:217], v[112:115]
	v_mfma_f32_16x16x32_bf16 v[100:103], v[184:187], v[222:225], v[100:103]
	v_mfma_f32_16x16x32_bf16 v[96:99], v[192:195], v[222:225], v[96:99]
	v_mfma_f32_16x16x32_bf16 v[84:87], v[184:187], v[230:233], v[84:87]
	v_mfma_f32_16x16x32_bf16 v[80:83], v[192:195], v[230:233], v[80:83]
	v_mfma_f32_16x16x32_bf16 v[68:71], v[184:187], v[238:241], v[68:71]
	v_mfma_f32_16x16x32_bf16 v[64:67], v[192:195], v[238:241], v[64:67]
	s_setprio 0
	s_barrier
; #define PG8_STAGE(bufoff, gbase, voff) do { _Pragma("unroll") for (int _i = 0; _i < 2; ++_i) \
;         __builtin_amdgcn_global_load_lds((const unsigned*)((const char*)(gbase) + (voff)[_i]), (PG8_LAS unsigned*)(lds + (bufoff) + ldsw + _i * 8192), 16, 0, 0); } while (0)
; #define PG8_LDA(dst, b, h) do { _Pragma("unroll") for (int m = 0; m < 4; ++m) _Pragma("unroll") for (int k = 0; k < 2; ++k) dst[m][k] = *(const PG8_LAS bf16x8*)(lds + PG8_SA(b, h) + aoff + m * 2048 + k * 1024); } while (0)
; #define PG8_LDB(dst, b, h) do { _Pragma("unroll") for (int n = 0; n < 2; ++n) _Pragma("unroll") for (int k = 0; k < 2; ++k) dst[n][k] = *(const PG8_LAS bf16x8*)(lds + PG8_SB(b, h) + boff + n * 2048 + k * 1024); } while (0)
; #define PG8_MMA(ai, bj, At, Bt) do { __builtin_amdgcn_s_setprio(1); _Pragma("unroll") for (int m = 0; m < 4; ++m) _Pragma("unroll") for (int n = 0; n < 2; ++n) _Pragma("unroll") for (int k = 0; k < 2; ++k) \
;         acc[ai][bj][m][n] = __builtin_amdgcn_mfma_f32_16x16x32_bf16(Bt[n][k], At[m][k], acc[ai][bj][m][n], 0, 0, 0); __builtin_amdgcn_s_setprio(0); } while (0)
; #define PG8_WAIT_V(n) asm volatile("s_waitcnt vmcnt(" #n ")" ::: "memory")
; #define PG8_WAIT_L(n) asm volatile("s_waitcnt lgkmcnt(" #n ")" ::: "memory")
; #define PG8_BAR __builtin_amdgcn_s_barrier()
; template <class Epi, class Sched, bool ALIGN_EPI = false, bool SP2 = false>
; __device__ __forceinline__ void gemm_phase(PG8_LAS unsigned char* lds, const Gemm g, const Sched& S, const Epi& E, const int tid) {
;     ...
;         for (int t = 0; t < nt; t += 2) {
;             const bool last = (t == nt - 2);
;             const char* a1 = cA + (size_t)(t + 1) * kstep;
;             const char* a2 = last ? nA : cA + (size_t)(t + 2) * kstep; const char* b2 = last ? nB : cB + (size_t)(t + 2) * kstep;
;             const char* a3 = a2 + kstep; const char* b3 = b2 + kstep;
;             if (last && has_next) S.a_ready(nxt);
;             if constexpr (SP2) {
;             PG8_LDB(B0, 0, 0); PG8_LDB(B1, 0, 1); PG8_SCHED; PG8_LDA(At, 0, 0); PG8_STAGE(PG8_SA(1, 1), a1 + hstep, voffA);
;     ...
;             PG8_LDA(At, 1, 1); PG8_STAGE(PG8_SB(1, 0), b3, voffB); PG8_STAGE(PG8_SB(1, 1), b3 + hstep, voffB); PG8_STAGE(PG8_SA(1, 0), a3, voffA);
;             PG8_WAIT_V(8); PG8_WAIT_L(0); PG8_BAR; PG8_MMA(1, 0, At, B0); PG8_MMA(1, 1, At, B1); PG8_BAR; PG8_SCHED;
	s_add_i32 s20, s56, s27
	v_lshl_add_u64 v[158:159], v[158:159], 0, s[28:29]
	s_mov_b32 m0, s20
	ds_read_b128 v[208:211], v153 offset:49152
	ds_read_b128 v[214:217], v153 offset:50176
	ds_read_b128 v[218:221], v153 offset:51200
	ds_read_b128 v[222:225], v153 offset:52224
	ds_read_b128 v[226:229], v153 offset:53248
	ds_read_b128 v[230:233], v153 offset:54272
	ds_read_b128 v[234:237], v153 offset:55296
	ds_read_b128 v[238:241], v153 offset:56320
	global_load_lds_dwordx4 v[158:159], off
	s_add_i32 m0, s20, 0x2000
	s_add_u32 s16, s16, 0x40080
	v_lshl_add_u64 v[158:159], v[174:175], 0, s[28:29]
	s_addc_u32 s17, s17, 0
	s_add_i32 s20, s57, s27
	global_load_lds_dwordx4 v[158:159], off
	v_lshl_add_u64 v[158:159], s[16:17], 0, v[160:161]
	s_mov_b32 m0, s20
	s_nop 0
	global_load_lds_dwordx4 v[158:159], off
	v_lshl_add_u64 v[158:159], s[16:17], 0, v[132:133]
	s_add_i32 m0, s20, 0x2000
	s_nop 0
	global_load_lds_dwordx4 v[158:159], off
	v_lshl_add_u64 v[158:159], v[178:179], 0, s[28:29]
	s_mov_b32 m0, s81
	s_nop 0
	global_load_lds_dwordx4 v[158:159], off
	v_lshl_add_u64 v[158:159], v[180:181], 0, s[28:29]
	s_mov_b32 m0, s82
	s_nop 0
	global_load_lds_dwordx4 v[158:159], off
	s_waitcnt vmcnt(8)
	s_waitcnt lgkmcnt(0)
	s_barrier
	s_setprio 1
	s_waitcnt lgkmcnt(0)
	v_mfma_f32_16x16x32_bf16 v[60:63], v[140:143], v[208:211], v[60:63]
	v_mfma_f32_16x16x32_bf16 v[56:59], v[162:165], v[208:211], v[56:59]
	v_mfma_f32_16x16x32_bf16 v[44:47], v[140:143], v[218:221], v[44:47]
	v_mfma_f32_16x16x32_bf16 v[40:43], v[162:165], v[218:221], v[40:43]
	v_mfma_f32_16x16x32_bf16 v[28:31], v[140:143], v[226:229], v[28:31]
	v_mfma_f32_16x16x32_bf16 v[24:27], v[162:165], v[226:229], v[24:27]
	v_mfma_f32_16x16x32_bf16 v[12:15], v[140:143], v[234:237], v[12:15]
	v_mfma_f32_16x16x32_bf16 v[8:11], v[162:165], v[234:237], v[8:11]
	v_mfma_f32_16x16x32_bf16 v[60:63], v[154:157], v[214:217], v[60:63]
	v_mfma_f32_16x16x32_bf16 v[56:59], v[166:169], v[214:217], v[56:59]
	v_mfma_f32_16x16x32_bf16 v[44:47], v[154:157], v[222:225], v[44:47]
	v_mfma_f32_16x16x32_bf16 v[40:43], v[166:169], v[222:225], v[40:43]
	v_mfma_f32_16x16x32_bf16 v[28:31], v[154:157], v[230:233], v[28:31]
	v_mfma_f32_16x16x32_bf16 v[24:27], v[166:169], v[230:233], v[24:27]
	v_mfma_f32_16x16x32_bf16 v[12:15], v[154:157], v[238:241], v[12:15]
	v_mfma_f32_16x16x32_bf16 v[8:11], v[166:169], v[238:241], v[8:11]
	v_mfma_f32_16x16x32_bf16 v[52:55], v[170:173], v[208:211], v[52:55]
	v_mfma_f32_16x16x32_bf16 v[48:51], v[188:191], v[208:211], v[48:51]
	v_mfma_f32_16x16x32_bf16 v[36:39], v[170:173], v[218:221], v[36:39]
	v_mfma_f32_16x16x32_bf16 v[32:35], v[188:191], v[218:221], v[32:35]
	v_mfma_f32_16x16x32_bf16 v[20:23], v[170:173], v[226:229], v[20:23]
	v_mfma_f32_16x16x32_bf16 v[16:19], v[188:191], v[226:229], v[16:19]
	v_mfma_f32_16x16x32_bf16 v[4:7], v[170:173], v[234:237], v[4:7]
	v_mfma_f32_16x16x32_bf16 v[0:3], v[188:191], v[234:237], v[0:3]
	v_mfma_f32_16x16x32_bf16 v[52:55], v[184:187], v[214:217], v[52:55]
	v_mfma_f32_16x16x32_bf16 v[48:51], v[192:195], v[214:217], v[48:51]
	v_mfma_f32_16x16x32_bf16 v[36:39], v[184:187], v[222:225], v[36:39]
	v_mfma_f32_16x16x32_bf16 v[32:35], v[192:195], v[222:225], v[32:35]
	v_mfma_f32_16x16x32_bf16 v[20:23], v[184:187], v[230:233], v[20:23]
	v_mfma_f32_16x16x32_bf16 v[16:19], v[192:195], v[230:233], v[16:19]
	v_mfma_f32_16x16x32_bf16 v[4:7], v[184:187], v[238:241], v[4:7]
	v_mfma_f32_16x16x32_bf16 v[0:3], v[192:195], v[238:241], v[0:3]
	s_setprio 0
	s_barrier
	s_add_i32 s51, s51, 2
	s_add_u32 s14, s14, 0x100
	s_addc_u32 s15, s15, 0
	s_add_u32 s43, s43, 0x100
	s_addc_u32 s49, s49, 0
	s_cmp_gt_u32 s51, 13
	s_cbranch_scc1 .Lmy_kdone_1
.LBB0_467:
	s_add_u32 s16, s14, 0xfffc0080
	s_addc_u32 s17, s15, -1
	s_add_i32 s56, 0, 0x10000
	s_cmp_eq_u32 s51, 12
	s_cselect_b32 s21, s1, s17
	s_cselect_b32 s20, s36, s16
	v_add_u32_e32 v138, s56, v147
	s_cselect_b32 s17, s37, s49
	s_cselect_b32 s16, s42, s43
	s_add_i32 s58, 0, 0x14000
	ds_read_b128 v[140:143], v138
	ds_read_b128 v[154:157], v138 offset:1024
	ds_read_b128 v[162:165], v138 offset:2048
	ds_read_b128 v[166:169], v138 offset:3072
	v_add_u32_e32 v138, s58, v147
	ds_read_b128 v[170:173], v138
	ds_read_b128 v[184:187], v138 offset:1024
	ds_read_b128 v[188:191], v138 offset:2048
	ds_read_b128 v[192:195], v138 offset:3072
	v_lshl_add_u64 v[158:159], s[14:15], 0, v[134:135]
	s_add_i32 m0, s3, 0xc000
	ds_read_b128 v[208:211], v153
	ds_read_b128 v[214:217], v153 offset:1024
	ds_read_b128 v[218:221], v153 offset:2048
	ds_read_b128 v[222:225], v153 offset:3072
	ds_read_b128 v[226:229], v153 offset:4096
	ds_read_b128 v[230:233], v153 offset:5120
	ds_read_b128 v[234:237], v153 offset:6144
	ds_read_b128 v[238:241], v153 offset:7168
	global_load_lds_dwordx4 v[158:159], off
	v_lshl_add_u64 v[158:159], s[14:15], 0, v[136:137]
	s_add_i32 m0, s3, 0xe000
	s_nop 0
	global_load_lds_dwordx4 v[158:159], off
	s_waitcnt vmcnt(8)
	s_waitcnt lgkmcnt(0)
	s_barrier
; #define PG8_STAGE(bufoff, gbase, voff) do { _Pragma("unroll") for (int _i = 0; _i < 2; ++_i) \
;         __builtin_amdgcn_global_load_lds((const unsigned*)((const char*)(gbase) + (voff)[_i]), (PG8_LAS unsigned*)(lds + (bufoff) + ldsw + _i * 8192), 16, 0, 0); } while (0)
; #define PG8_LDA(dst, b, h) do { _Pragma("unroll") for (int m = 0; m < 4; ++m) _Pragma("unroll") for (int k = 0; k < 2; ++k) dst[m][k] = *(const PG8_LAS bf16x8*)(lds + PG8_SA(b, h) + aoff + m * 2048 + k * 1024); } while (0)
; #define PG8_MMA(ai, bj, At, Bt) do { __builtin_amdgcn_s_setprio(1); _Pragma("unroll") for (int m = 0; m < 4; ++m) _Pragma("unroll") for (int n = 0; n < 2; ++n) _Pragma("unroll") for (int k = 0; k < 2; ++k) \
;         acc[ai][bj][m][n] = __builtin_amdgcn_mfma_f32_16x16x32_bf16(Bt[n][k], At[m][k], acc[ai][bj][m][n], 0, 0, 0); __builtin_amdgcn_s_setprio(0); } while (0)
; #define PG8_WAIT_V(n) asm volatile("s_waitcnt vmcnt(" #n ")" ::: "memory")
; #define PG8_WAIT_L(n) asm volatile("s_waitcnt lgkmcnt(" #n ")" ::: "memory")
; #define PG8_BAR __builtin_amdgcn_s_barrier()
; #define PG8_SCHED __builtin_amdgcn_sched_barrier(0)
; template <class Epi, class Sched, bool ALIGN_EPI = false, bool SP2 = false>
; __device__ __forceinline__ void gemm_phase(PG8_LAS unsigned char* lds, const Gemm g, const Sched& S, const Epi& E, const int tid) {
;     ...
;             PG8_WAIT_V(8); PG8_WAIT_L(0); PG8_BAR; PG8_MMA(0, 0, At, B0); PG8_MMA(0, 1, At, B1); PG8_BAR; PG8_SCHED;
;             PG8_LDA(At, 0, 1); PG8_STAGE(PG8_SB(0, 0), b2, voffB); PG8_STAGE(PG8_SB(0, 1), b2 + hstep, voffB); PG8_STAGE(PG8_SA(0, 0), a2, voffA);
;             PG8_WAIT_V(8); PG8_WAIT_L(0); PG8_BAR; PG8_MMA(1, 0, At, B0); PG8_MMA(1, 1, At, B1); PG8_BAR; PG8_SCHED;
	s_setprio 1
	s_waitcnt lgkmcnt(0)
	v_mfma_f32_16x16x32_bf16 v[124:127], v[140:143], v[208:211], v[124:127]
	v_mfma_f32_16x16x32_bf16 v[120:123], v[162:165], v[208:211], v[120:123]
	v_mfma_f32_16x16x32_bf16 v[108:111], v[140:143], v[218:221], v[108:111]
	v_mfma_f32_16x16x32_bf16 v[104:107], v[162:165], v[218:221], v[104:107]
	v_mfma_f32_16x16x32_bf16 v[92:95], v[140:143], v[226:229], v[92:95]
	v_mfma_f32_16x16x32_bf16 v[88:91], v[162:165], v[226:229], v[88:91]
	v_mfma_f32_16x16x32_bf16 v[76:79], v[140:143], v[234:237], v[76:79]
	v_mfma_f32_16x16x32_bf16 v[72:75], v[162:165], v[234:237], v[72:75]
	v_mfma_f32_16x16x32_bf16 v[124:127], v[154:157], v[214:217], v[124:127]
	v_mfma_f32_16x16x32_bf16 v[120:123], v[166:169], v[214:217], v[120:123]
	v_mfma_f32_16x16x32_bf16 v[108:111], v[154:157], v[222:225], v[108:111]
	v_mfma_f32_16x16x32_bf16 v[104:107], v[166:169], v[222:225], v[104:107]
	v_mfma_f32_16x16x32_bf16 v[92:95], v[154:157], v[230:233], v[92:95]
	v_mfma_f32_16x16x32_bf16 v[88:91], v[166:169], v[230:233], v[88:91]
	v_mfma_f32_16x16x32_bf16 v[76:79], v[154:157], v[238:241], v[76:79]
	v_mfma_f32_16x16x32_bf16 v[72:75], v[166:169], v[238:241], v[72:75]
	v_mfma_f32_16x16x32_bf16 v[116:119], v[170:173], v[208:211], v[116:119]
	v_mfma_f32_16x16x32_bf16 v[112:115], v[188:191], v[208:211], v[112:115]
	v_mfma_f32_16x16x32_bf16 v[100:103], v[170:173], v[218:221], v[100:103]
	v_mfma_f32_16x16x32_bf16 v[96:99], v[188:191], v[218:221], v[96:99]
	v_mfma_f32_16x16x32_bf16 v[84:87], v[170:173], v[226:229], v[84:87]
	v_mfma_f32_16x16x32_bf16 v[80:83], v[188:191], v[226:229], v[80:83]
	v_mfma_f32_16x16x32_bf16 v[68:71], v[170:173], v[234:237], v[68:71]
	v_mfma_f32_16x16x32_bf16 v[64:67], v[188:191], v[234:237], v[64:67]
	v_mfma_f32_16x16x32_bf16 v[116:119], v[184:187], v[214:217], v[116:119]
	v_mfma_f32_16x16x32_bf16 v[112:115], v[192:195], v[214:217], v[112:115]
	v_mfma_f32_16x16x32_bf16 v[100:103], v[184:187], v[222:225], v[100:103]
	v_mfma_f32_16x16x32_bf16 v[96:99], v[192:195], v[222:225], v[96:99]
	v_mfma_f32_16x16x32_bf16 v[84:87], v[184:187], v[230:233], v[84:87]
	v_mfma_f32_16x16x32_bf16 v[80:83], v[192:195], v[230:233], v[80:83]
	v_mfma_f32_16x16x32_bf16 v[68:71], v[184:187], v[238:241], v[68:71]
	v_mfma_f32_16x16x32_bf16 v[64:67], v[192:195], v[238:241], v[64:67]
	s_setprio 0
	s_barrier
	s_add_i32 s56, s56, s27
	v_lshl_add_u64 v[158:159], s[16:17], 0, v[160:161]
	s_mov_b32 m0, s56
	ds_read_b128 v[208:211], v153 offset:16384
	ds_read_b128 v[214:217], v153 offset:17408
	ds_read_b128 v[218:221], v153 offset:18432
	ds_read_b128 v[222:225], v153 offset:19456
	ds_read_b128 v[226:229], v153 offset:20480
	ds_read_b128 v[230:233], v153 offset:21504
	ds_read_b128 v[234:237], v153 offset:22528
	ds_read_b128 v[238:241], v153 offset:23552
	global_load_lds_dwordx4 v[158:159], off
	s_add_i32 m0, s56, 0x2000
	s_add_u32 s56, s16, 0x40000
	v_lshl_add_u64 v[174:175], s[16:17], 0, v[132:133]
	s_addc_u32 s57, s17, 0
	s_add_i32 s58, s58, s27
	global_load_lds_dwordx4 v[174:175], off
	v_lshl_add_u64 v[178:179], s[56:57], 0, v[160:161]
	s_mov_b32 m0, s58
	v_lshl_add_u64 v[180:181], s[20:21], 0, v[130:131]
	global_load_lds_dwordx4 v[178:179], off
	v_lshl_add_u64 v[178:179], s[56:57], 0, v[132:133]
	s_add_i32 m0, s58, 0x2000
	s_nop 0
	global_load_lds_dwordx4 v[178:179], off
	v_lshl_add_u64 v[178:179], s[20:21], 0, v[128:129]
	s_mov_b32 m0, s3
	s_nop 0
	global_load_lds_dwordx4 v[178:179], off
	s_mov_b32 m0, s30
	s_nop 0
	global_load_lds_dwordx4 v[180:181], off
	s_waitcnt vmcnt(8)
	s_waitcnt lgkmcnt(0)
	s_barrier
	s_setprio 1
	s_waitcnt lgkmcnt(0)
	v_mfma_f32_16x16x32_bf16 v[60:63], v[140:143], v[208:211], v[60:63]
	v_mfma_f32_16x16x32_bf16 v[56:59], v[162:165], v[208:211], v[56:59]
	v_mfma_f32_16x16x32_bf16 v[44:47], v[140:143], v[218:221], v[44:47]
	v_mfma_f32_16x16x32_bf16 v[40:43], v[162:165], v[218:221], v[40:43]
	v_mfma_f32_16x16x32_bf16 v[28:31], v[140:143], v[226:229], v[28:31]
	v_mfma_f32_16x16x32_bf16 v[24:27], v[162:165], v[226:229], v[24:27]
	v_mfma_f32_16x16x32_bf16 v[12:15], v[140:143], v[234:237], v[12:15]
	v_mfma_f32_16x16x32_bf16 v[8:11], v[162:165], v[234:237], v[8:11]
	v_mfma_f32_16x16x32_bf16 v[60:63], v[154:157], v[214:217], v[60:63]
	v_mfma_f32_16x16x32_bf16 v[56:59], v[166:169], v[214:217], v[56:59]
	v_mfma_f32_16x16x32_bf16 v[44:47], v[154:157], v[222:225], v[44:47]
	v_mfma_f32_16x16x32_bf16 v[40:43], v[166:169], v[222:225], v[40:43]
	v_mfma_f32_16x16x32_bf16 v[28:31], v[154:157], v[230:233], v[28:31]
	v_mfma_f32_16x16x32_bf16 v[24:27], v[166:169], v[230:233], v[24:27]
	v_mfma_f32_16x16x32_bf16 v[12:15], v[154:157], v[238:241], v[12:15]
	v_mfma_f32_16x16x32_bf16 v[8:11], v[166:169], v[238:241], v[8:11]
	v_mfma_f32_16x16x32_bf16 v[52:55], v[170:173], v[208:211], v[52:55]
	v_mfma_f32_16x16x32_bf16 v[48:51], v[188:191], v[208:211], v[48:51]
	v_mfma_f32_16x16x32_bf16 v[36:39], v[170:173], v[218:221], v[36:39]
	v_mfma_f32_16x16x32_bf16 v[32:35], v[188:191], v[218:221], v[32:35]
	v_mfma_f32_16x16x32_bf16 v[20:23], v[170:173], v[226:229], v[20:23]
	v_mfma_f32_16x16x32_bf16 v[16:19], v[188:191], v[226:229], v[16:19]
	v_mfma_f32_16x16x32_bf16 v[4:7], v[170:173], v[234:237], v[4:7]
	v_mfma_f32_16x16x32_bf16 v[0:3], v[188:191], v[234:237], v[0:3]
	v_mfma_f32_16x16x32_bf16 v[52:55], v[184:187], v[214:217], v[52:55]
	v_mfma_f32_16x16x32_bf16 v[48:51], v[192:195], v[214:217], v[48:51]
	v_mfma_f32_16x16x32_bf16 v[36:39], v[184:187], v[222:225], v[36:39]
	v_mfma_f32_16x16x32_bf16 v[32:35], v[192:195], v[222:225], v[32:35]
	v_mfma_f32_16x16x32_bf16 v[20:23], v[184:187], v[230:233], v[20:23]
	v_mfma_f32_16x16x32_bf16 v[16:19], v[192:195], v[230:233], v[16:19]
	v_mfma_f32_16x16x32_bf16 v[4:7], v[184:187], v[238:241], v[4:7]
	v_mfma_f32_16x16x32_bf16 v[0:3], v[192:195], v[238:241], v[0:3]
	s_setprio 0
	s_barrier
; #define PG8_STAGE(bufoff, gbase, voff) do { _Pragma("unroll") for (int _i = 0; _i < 2; ++_i) \
;         __builtin_amdgcn_global_load_lds((const unsigned*)((const char*)(gbase) + (voff)[_i]), (PG8_LAS unsigned*)(lds + (bufoff) + ldsw + _i * 8192), 16, 0, 0); } while (0)
; #define PG8_LDA(dst, b, h) do { _Pragma("unroll") for (int m = 0; m < 4; ++m) _Pragma("unroll") for (int k = 0; k < 2; ++k) dst[m][k] = *(const PG8_LAS bf16x8*)(lds + PG8_SA(b, h) + aoff + m * 2048 + k * 1024); } while (0)
; #define PG8_LDB(dst, b, h) do { _Pragma("unroll") for (int n = 0; n < 2; ++n) _Pragma("unroll") for (int k = 0; k < 2; ++k) dst[n][k] = *(const PG8_LAS bf16x8*)(lds + PG8_SB(b, h) + boff + n * 2048 + k * 1024); } while (0)
; #define PG8_MMA(ai, bj, At, Bt) do { __builtin_amdgcn_s_setprio(1); _Pragma("unroll") for (int m = 0; m < 4; ++m) _Pragma("unroll") for (int n = 0; n < 2; ++n) _Pragma("unroll") for (int k = 0; k < 2; ++k) \
;         acc[ai][bj][m][n] = __builtin_amdgcn_mfma_f32_16x16x32_bf16(Bt[n][k], At[m][k], acc[ai][bj][m][n], 0, 0, 0); __builtin_amdgcn_s_setprio(0); } while (0)
; #define PG8_WAIT_V(n) asm volatile("s_waitcnt vmcnt(" #n ")" ::: "memory")
; #define PG8_WAIT_L(n) asm volatile("s_waitcnt lgkmcnt(" #n ")" ::: "memory")
; #define PG8_BAR __builtin_amdgcn_s_barrier()
; #define PG8_SCHED __builtin_amdgcn_sched_barrier(0)
; template <class Epi, class Sched, bool ALIGN_EPI = false, bool SP2 = false>
; __device__ __forceinline__ void gemm_phase(PG8_LAS unsigned char* lds, const Gemm g, const Sched& S, const Epi& E, const int tid) {
;     ...
;             PG8_LDB(B0, 1, 0); PG8_LDB(B1, 1, 1); PG8_SCHED; PG8_LDA(At, 1, 0); PG8_STAGE(PG8_SA(0, 1), a2 + hstep, voffA);
;             PG8_WAIT_V(8); PG8_WAIT_L(0); PG8_BAR; PG8_MMA(0, 0, At, B0); PG8_MMA(0, 1, At, B1); PG8_BAR; PG8_SCHED;
	s_add_i32 s56, 0, 0x18000
	v_add_u32_e32 v138, s56, v147
	s_add_i32 s57, 0, 0x1c000
	ds_read_b128 v[140:143], v138
	ds_read_b128 v[154:157], v138 offset:1024
	ds_read_b128 v[162:165], v138 offset:2048
	ds_read_b128 v[166:169], v138 offset:3072
	v_add_u32_e32 v138, s57, v147
	ds_read_b128 v[170:173], v138
	ds_read_b128 v[184:187], v138 offset:1024
	ds_read_b128 v[188:191], v138 offset:2048
	ds_read_b128 v[192:195], v138 offset:3072
	s_add_u32 s20, s20, 0x40000
	s_addc_u32 s21, s21, 0
	s_mov_b32 m0, s31
	v_lshl_add_u64 v[196:197], s[20:21], 0, v[128:129]
	ds_read_b128 v[208:211], v153 offset:32768
	ds_read_b128 v[214:217], v153 offset:33792
	ds_read_b128 v[218:221], v153 offset:34816
	ds_read_b128 v[222:225], v153 offset:35840
	ds_read_b128 v[226:229], v153 offset:36864
	ds_read_b128 v[230:233], v153 offset:37888
	ds_read_b128 v[234:237], v153 offset:38912
	ds_read_b128 v[238:241], v153 offset:39936
	global_load_lds_dwordx4 v[196:197], off
	v_lshl_add_u64 v[196:197], s[20:21], 0, v[130:131]
	s_mov_b32 m0, s34
	s_nop 0
	global_load_lds_dwordx4 v[196:197], off
	s_waitcnt vmcnt(8)
	s_waitcnt lgkmcnt(0)
	s_barrier
	s_setprio 1
	s_waitcnt lgkmcnt(0)
	v_mfma_f32_16x16x32_bf16 v[124:127], v[140:143], v[208:211], v[124:127]
	v_mfma_f32_16x16x32_bf16 v[120:123], v[162:165], v[208:211], v[120:123]
	v_mfma_f32_16x16x32_bf16 v[108:111], v[140:143], v[218:221], v[108:111]
	v_mfma_f32_16x16x32_bf16 v[104:107], v[162:165], v[218:221], v[104:107]
	v_mfma_f32_16x16x32_bf16 v[92:95], v[140:143], v[226:229], v[92:95]
	v_mfma_f32_16x16x32_bf16 v[88:91], v[162:165], v[226:229], v[88:91]
	v_mfma_f32_16x16x32_bf16 v[76:79], v[140:143], v[234:237], v[76:79]
	v_mfma_f32_16x16x32_bf16 v[72:75], v[162:165], v[234:237], v[72:75]
	v_mfma_f32_16x16x32_bf16 v[124:127], v[154:157], v[214:217], v[124:127]
	v_mfma_f32_16x16x32_bf16 v[120:123], v[166:169], v[214:217], v[120:123]
	v_mfma_f32_16x16x32_bf16 v[108:111], v[154:157], v[222:225], v[108:111]
	v_mfma_f32_16x16x32_bf16 v[104:107], v[166:169], v[222:225], v[104:107]
	v_mfma_f32_16x16x32_bf16 v[92:95], v[154:157], v[230:233], v[92:95]
	v_mfma_f32_16x16x32_bf16 v[88:91], v[166:169], v[230:233], v[88:91]
	v_mfma_f32_16x16x32_bf16 v[76:79], v[154:157], v[238:241], v[76:79]
	v_mfma_f32_16x16x32_bf16 v[72:75], v[166:169], v[238:241], v[72:75]
	v_mfma_f32_16x16x32_bf16 v[116:119], v[170:173], v[208:211], v[116:119]
	v_mfma_f32_16x16x32_bf16 v[112:115], v[188:191], v[208:211], v[112:115]
	v_mfma_f32_16x16x32_bf16 v[100:103], v[170:173], v[218:221], v[100:103]
	v_mfma_f32_16x16x32_bf16 v[96:99], v[188:191], v[218:221], v[96:99]
	v_mfma_f32_16x16x32_bf16 v[84:87], v[170:173], v[226:229], v[84:87]
	v_mfma_f32_16x16x32_bf16 v[80:83], v[188:191], v[226:229], v[80:83]
	v_mfma_f32_16x16x32_bf16 v[68:71], v[170:173], v[234:237], v[68:71]
	v_mfma_f32_16x16x32_bf16 v[64:67], v[188:191], v[234:237], v[64:67]
	v_mfma_f32_16x16x32_bf16 v[116:119], v[184:187], v[214:217], v[116:119]
	v_mfma_f32_16x16x32_bf16 v[112:115], v[192:195], v[214:217], v[112:115]
	v_mfma_f32_16x16x32_bf16 v[100:103], v[184:187], v[222:225], v[100:103]
	v_mfma_f32_16x16x32_bf16 v[96:99], v[192:195], v[222:225], v[96:99]
	v_mfma_f32_16x16x32_bf16 v[84:87], v[184:187], v[230:233], v[84:87]
	v_mfma_f32_16x16x32_bf16 v[80:83], v[192:195], v[230:233], v[80:83]
	v_mfma_f32_16x16x32_bf16 v[68:71], v[184:187], v[238:241], v[68:71]
	v_mfma_f32_16x16x32_bf16 v[64:67], v[192:195], v[238:241], v[64:67]
	s_setprio 0
	s_barrier
; #define PG8_STAGE(bufoff, gbase, voff) do { _Pragma("unroll") for (int _i = 0; _i < 2; ++_i) \
;         __builtin_amdgcn_global_load_lds((const unsigned*)((const char*)(gbase) + (voff)[_i]), (PG8_LAS unsigned*)(lds + (bufoff) + ldsw + _i * 8192), 16, 0, 0); } while (0)
; #define PG8_LDA(dst, b, h) do { _Pragma("unroll") for (int m = 0; m < 4; ++m) _Pragma("unroll") for (int k = 0; k < 2; ++k) dst[m][k] = *(const PG8_LAS bf16x8*)(lds + PG8_SA(b, h) + aoff + m * 2048 + k * 1024); } while (0)
; #define PG8_MMA(ai, bj, At, Bt) do { __builtin_amdgcn_s_setprio(1); _Pragma("unroll") for (int m = 0; m < 4; ++m) _Pragma("unroll") for (int n = 0; n < 2; ++n) _Pragma("unroll") for (int k = 0; k < 2; ++k) \
;         acc[ai][bj][m][n] = __builtin_amdgcn_mfma_f32_16x16x32_bf16(Bt[n][k], At[m][k], acc[ai][bj][m][n], 0, 0, 0); __builtin_amdgcn_s_setprio(0); } while (0)
; #define PG8_WAIT_V(n) asm volatile("s_waitcnt vmcnt(" #n ")" ::: "memory")
; #define PG8_WAIT_L(n) asm volatile("s_waitcnt lgkmcnt(" #n ")" ::: "memory")
; #define PG8_BAR __builtin_amdgcn_s_barrier()
; #define PG8_SCHED __builtin_amdgcn_sched_barrier(0)
; template <class Epi, class Sched, bool ALIGN_EPI = false, bool SP2 = false>
; __device__ __forceinline__ void gemm_phase(PG8_LAS unsigned char* lds, const Gemm g, const Sched& S, const Epi& E, const int tid) {
;     ...
;             PG8_LDA(At, 1, 1); PG8_STAGE(PG8_SB(1, 0), b3, voffB); PG8_STAGE(PG8_SB(1, 1), b3 + hstep, voffB); PG8_STAGE(PG8_SA(1, 0), a3, voffA);
;             PG8_WAIT_V(8); PG8_WAIT_L(0); PG8_BAR; PG8_MMA(1, 0, At, B0); PG8_MMA(1, 1, At, B1); PG8_BAR; PG8_SCHED;
	s_add_i32 s20, s56, s27
	v_lshl_add_u64 v[158:159], v[158:159], 0, s[28:29]
	s_mov_b32 m0, s20
	ds_read_b128 v[208:211], v153 offset:49152
	ds_read_b128 v[214:217], v153 offset:50176
	ds_read_b128 v[218:221], v153 offset:51200
	ds_read_b128 v[222:225], v153 offset:52224
	ds_read_b128 v[226:229], v153 offset:53248
	ds_read_b128 v[230:233], v153 offset:54272
	ds_read_b128 v[234:237], v153 offset:55296
	ds_read_b128 v[238:241], v153 offset:56320
	global_load_lds_dwordx4 v[158:159], off
	s_add_i32 m0, s20, 0x2000
	s_add_u32 s16, s16, 0x40080
	v_lshl_add_u64 v[158:159], v[174:175], 0, s[28:29]
	s_addc_u32 s17, s17, 0
	s_add_i32 s20, s57, s27
	global_load_lds_dwordx4 v[158:159], off
	v_lshl_add_u64 v[158:159], s[16:17], 0, v[160:161]
	s_mov_b32 m0, s20
	s_nop 0
	global_load_lds_dwordx4 v[158:159], off
	v_lshl_add_u64 v[158:159], s[16:17], 0, v[132:133]
	s_add_i32 m0, s20, 0x2000
	s_nop 0
	global_load_lds_dwordx4 v[158:159], off
	v_lshl_add_u64 v[158:159], v[178:179], 0, s[28:29]
	s_mov_b32 m0, s81
	s_nop 0
	global_load_lds_dwordx4 v[158:159], off
	v_lshl_add_u64 v[158:159], v[180:181], 0, s[28:29]
	s_mov_b32 m0, s82
	s_nop 0
	global_load_lds_dwordx4 v[158:159], off
	s_waitcnt vmcnt(8)
	s_waitcnt lgkmcnt(0)
	s_barrier
	s_setprio 1
	s_waitcnt lgkmcnt(0)
	v_mfma_f32_16x16x32_bf16 v[60:63], v[140:143], v[208:211], v[60:63]
	v_mfma_f32_16x16x32_bf16 v[56:59], v[162:165], v[208:211], v[56:59]
	v_mfma_f32_16x16x32_bf16 v[44:47], v[140:143], v[218:221], v[44:47]
	v_mfma_f32_16x16x32_bf16 v[40:43], v[162:165], v[218:221], v[40:43]
	v_mfma_f32_16x16x32_bf16 v[28:31], v[140:143], v[226:229], v[28:31]
	v_mfma_f32_16x16x32_bf16 v[24:27], v[162:165], v[226:229], v[24:27]
	v_mfma_f32_16x16x32_bf16 v[12:15], v[140:143], v[234:237], v[12:15]
	v_mfma_f32_16x16x32_bf16 v[8:11], v[162:165], v[234:237], v[8:11]
	v_mfma_f32_16x16x32_bf16 v[60:63], v[154:157], v[214:217], v[60:63]
	v_mfma_f32_16x16x32_bf16 v[56:59], v[166:169], v[214:217], v[56:59]
	v_mfma_f32_16x16x32_bf16 v[44:47], v[154:157], v[222:225], v[44:47]
	v_mfma_f32_16x16x32_bf16 v[40:43], v[166:169], v[222:225], v[40:43]
	v_mfma_f32_16x16x32_bf16 v[28:31], v[154:157], v[230:233], v[28:31]
	v_mfma_f32_16x16x32_bf16 v[24:27], v[166:169], v[230:233], v[24:27]
	v_mfma_f32_16x16x32_bf16 v[12:15], v[154:157], v[238:241], v[12:15]
	v_mfma_f32_16x16x32_bf16 v[8:11], v[166:169], v[238:241], v[8:11]
	v_mfma_f32_16x16x32_bf16 v[52:55], v[170:173], v[208:211], v[52:55]
	v_mfma_f32_16x16x32_bf16 v[48:51], v[188:191], v[208:211], v[48:51]
	v_mfma_f32_16x16x32_bf16 v[36:39], v[170:173], v[218:221], v[36:39]
	v_mfma_f32_16x16x32_bf16 v[32:35], v[188:191], v[218:221], v[32:35]
	v_mfma_f32_16x16x32_bf16 v[20:23], v[170:173], v[226:229], v[20:23]
	v_mfma_f32_16x16x32_bf16 v[16:19], v[188:191], v[226:229], v[16:19]
	v_mfma_f32_16x16x32_bf16 v[4:7], v[170:173], v[234:237], v[4:7]
	v_mfma_f32_16x16x32_bf16 v[0:3], v[188:191], v[234:237], v[0:3]
	v_mfma_f32_16x16x32_bf16 v[52:55], v[184:187], v[214:217], v[52:55]
	v_mfma_f32_16x16x32_bf16 v[48:51], v[192:195], v[214:217], v[48:51]
	v_mfma_f32_16x16x32_bf16 v[36:39], v[184:187], v[222:225], v[36:39]
	v_mfma_f32_16x16x32_bf16 v[32:35], v[192:195], v[222:225], v[32:35]
	v_mfma_f32_16x16x32_bf16 v[20:23], v[184:187], v[230:233], v[20:23]
	v_mfma_f32_16x16x32_bf16 v[16:19], v[192:195], v[230:233], v[16:19]
	v_mfma_f32_16x16x32_bf16 v[4:7], v[184:187], v[238:241], v[4:7]
	v_mfma_f32_16x16x32_bf16 v[0:3], v[192:195], v[238:241], v[0:3]
	s_setprio 0
	s_barrier
	s_add_i32 s51, s51, 2
	s_add_u32 s14, s14, 0x100
	s_addc_u32 s15, s15, 0
	s_add_u32 s43, s43, 0x100
	s_addc_u32 s49, s49, 0
	s_cmp_gt_u32 s51, 13
	s_cbranch_scc0 .LBB0_467

; #define PG8_STAGE(bufoff, gbase, voff) do { _Pragma("unroll") for (int _i = 0; _i < 2; ++_i) \
;         __builtin_amdgcn_global_load_lds((const unsigned*)((const char*)(gbase) + (voff)[_i]), (PG8_LAS unsigned*)(lds + (bufoff) + ldsw + _i * 8192), 16, 0, 0); } while (0)
; #define PG8_LDA(dst, b, h) do { _Pragma("unroll") for (int m = 0; m < 4; ++m) _Pragma("unroll") for (int k = 0; k < 2; ++k) dst[m][k] = *(const PG8_LAS bf16x8*)(lds + PG8_SA(b, h) + aoff + m * 2048 + k * 1024); } while (0)
; #define PG8_LDB(dst, b, h) do { _Pragma("unroll") for (int n = 0; n < 2; ++n) _Pragma("unroll") for (int k = 0; k < 2; ++k) dst[n][k] = *(const PG8_LAS bf16x8*)(lds + PG8_SB(b, h) + boff + n * 2048 + k * 1024); } while (0)
; #define PG8_MMA(ai, bj, At, Bt) do { __builtin_amdgcn_s_setprio(1); _Pragma("unroll") for (int m = 0; m < 4; ++m) _Pragma("unroll") for (int n = 0; n < 2; ++n) _Pragma("unroll") for (int k = 0; k < 2; ++k) \
;         acc[ai][bj][m][n] = __builtin_amdgcn_mfma_f32_16x16x32_bf16(Bt[n][k], At[m][k], acc[ai][bj][m][n], 0, 0, 0); __builtin_amdgcn_s_setprio(0); } while (0)
; template <class Epi, class Sched, bool ALIGN_EPI = false, bool SP2 = false>
; __device__ __forceinline__ void gemm_phase(PG8_LAS unsigned char* lds, const Gemm g, const Sched& S, const Epi& E, const int tid) {
;     ...
;         const bool has_next = S.next(ui + 1, nxt);
;         const char* nA = has_next ? (const char*)g.A + (size_t)nxt.pm * tstep : cA; const char* nB = has_next ? (const char*)g.Bt + (size_t)nxt.pn * tstep : cB;
;         for (int t = 0; t < nt; t += 2) {
;             const bool last = (t == nt - 2);
;             const char* a1 = cA + (size_t)(t + 1) * kstep;
;             const char* a2 = last ? nA : cA + (size_t)(t + 2) * kstep; const char* b2 = last ? nB : cB + (size_t)(t + 2) * kstep;
;             const char* a3 = a2 + kstep; const char* b3 = b2 + kstep;
;             if (last && has_next) S.a_ready(nxt);
;             if constexpr (SP2) {
;             PG8_LDB(B0, 0, 0); PG8_LDB(B1, 0, 1); PG8_SCHED; PG8_LDA(At, 0, 0); PG8_STAGE(PG8_SA(1, 1), a1 + hstep, voffA);
;             PG8_WAIT_V(8); PG8_WAIT_L(0); PG8_BAR; PG8_MMA(0, 0, At, B0); PG8_MMA(0, 1, At, B1); PG8_BAR; PG8_SCHED;
;             PG8_LDA(At, 0, 1); PG8_STAGE(PG8_SB(0, 0), b2, voffB); PG8_STAGE(PG8_SB(0, 1), b2 + hstep, voffB); PG8_STAGE(PG8_SA(0, 0), a2, voffA);
.LBB0_516:
	s_ashr_i32 s11, s10, 31
	s_lshl_b64 s[12:13], s[10:11], 19
	s_add_u32 s12, s27, s12
	s_addc_u32 s13, s26, s13
	s_and_b64 s[14:15], s[40:41], exec
	s_cselect_b32 s11, s13, s19
	s_cselect_b32 s36, s12, s18
	s_ashr_i32 s9, s8, 31
	s_lshl_b64 s[14:15], s[8:9], 19
	s_add_u32 s14, s30, s14
	s_addc_u32 s15, s31, s15
	s_and_b64 s[22:23], s[40:41], exec
	s_cselect_b32 s9, s15, s21
	s_cselect_b32 s37, s14, s20
	s_add_u32 s18, s18, 0x40080
	s_addc_u32 s19, s19, 0
	s_add_u32 s42, s20, 0x100
	s_addc_u32 s43, s21, 0
	s_mov_b32 s51, -2
	s_add_u32 s20, s18, 0xfffc0080
	s_addc_u32 s21, s19, -1
	s_add_i32 s52, 0, 0x10000
	s_cmp_eq_u32 s51, 12
	s_cselect_b32 s23, s11, s21
	s_cselect_b32 s22, s36, s20
	v_add_u32_e32 v138, s52, v141
	s_cselect_b32 s21, s9, s43
	s_cselect_b32 s20, s37, s42
	s_add_i32 s56, 0, 0x14000
	ds_read_b128 v[150:153], v138
	ds_read_b128 v[154:157], v138 offset:1024
	ds_read_b128 v[162:165], v138 offset:2048
	ds_read_b128 v[166:169], v138 offset:3072
	v_add_u32_e32 v138, s56, v141
	ds_read_b128 v[170:173], v138
	ds_read_b128 v[184:187], v138 offset:1024
	ds_read_b128 v[188:191], v138 offset:2048
	ds_read_b128 v[192:195], v138 offset:3072
	v_lshl_add_u64 v[158:159], s[18:19], 0, v[134:135]
	s_add_i32 m0, s35, 0xc000
	ds_read_b128 v[208:211], v149
	ds_read_b128 v[214:217], v149 offset:1024
	ds_read_b128 v[218:221], v149 offset:2048
	ds_read_b128 v[222:225], v149 offset:3072
	ds_read_b128 v[226:229], v149 offset:4096
	ds_read_b128 v[230:233], v149 offset:5120
	ds_read_b128 v[234:237], v149 offset:6144
	ds_read_b128 v[238:241], v149 offset:7168
	global_load_lds_dwordx4 v[158:159], off
	v_lshl_add_u64 v[158:159], s[18:19], 0, v[136:137]
	s_add_i32 m0, s35, 0xe000
	s_nop 0
	global_load_lds_dwordx4 v[158:159], off
	s_waitcnt vmcnt(16)
	s_waitcnt lgkmcnt(0)
	s_barrier
	s_setprio 1
	s_waitcnt lgkmcnt(0)
	v_mfma_f32_16x16x32_bf16 v[124:127], v[150:153], v[208:211], 0
	v_mfma_f32_16x16x32_bf16 v[116:119], v[162:165], v[208:211], 0
	v_mfma_f32_16x16x32_bf16 v[108:111], v[150:153], v[218:221], 0
	v_mfma_f32_16x16x32_bf16 v[100:103], v[162:165], v[218:221], 0
	v_mfma_f32_16x16x32_bf16 v[92:95], v[150:153], v[226:229], 0
	v_mfma_f32_16x16x32_bf16 v[84:87], v[162:165], v[226:229], 0
	v_mfma_f32_16x16x32_bf16 v[76:79], v[150:153], v[234:237], 0
	v_mfma_f32_16x16x32_bf16 v[68:71], v[162:165], v[234:237], 0
	v_mfma_f32_16x16x32_bf16 v[124:127], v[154:157], v[214:217], v[124:127]
	v_mfma_f32_16x16x32_bf16 v[116:119], v[166:169], v[214:217], v[116:119]
	v_mfma_f32_16x16x32_bf16 v[108:111], v[154:157], v[222:225], v[108:111]
	v_mfma_f32_16x16x32_bf16 v[100:103], v[166:169], v[222:225], v[100:103]
	v_mfma_f32_16x16x32_bf16 v[92:95], v[154:157], v[230:233], v[92:95]
	v_mfma_f32_16x16x32_bf16 v[84:87], v[166:169], v[230:233], v[84:87]
	v_mfma_f32_16x16x32_bf16 v[76:79], v[154:157], v[238:241], v[76:79]
	v_mfma_f32_16x16x32_bf16 v[68:71], v[166:169], v[238:241], v[68:71]
	v_mfma_f32_16x16x32_bf16 v[120:123], v[170:173], v[208:211], 0
	v_mfma_f32_16x16x32_bf16 v[112:115], v[188:191], v[208:211], 0
	v_mfma_f32_16x16x32_bf16 v[104:107], v[170:173], v[218:221], 0
	v_mfma_f32_16x16x32_bf16 v[96:99], v[188:191], v[218:221], 0
	v_mfma_f32_16x16x32_bf16 v[88:91], v[170:173], v[226:229], 0
	v_mfma_f32_16x16x32_bf16 v[80:83], v[188:191], v[226:229], 0
	v_mfma_f32_16x16x32_bf16 v[72:75], v[170:173], v[234:237], 0
	v_mfma_f32_16x16x32_bf16 v[64:67], v[188:191], v[234:237], 0
	v_mfma_f32_16x16x32_bf16 v[120:123], v[184:187], v[214:217], v[120:123]
	v_mfma_f32_16x16x32_bf16 v[112:115], v[192:195], v[214:217], v[112:115]
	v_mfma_f32_16x16x32_bf16 v[104:107], v[184:187], v[222:225], v[104:107]
	v_mfma_f32_16x16x32_bf16 v[96:99], v[192:195], v[222:225], v[96:99]
	v_mfma_f32_16x16x32_bf16 v[88:91], v[184:187], v[230:233], v[88:91]
	v_mfma_f32_16x16x32_bf16 v[80:83], v[192:195], v[230:233], v[80:83]
	v_mfma_f32_16x16x32_bf16 v[72:75], v[184:187], v[238:241], v[72:75]
	v_mfma_f32_16x16x32_bf16 v[64:67], v[192:195], v[238:241], v[64:67]
	s_setprio 0
	s_barrier
	s_add_i32 s52, s52, s34
	v_lshl_add_u64 v[158:159], s[20:21], 0, v[160:161]
	s_mov_b32 m0, s52
	ds_read_b128 v[208:211], v149 offset:16384
	ds_read_b128 v[214:217], v149 offset:17408
	ds_read_b128 v[218:221], v149 offset:18432
	ds_read_b128 v[222:225], v149 offset:19456
	ds_read_b128 v[226:229], v149 offset:20480
	ds_read_b128 v[230:233], v149 offset:21504
	ds_read_b128 v[234:237], v149 offset:22528
	ds_read_b128 v[238:241], v149 offset:23552
	global_load_lds_dwordx4 v[158:159], off
	s_add_i32 m0, s52, 0x2000
	s_add_u32 s52, s20, 0x40000
	v_lshl_add_u64 v[174:175], s[20:21], 0, v[132:133]
	s_addc_u32 s53, s21, 0
	s_add_i32 s56, s56, s34
	global_load_lds_dwordx4 v[174:175], off
	v_lshl_add_u64 v[178:179], s[52:53], 0, v[160:161]
	s_mov_b32 m0, s56
	v_lshl_add_u64 v[180:181], s[22:23], 0, v[130:131]
	global_load_lds_dwordx4 v[178:179], off
	v_lshl_add_u64 v[178:179], s[52:53], 0, v[132:133]
	s_add_i32 m0, s56, 0x2000
	s_nop 0
	global_load_lds_dwordx4 v[178:179], off
	v_lshl_add_u64 v[178:179], s[22:23], 0, v[128:129]
	s_mov_b32 m0, s35
	s_nop 0
	global_load_lds_dwordx4 v[178:179], off
	s_mov_b32 m0, s44
	s_nop 0
	global_load_lds_dwordx4 v[180:181], off
	s_cmp_lt_u32 s47, 2
	s_cbranch_scc1 .Lmy_w8_2
	s_waitcnt vmcnt(16)
	s_branch .Lmy_wj_2

; #define PG8_STAGE(bufoff, gbase, voff) do { _Pragma("unroll") for (int _i = 0; _i < 2; ++_i) \
;         __builtin_amdgcn_global_load_lds((const unsigned*)((const char*)(gbase) + (voff)[_i]), (PG8_LAS unsigned*)(lds + (bufoff) + ldsw + _i * 8192), 16, 0, 0); } while (0)
; #define PG8_LDA(dst, b, h) do { _Pragma("unroll") for (int m = 0; m < 4; ++m) _Pragma("unroll") for (int k = 0; k < 2; ++k) dst[m][k] = *(const PG8_LAS bf16x8*)(lds + PG8_SA(b, h) + aoff + m * 2048 + k * 1024); } while (0)
; #define PG8_LDB(dst, b, h) do { _Pragma("unroll") for (int n = 0; n < 2; ++n) _Pragma("unroll") for (int k = 0; k < 2; ++k) dst[n][k] = *(const PG8_LAS bf16x8*)(lds + PG8_SB(b, h) + boff + n * 2048 + k * 1024); } while (0)
; #define PG8_MMA(ai, bj, At, Bt) do { __builtin_amdgcn_s_setprio(1); _Pragma("unroll") for (int m = 0; m < 4; ++m) _Pragma("unroll") for (int n = 0; n < 2; ++n) _Pragma("unroll") for (int k = 0; k < 2; ++k) \
;         acc[ai][bj][m][n] = __builtin_amdgcn_mfma_f32_16x16x32_bf16(Bt[n][k], At[m][k], acc[ai][bj][m][n], 0, 0, 0); __builtin_amdgcn_s_setprio(0); } while (0)
; #define PG8_WAIT_V(n) asm volatile("s_waitcnt vmcnt(" #n ")" ::: "memory")
; #define PG8_WAIT_L(n) asm volatile("s_waitcnt lgkmcnt(" #n ")" ::: "memory")
; #define PG8_BAR __builtin_amdgcn_s_barrier()
; #define PG8_SCHED __builtin_amdgcn_sched_barrier(0)
; template <class Epi, class Sched, bool ALIGN_EPI = false, bool SP2 = false>
; __device__ __forceinline__ void gemm_phase(PG8_LAS unsigned char* lds, const Gemm g, const Sched& S, const Epi& E, const int tid) {
;     ...
;             PG8_WAIT_V(8); PG8_WAIT_L(0); PG8_BAR; PG8_MMA(1, 0, At, B0); PG8_MMA(1, 1, At, B1); PG8_BAR; PG8_SCHED;
;             PG8_LDB(B0, 1, 0); PG8_LDB(B1, 1, 1); PG8_SCHED; PG8_LDA(At, 1, 0); PG8_STAGE(PG8_SA(0, 1), a2 + hstep, voffA);
;             PG8_WAIT_V(8); PG8_WAIT_L(0); PG8_BAR; PG8_MMA(0, 0, At, B0); PG8_MMA(0, 1, At, B1); PG8_BAR; PG8_SCHED;
.Lmy_wj_2:
	s_waitcnt lgkmcnt(0)
	s_barrier
	s_setprio 1
	s_waitcnt lgkmcnt(0)
	v_mfma_f32_16x16x32_bf16 v[60:63], v[150:153], v[208:211], 0
	v_mfma_f32_16x16x32_bf16 v[52:55], v[162:165], v[208:211], 0
	v_mfma_f32_16x16x32_bf16 v[44:47], v[150:153], v[218:221], 0
	v_mfma_f32_16x16x32_bf16 v[36:39], v[162:165], v[218:221], 0
	v_mfma_f32_16x16x32_bf16 v[28:31], v[150:153], v[226:229], 0
	v_mfma_f32_16x16x32_bf16 v[20:23], v[162:165], v[226:229], 0
	v_mfma_f32_16x16x32_bf16 v[12:15], v[150:153], v[234:237], 0
	v_mfma_f32_16x16x32_bf16 v[4:7], v[162:165], v[234:237], 0
	v_mfma_f32_16x16x32_bf16 v[60:63], v[154:157], v[214:217], v[60:63]
	v_mfma_f32_16x16x32_bf16 v[52:55], v[166:169], v[214:217], v[52:55]
	v_mfma_f32_16x16x32_bf16 v[44:47], v[154:157], v[222:225], v[44:47]
	v_mfma_f32_16x16x32_bf16 v[36:39], v[166:169], v[222:225], v[36:39]
	v_mfma_f32_16x16x32_bf16 v[28:31], v[154:157], v[230:233], v[28:31]
	v_mfma_f32_16x16x32_bf16 v[20:23], v[166:169], v[230:233], v[20:23]
	v_mfma_f32_16x16x32_bf16 v[12:15], v[154:157], v[238:241], v[12:15]
	v_mfma_f32_16x16x32_bf16 v[4:7], v[166:169], v[238:241], v[4:7]
	v_mfma_f32_16x16x32_bf16 v[56:59], v[170:173], v[208:211], 0
	v_mfma_f32_16x16x32_bf16 v[48:51], v[188:191], v[208:211], 0
	v_mfma_f32_16x16x32_bf16 v[40:43], v[170:173], v[218:221], 0
	v_mfma_f32_16x16x32_bf16 v[32:35], v[188:191], v[218:221], 0
	v_mfma_f32_16x16x32_bf16 v[24:27], v[170:173], v[226:229], 0
	v_mfma_f32_16x16x32_bf16 v[16:19], v[188:191], v[226:229], 0
	v_mfma_f32_16x16x32_bf16 v[8:11], v[170:173], v[234:237], 0
	v_mfma_f32_16x16x32_bf16 v[0:3], v[188:191], v[234:237], 0
	v_mfma_f32_16x16x32_bf16 v[56:59], v[184:187], v[214:217], v[56:59]
	v_mfma_f32_16x16x32_bf16 v[48:51], v[192:195], v[214:217], v[48:51]
	v_mfma_f32_16x16x32_bf16 v[40:43], v[184:187], v[222:225], v[40:43]
	v_mfma_f32_16x16x32_bf16 v[32:35], v[192:195], v[222:225], v[32:35]
	v_mfma_f32_16x16x32_bf16 v[24:27], v[184:187], v[230:233], v[24:27]
	v_mfma_f32_16x16x32_bf16 v[16:19], v[192:195], v[230:233], v[16:19]
	v_mfma_f32_16x16x32_bf16 v[8:11], v[184:187], v[238:241], v[8:11]
	v_mfma_f32_16x16x32_bf16 v[0:3], v[192:195], v[238:241], v[0:3]
	s_setprio 0
	s_barrier
	s_add_i32 s52, 0, 0x18000
	v_add_u32_e32 v138, s52, v141
	s_add_i32 s53, 0, 0x1c000
	ds_read_b128 v[150:153], v138
	ds_read_b128 v[154:157], v138 offset:1024
	ds_read_b128 v[162:165], v138 offset:2048
	ds_read_b128 v[166:169], v138 offset:3072
	v_add_u32_e32 v138, s53, v141
	ds_read_b128 v[170:173], v138
	ds_read_b128 v[184:187], v138 offset:1024
	ds_read_b128 v[188:191], v138 offset:2048
	ds_read_b128 v[192:195], v138 offset:3072
	s_add_u32 s22, s22, 0x40000
	s_addc_u32 s23, s23, 0
	s_mov_b32 m0, s45
	v_lshl_add_u64 v[196:197], s[22:23], 0, v[128:129]
	ds_read_b128 v[208:211], v149 offset:32768
	ds_read_b128 v[214:217], v149 offset:33792
	ds_read_b128 v[218:221], v149 offset:34816
	ds_read_b128 v[222:225], v149 offset:35840
	ds_read_b128 v[226:229], v149 offset:36864
	ds_read_b128 v[230:233], v149 offset:37888
	ds_read_b128 v[234:237], v149 offset:38912
	ds_read_b128 v[238:241], v149 offset:39936
	global_load_lds_dwordx4 v[196:197], off
	v_lshl_add_u64 v[196:197], s[22:23], 0, v[130:131]
	s_mov_b32 m0, s46
	s_nop 0
	global_load_lds_dwordx4 v[196:197], off
	s_waitcnt vmcnt(8)
	s_waitcnt lgkmcnt(0)
	s_barrier
	s_setprio 1
	s_waitcnt lgkmcnt(0)
	v_mfma_f32_16x16x32_bf16 v[124:127], v[150:153], v[208:211], v[124:127]
	v_mfma_f32_16x16x32_bf16 v[116:119], v[162:165], v[208:211], v[116:119]
	v_mfma_f32_16x16x32_bf16 v[108:111], v[150:153], v[218:221], v[108:111]
	v_mfma_f32_16x16x32_bf16 v[100:103], v[162:165], v[218:221], v[100:103]
	v_mfma_f32_16x16x32_bf16 v[92:95], v[150:153], v[226:229], v[92:95]
	v_mfma_f32_16x16x32_bf16 v[84:87], v[162:165], v[226:229], v[84:87]
	v_mfma_f32_16x16x32_bf16 v[76:79], v[150:153], v[234:237], v[76:79]
	v_mfma_f32_16x16x32_bf16 v[68:71], v[162:165], v[234:237], v[68:71]
	v_mfma_f32_16x16x32_bf16 v[124:127], v[154:157], v[214:217], v[124:127]
	v_mfma_f32_16x16x32_bf16 v[116:119], v[166:169], v[214:217], v[116:119]
	v_mfma_f32_16x16x32_bf16 v[108:111], v[154:157], v[222:225], v[108:111]
	v_mfma_f32_16x16x32_bf16 v[100:103], v[166:169], v[222:225], v[100:103]
	v_mfma_f32_16x16x32_bf16 v[92:95], v[154:157], v[230:233], v[92:95]
	v_mfma_f32_16x16x32_bf16 v[84:87], v[166:169], v[230:233], v[84:87]
	v_mfma_f32_16x16x32_bf16 v[76:79], v[154:157], v[238:241], v[76:79]
	v_mfma_f32_16x16x32_bf16 v[68:71], v[166:169], v[238:241], v[68:71]
	v_mfma_f32_16x16x32_bf16 v[120:123], v[170:173], v[208:211], v[120:123]
	v_mfma_f32_16x16x32_bf16 v[112:115], v[188:191], v[208:211], v[112:115]
	v_mfma_f32_16x16x32_bf16 v[104:107], v[170:173], v[218:221], v[104:107]
	v_mfma_f32_16x16x32_bf16 v[96:99], v[188:191], v[218:221], v[96:99]
	v_mfma_f32_16x16x32_bf16 v[88:91], v[170:173], v[226:229], v[88:91]
	v_mfma_f32_16x16x32_bf16 v[80:83], v[188:191], v[226:229], v[80:83]
	v_mfma_f32_16x16x32_bf16 v[72:75], v[170:173], v[234:237], v[72:75]
	v_mfma_f32_16x16x32_bf16 v[64:67], v[188:191], v[234:237], v[64:67]
	v_mfma_f32_16x16x32_bf16 v[120:123], v[184:187], v[214:217], v[120:123]
	v_mfma_f32_16x16x32_bf16 v[112:115], v[192:195], v[214:217], v[112:115]
	v_mfma_f32_16x16x32_bf16 v[104:107], v[184:187], v[222:225], v[104:107]
	v_mfma_f32_16x16x32_bf16 v[96:99], v[192:195], v[222:225], v[96:99]
	v_mfma_f32_16x16x32_bf16 v[88:91], v[184:187], v[230:233], v[88:91]
	v_mfma_f32_16x16x32_bf16 v[80:83], v[192:195], v[230:233], v[80:83]
	v_mfma_f32_16x16x32_bf16 v[72:75], v[184:187], v[238:241], v[72:75]
	v_mfma_f32_16x16x32_bf16 v[64:67], v[192:195], v[238:241], v[64:67]
	s_setprio 0
	s_barrier
; #define PG8_STAGE(bufoff, gbase, voff) do { _Pragma("unroll") for (int _i = 0; _i < 2; ++_i) \
;         __builtin_amdgcn_global_load_lds((const unsigned*)((const char*)(gbase) + (voff)[_i]), (PG8_LAS unsigned*)(lds + (bufoff) + ldsw + _i * 8192), 16, 0, 0); } while (0)
; #define PG8_LDA(dst, b, h) do { _Pragma("unroll") for (int m = 0; m < 4; ++m) _Pragma("unroll") for (int k = 0; k < 2; ++k) dst[m][k] = *(const PG8_LAS bf16x8*)(lds + PG8_SA(b, h) + aoff + m * 2048 + k * 1024); } while (0)
; #define PG8_LDB(dst, b, h) do { _Pragma("unroll") for (int n = 0; n < 2; ++n) _Pragma("unroll") for (int k = 0; k < 2; ++k) dst[n][k] = *(const PG8_LAS bf16x8*)(lds + PG8_SB(b, h) + boff + n * 2048 + k * 1024); } while (0)
; #define PG8_MMA(ai, bj, At, Bt) do { __builtin_amdgcn_s_setprio(1); _Pragma("unroll") for (int m = 0; m < 4; ++m) _Pragma("unroll") for (int n = 0; n < 2; ++n) _Pragma("unroll") for (int k = 0; k < 2; ++k) \
;         acc[ai][bj][m][n] = __builtin_amdgcn_mfma_f32_16x16x32_bf16(Bt[n][k], At[m][k], acc[ai][bj][m][n], 0, 0, 0); __builtin_amdgcn_s_setprio(0); } while (0)
; #define PG8_WAIT_V(n) asm volatile("s_waitcnt vmcnt(" #n ")" ::: "memory")
; #define PG8_WAIT_L(n) asm volatile("s_waitcnt lgkmcnt(" #n ")" ::: "memory")
; #define PG8_BAR __builtin_amdgcn_s_barrier()
; template <class Epi, class Sched, bool ALIGN_EPI = false, bool SP2 = false>
; __device__ __forceinline__ void gemm_phase(PG8_LAS unsigned char* lds, const Gemm g, const Sched& S, const Epi& E, const int tid) {
;     ...
;         for (int t = 0; t < nt; t += 2) {
;             const bool last = (t == nt - 2);
;             const char* a1 = cA + (size_t)(t + 1) * kstep;
;             const char* a2 = last ? nA : cA + (size_t)(t + 2) * kstep; const char* b2 = last ? nB : cB + (size_t)(t + 2) * kstep;
;             const char* a3 = a2 + kstep; const char* b3 = b2 + kstep;
;             if (last && has_next) S.a_ready(nxt);
;             if constexpr (SP2) {
;             PG8_LDB(B0, 0, 0); PG8_LDB(B1, 0, 1); PG8_SCHED; PG8_LDA(At, 0, 0); PG8_STAGE(PG8_SA(1, 1), a1 + hstep, voffA);
;     ...
;             PG8_LDA(At, 1, 1); PG8_STAGE(PG8_SB(1, 0), b3, voffB); PG8_STAGE(PG8_SB(1, 1), b3 + hstep, voffB); PG8_STAGE(PG8_SA(1, 0), a3, voffA);
;             PG8_WAIT_V(8); PG8_WAIT_L(0); PG8_BAR; PG8_MMA(1, 0, At, B0); PG8_MMA(1, 1, At, B1); PG8_BAR; PG8_SCHED;
	s_add_i32 s22, s52, s34
	v_lshl_add_u64 v[158:159], v[158:159], 0, s[28:29]
	s_mov_b32 m0, s22
	ds_read_b128 v[208:211], v149 offset:49152
	ds_read_b128 v[214:217], v149 offset:50176
	ds_read_b128 v[218:221], v149 offset:51200
	ds_read_b128 v[222:225], v149 offset:52224
	ds_read_b128 v[226:229], v149 offset:53248
	ds_read_b128 v[230:233], v149 offset:54272
	ds_read_b128 v[234:237], v149 offset:55296
	ds_read_b128 v[238:241], v149 offset:56320
	global_load_lds_dwordx4 v[158:159], off
	s_add_i32 m0, s22, 0x2000
	s_add_u32 s20, s20, 0x40080
	v_lshl_add_u64 v[158:159], v[174:175], 0, s[28:29]
	s_addc_u32 s21, s21, 0
	s_add_i32 s22, s53, s34
	global_load_lds_dwordx4 v[158:159], off
	v_lshl_add_u64 v[158:159], s[20:21], 0, v[160:161]
	s_mov_b32 m0, s22
	s_nop 0
	global_load_lds_dwordx4 v[158:159], off
	v_lshl_add_u64 v[158:159], s[20:21], 0, v[132:133]
	s_add_i32 m0, s22, 0x2000
	s_nop 0
	global_load_lds_dwordx4 v[158:159], off
	v_lshl_add_u64 v[158:159], v[178:179], 0, s[28:29]
	s_mov_b32 m0, s49
	s_nop 0
	global_load_lds_dwordx4 v[158:159], off
	v_lshl_add_u64 v[158:159], v[180:181], 0, s[28:29]
	s_mov_b32 m0, s50
	s_nop 0
	global_load_lds_dwordx4 v[158:159], off
	s_waitcnt vmcnt(8)
	s_waitcnt lgkmcnt(0)
	s_barrier
	s_setprio 1
	s_waitcnt lgkmcnt(0)
	v_mfma_f32_16x16x32_bf16 v[60:63], v[150:153], v[208:211], v[60:63]
	v_mfma_f32_16x16x32_bf16 v[52:55], v[162:165], v[208:211], v[52:55]
	v_mfma_f32_16x16x32_bf16 v[44:47], v[150:153], v[218:221], v[44:47]
	v_mfma_f32_16x16x32_bf16 v[36:39], v[162:165], v[218:221], v[36:39]
	v_mfma_f32_16x16x32_bf16 v[28:31], v[150:153], v[226:229], v[28:31]
	v_mfma_f32_16x16x32_bf16 v[20:23], v[162:165], v[226:229], v[20:23]
	v_mfma_f32_16x16x32_bf16 v[12:15], v[150:153], v[234:237], v[12:15]
	v_mfma_f32_16x16x32_bf16 v[4:7], v[162:165], v[234:237], v[4:7]
	v_mfma_f32_16x16x32_bf16 v[60:63], v[154:157], v[214:217], v[60:63]
	v_mfma_f32_16x16x32_bf16 v[52:55], v[166:169], v[214:217], v[52:55]
	v_mfma_f32_16x16x32_bf16 v[44:47], v[154:157], v[222:225], v[44:47]
	v_mfma_f32_16x16x32_bf16 v[36:39], v[166:169], v[222:225], v[36:39]
	v_mfma_f32_16x16x32_bf16 v[28:31], v[154:157], v[230:233], v[28:31]
	v_mfma_f32_16x16x32_bf16 v[20:23], v[166:169], v[230:233], v[20:23]
	v_mfma_f32_16x16x32_bf16 v[12:15], v[154:157], v[238:241], v[12:15]
	v_mfma_f32_16x16x32_bf16 v[4:7], v[166:169], v[238:241], v[4:7]
	v_mfma_f32_16x16x32_bf16 v[56:59], v[170:173], v[208:211], v[56:59]
	v_mfma_f32_16x16x32_bf16 v[48:51], v[188:191], v[208:211], v[48:51]
	v_mfma_f32_16x16x32_bf16 v[40:43], v[170:173], v[218:221], v[40:43]
	v_mfma_f32_16x16x32_bf16 v[32:35], v[188:191], v[218:221], v[32:35]
	v_mfma_f32_16x16x32_bf16 v[24:27], v[170:173], v[226:229], v[24:27]
	v_mfma_f32_16x16x32_bf16 v[16:19], v[188:191], v[226:229], v[16:19]
	v_mfma_f32_16x16x32_bf16 v[8:11], v[170:173], v[234:237], v[8:11]
	v_mfma_f32_16x16x32_bf16 v[0:3], v[188:191], v[234:237], v[0:3]
	v_mfma_f32_16x16x32_bf16 v[56:59], v[184:187], v[214:217], v[56:59]
	v_mfma_f32_16x16x32_bf16 v[48:51], v[192:195], v[214:217], v[48:51]
	v_mfma_f32_16x16x32_bf16 v[40:43], v[184:187], v[222:225], v[40:43]
	v_mfma_f32_16x16x32_bf16 v[32:35], v[192:195], v[222:225], v[32:35]
	v_mfma_f32_16x16x32_bf16 v[24:27], v[184:187], v[230:233], v[24:27]
	v_mfma_f32_16x16x32_bf16 v[16:19], v[192:195], v[230:233], v[16:19]
	v_mfma_f32_16x16x32_bf16 v[8:11], v[184:187], v[238:241], v[8:11]
	v_mfma_f32_16x16x32_bf16 v[0:3], v[192:195], v[238:241], v[0:3]
	s_setprio 0
	s_barrier
	s_add_i32 s51, s51, 2
	s_add_u32 s18, s18, 0x100
	s_addc_u32 s19, s19, 0
	s_add_u32 s42, s42, 0x100
	s_addc_u32 s43, s43, 0
	s_cmp_gt_u32 s51, 13
	s_cbranch_scc1 .Lmy_kdone_2
.LBB0_517:
	s_add_u32 s20, s18, 0xfffc0080
	s_addc_u32 s21, s19, -1
	s_add_i32 s52, 0, 0x10000
	s_cmp_eq_u32 s51, 12
	s_cselect_b32 s23, s11, s21
	s_cselect_b32 s22, s36, s20
	v_add_u32_e32 v138, s52, v141
	s_cselect_b32 s21, s9, s43
	s_cselect_b32 s20, s37, s42
	s_add_i32 s56, 0, 0x14000
	ds_read_b128 v[150:153], v138
	ds_read_b128 v[154:157], v138 offset:1024
	ds_read_b128 v[162:165], v138 offset:2048
	ds_read_b128 v[166:169], v138 offset:3072
	v_add_u32_e32 v138, s56, v141
	ds_read_b128 v[170:173], v138
	ds_read_b128 v[184:187], v138 offset:1024
	ds_read_b128 v[188:191], v138 offset:2048
	ds_read_b128 v[192:195], v138 offset:3072
	v_lshl_add_u64 v[158:159], s[18:19], 0, v[134:135]
	s_add_i32 m0, s35, 0xc000
	ds_read_b128 v[208:211], v149
	ds_read_b128 v[214:217], v149 offset:1024
	ds_read_b128 v[218:221], v149 offset:2048
	ds_read_b128 v[222:225], v149 offset:3072
	ds_read_b128 v[226:229], v149 offset:4096
	ds_read_b128 v[230:233], v149 offset:5120
	ds_read_b128 v[234:237], v149 offset:6144
	ds_read_b128 v[238:241], v149 offset:7168
	global_load_lds_dwordx4 v[158:159], off
	v_lshl_add_u64 v[158:159], s[18:19], 0, v[136:137]
	s_add_i32 m0, s35, 0xe000
	s_nop 0
	global_load_lds_dwordx4 v[158:159], off
	s_waitcnt vmcnt(8)
	s_waitcnt lgkmcnt(0)
	s_barrier
; #define PG8_STAGE(bufoff, gbase, voff) do { _Pragma("unroll") for (int _i = 0; _i < 2; ++_i) \
;         __builtin_amdgcn_global_load_lds((const unsigned*)((const char*)(gbase) + (voff)[_i]), (PG8_LAS unsigned*)(lds + (bufoff) + ldsw + _i * 8192), 16, 0, 0); } while (0)
; #define PG8_LDA(dst, b, h) do { _Pragma("unroll") for (int m = 0; m < 4; ++m) _Pragma("unroll") for (int k = 0; k < 2; ++k) dst[m][k] = *(const PG8_LAS bf16x8*)(lds + PG8_SA(b, h) + aoff + m * 2048 + k * 1024); } while (0)
; #define PG8_MMA(ai, bj, At, Bt) do { __builtin_amdgcn_s_setprio(1); _Pragma("unroll") for (int m = 0; m < 4; ++m) _Pragma("unroll") for (int n = 0; n < 2; ++n) _Pragma("unroll") for (int k = 0; k < 2; ++k) \
;         acc[ai][bj][m][n] = __builtin_amdgcn_mfma_f32_16x16x32_bf16(Bt[n][k], At[m][k], acc[ai][bj][m][n], 0, 0, 0); __builtin_amdgcn_s_setprio(0); } while (0)
; #define PG8_WAIT_V(n) asm volatile("s_waitcnt vmcnt(" #n ")" ::: "memory")
; #define PG8_WAIT_L(n) asm volatile("s_waitcnt lgkmcnt(" #n ")" ::: "memory")
; #define PG8_BAR __builtin_amdgcn_s_barrier()
; #define PG8_SCHED __builtin_amdgcn_sched_barrier(0)
; template <class Epi, class Sched, bool ALIGN_EPI = false, bool SP2 = false>
; __device__ __forceinline__ void gemm_phase(PG8_LAS unsigned char* lds, const Gemm g, const Sched& S, const Epi& E, const int tid) {
;     ...
;             PG8_WAIT_V(8); PG8_WAIT_L(0); PG8_BAR; PG8_MMA(0, 0, At, B0); PG8_MMA(0, 1, At, B1); PG8_BAR; PG8_SCHED;
;             PG8_LDA(At, 0, 1); PG8_STAGE(PG8_SB(0, 0), b2, voffB); PG8_STAGE(PG8_SB(0, 1), b2 + hstep, voffB); PG8_STAGE(PG8_SA(0, 0), a2, voffA);
;             PG8_WAIT_V(8); PG8_WAIT_L(0); PG8_BAR; PG8_MMA(1, 0, At, B0); PG8_MMA(1, 1, At, B1); PG8_BAR; PG8_SCHED;
	s_setprio 1
	s_waitcnt lgkmcnt(0)
	v_mfma_f32_16x16x32_bf16 v[124:127], v[150:153], v[208:211], v[124:127]
	v_mfma_f32_16x16x32_bf16 v[116:119], v[162:165], v[208:211], v[116:119]
	v_mfma_f32_16x16x32_bf16 v[108:111], v[150:153], v[218:221], v[108:111]
	v_mfma_f32_16x16x32_bf16 v[100:103], v[162:165], v[218:221], v[100:103]
	v_mfma_f32_16x16x32_bf16 v[92:95], v[150:153], v[226:229], v[92:95]
	v_mfma_f32_16x16x32_bf16 v[84:87], v[162:165], v[226:229], v[84:87]
	v_mfma_f32_16x16x32_bf16 v[76:79], v[150:153], v[234:237], v[76:79]
	v_mfma_f32_16x16x32_bf16 v[68:71], v[162:165], v[234:237], v[68:71]
	v_mfma_f32_16x16x32_bf16 v[124:127], v[154:157], v[214:217], v[124:127]
	v_mfma_f32_16x16x32_bf16 v[116:119], v[166:169], v[214:217], v[116:119]
	v_mfma_f32_16x16x32_bf16 v[108:111], v[154:157], v[222:225], v[108:111]
	v_mfma_f32_16x16x32_bf16 v[100:103], v[166:169], v[222:225], v[100:103]
	v_mfma_f32_16x16x32_bf16 v[92:95], v[154:157], v[230:233], v[92:95]
	v_mfma_f32_16x16x32_bf16 v[84:87], v[166:169], v[230:233], v[84:87]
	v_mfma_f32_16x16x32_bf16 v[76:79], v[154:157], v[238:241], v[76:79]
	v_mfma_f32_16x16x32_bf16 v[68:71], v[166:169], v[238:241], v[68:71]
	v_mfma_f32_16x16x32_bf16 v[120:123], v[170:173], v[208:211], v[120:123]
	v_mfma_f32_16x16x32_bf16 v[112:115], v[188:191], v[208:211], v[112:115]
	v_mfma_f32_16x16x32_bf16 v[104:107], v[170:173], v[218:221], v[104:107]
	v_mfma_f32_16x16x32_bf16 v[96:99], v[188:191], v[218:221], v[96:99]
	v_mfma_f32_16x16x32_bf16 v[88:91], v[170:173], v[226:229], v[88:91]
	v_mfma_f32_16x16x32_bf16 v[80:83], v[188:191], v[226:229], v[80:83]
	v_mfma_f32_16x16x32_bf16 v[72:75], v[170:173], v[234:237], v[72:75]
	v_mfma_f32_16x16x32_bf16 v[64:67], v[188:191], v[234:237], v[64:67]
	v_mfma_f32_16x16x32_bf16 v[120:123], v[184:187], v[214:217], v[120:123]
	v_mfma_f32_16x16x32_bf16 v[112:115], v[192:195], v[214:217], v[112:115]
	v_mfma_f32_16x16x32_bf16 v[104:107], v[184:187], v[222:225], v[104:107]
	v_mfma_f32_16x16x32_bf16 v[96:99], v[192:195], v[222:225], v[96:99]
	v_mfma_f32_16x16x32_bf16 v[88:91], v[184:187], v[230:233], v[88:91]
	v_mfma_f32_16x16x32_bf16 v[80:83], v[192:195], v[230:233], v[80:83]
	v_mfma_f32_16x16x32_bf16 v[72:75], v[184:187], v[238:241], v[72:75]
	v_mfma_f32_16x16x32_bf16 v[64:67], v[192:195], v[238:241], v[64:67]
	s_setprio 0
	s_barrier
	s_add_i32 s52, s52, s34
	v_lshl_add_u64 v[158:159], s[20:21], 0, v[160:161]
	s_mov_b32 m0, s52
	ds_read_b128 v[208:211], v149 offset:16384
	ds_read_b128 v[214:217], v149 offset:17408
	ds_read_b128 v[218:221], v149 offset:18432
	ds_read_b128 v[222:225], v149 offset:19456
	ds_read_b128 v[226:229], v149 offset:20480
	ds_read_b128 v[230:233], v149 offset:21504
	ds_read_b128 v[234:237], v149 offset:22528
	ds_read_b128 v[238:241], v149 offset:23552
	global_load_lds_dwordx4 v[158:159], off
	s_add_i32 m0, s52, 0x2000
	s_add_u32 s52, s20, 0x40000
	v_lshl_add_u64 v[174:175], s[20:21], 0, v[132:133]
	s_addc_u32 s53, s21, 0
	s_add_i32 s56, s56, s34
	global_load_lds_dwordx4 v[174:175], off
	v_lshl_add_u64 v[178:179], s[52:53], 0, v[160:161]
	s_mov_b32 m0, s56
	v_lshl_add_u64 v[180:181], s[22:23], 0, v[130:131]
	global_load_lds_dwordx4 v[178:179], off
	v_lshl_add_u64 v[178:179], s[52:53], 0, v[132:133]
	s_add_i32 m0, s56, 0x2000
	s_nop 0
	global_load_lds_dwordx4 v[178:179], off
	v_lshl_add_u64 v[178:179], s[22:23], 0, v[128:129]
	s_mov_b32 m0, s35
	s_nop 0
	global_load_lds_dwordx4 v[178:179], off
	s_mov_b32 m0, s44
	s_nop 0
	global_load_lds_dwordx4 v[180:181], off
	s_waitcnt vmcnt(8)
	s_waitcnt lgkmcnt(0)
	s_barrier
	s_setprio 1
	s_waitcnt lgkmcnt(0)
	v_mfma_f32_16x16x32_bf16 v[60:63], v[150:153], v[208:211], v[60:63]
	v_mfma_f32_16x16x32_bf16 v[52:55], v[162:165], v[208:211], v[52:55]
	v_mfma_f32_16x16x32_bf16 v[44:47], v[150:153], v[218:221], v[44:47]
	v_mfma_f32_16x16x32_bf16 v[36:39], v[162:165], v[218:221], v[36:39]
	v_mfma_f32_16x16x32_bf16 v[28:31], v[150:153], v[226:229], v[28:31]
	v_mfma_f32_16x16x32_bf16 v[20:23], v[162:165], v[226:229], v[20:23]
	v_mfma_f32_16x16x32_bf16 v[12:15], v[150:153], v[234:237], v[12:15]
	v_mfma_f32_16x16x32_bf16 v[4:7], v[162:165], v[234:237], v[4:7]
	v_mfma_f32_16x16x32_bf16 v[60:63], v[154:157], v[214:217], v[60:63]
	v_mfma_f32_16x16x32_bf16 v[52:55], v[166:169], v[214:217], v[52:55]
	v_mfma_f32_16x16x32_bf16 v[44:47], v[154:157], v[222:225], v[44:47]
	v_mfma_f32_16x16x32_bf16 v[36:39], v[166:169], v[222:225], v[36:39]
	v_mfma_f32_16x16x32_bf16 v[28:31], v[154:157], v[230:233], v[28:31]
	v_mfma_f32_16x16x32_bf16 v[20:23], v[166:169], v[230:233], v[20:23]
	v_mfma_f32_16x16x32_bf16 v[12:15], v[154:157], v[238:241], v[12:15]
	v_mfma_f32_16x16x32_bf16 v[4:7], v[166:169], v[238:241], v[4:7]
	v_mfma_f32_16x16x32_bf16 v[56:59], v[170:173], v[208:211], v[56:59]
	v_mfma_f32_16x16x32_bf16 v[48:51], v[188:191], v[208:211], v[48:51]
	v_mfma_f32_16x16x32_bf16 v[40:43], v[170:173], v[218:221], v[40:43]
	v_mfma_f32_16x16x32_bf16 v[32:35], v[188:191], v[218:221], v[32:35]
	v_mfma_f32_16x16x32_bf16 v[24:27], v[170:173], v[226:229], v[24:27]
	v_mfma_f32_16x16x32_bf16 v[16:19], v[188:191], v[226:229], v[16:19]
	v_mfma_f32_16x16x32_bf16 v[8:11], v[170:173], v[234:237], v[8:11]
	v_mfma_f32_16x16x32_bf16 v[0:3], v[188:191], v[234:237], v[0:3]
	v_mfma_f32_16x16x32_bf16 v[56:59], v[184:187], v[214:217], v[56:59]
	v_mfma_f32_16x16x32_bf16 v[48:51], v[192:195], v[214:217], v[48:51]
	v_mfma_f32_16x16x32_bf16 v[40:43], v[184:187], v[222:225], v[40:43]
	v_mfma_f32_16x16x32_bf16 v[32:35], v[192:195], v[222:225], v[32:35]
	v_mfma_f32_16x16x32_bf16 v[24:27], v[184:187], v[230:233], v[24:27]
	v_mfma_f32_16x16x32_bf16 v[16:19], v[192:195], v[230:233], v[16:19]
	v_mfma_f32_16x16x32_bf16 v[8:11], v[184:187], v[238:241], v[8:11]
	v_mfma_f32_16x16x32_bf16 v[0:3], v[192:195], v[238:241], v[0:3]
	s_setprio 0
	s_barrier
; #define PG8_STAGE(bufoff, gbase, voff) do { _Pragma("unroll") for (int _i = 0; _i < 2; ++_i) \
;         __builtin_amdgcn_global_load_lds((const unsigned*)((const char*)(gbase) + (voff)[_i]), (PG8_LAS unsigned*)(lds + (bufoff) + ldsw + _i * 8192), 16, 0, 0); } while (0)
; #define PG8_LDA(dst, b, h) do { _Pragma("unroll") for (int m = 0; m < 4; ++m) _Pragma("unroll") for (int k = 0; k < 2; ++k) dst[m][k] = *(const PG8_LAS bf16x8*)(lds + PG8_SA(b, h) + aoff + m * 2048 + k * 1024); } while (0)
; #define PG8_LDB(dst, b, h) do { _Pragma("unroll") for (int n = 0; n < 2; ++n) _Pragma("unroll") for (int k = 0; k < 2; ++k) dst[n][k] = *(const PG8_LAS bf16x8*)(lds + PG8_SB(b, h) + boff + n * 2048 + k * 1024); } while (0)
; #define PG8_MMA(ai, bj, At, Bt) do { __builtin_amdgcn_s_setprio(1); _Pragma("unroll") for (int m = 0; m < 4; ++m) _Pragma("unroll") for (int n = 0; n < 2; ++n) _Pragma("unroll") for (int k = 0; k < 2; ++k) \
;         acc[ai][bj][m][n] = __builtin_amdgcn_mfma_f32_16x16x32_bf16(Bt[n][k], At[m][k], acc[ai][bj][m][n], 0, 0, 0); __builtin_amdgcn_s_setprio(0); } while (0)
; #define PG8_WAIT_V(n) asm volatile("s_waitcnt vmcnt(" #n ")" ::: "memory")
; #define PG8_WAIT_L(n) asm volatile("s_waitcnt lgkmcnt(" #n ")" ::: "memory")
; #define PG8_BAR __builtin_amdgcn_s_barrier()
; #define PG8_SCHED __builtin_amdgcn_sched_barrier(0)
; template <class Epi, class Sched, bool ALIGN_EPI = false, bool SP2 = false>
; __device__ __forceinline__ void gemm_phase(PG8_LAS unsigned char* lds, const Gemm g, const Sched& S, const Epi& E, const int tid) {
;     ...
;             PG8_LDB(B0, 1, 0); PG8_LDB(B1, 1, 1); PG8_SCHED; PG8_LDA(At, 1, 0); PG8_STAGE(PG8_SA(0, 1), a2 + hstep, voffA);
;             PG8_WAIT_V(8); PG8_WAIT_L(0); PG8_BAR; PG8_MMA(0, 0, At, B0); PG8_MMA(0, 1, At, B1); PG8_BAR; PG8_SCHED;
	s_add_i32 s52, 0, 0x18000
	v_add_u32_e32 v138, s52, v141
	s_add_i32 s53, 0, 0x1c000
	ds_read_b128 v[150:153], v138
	ds_read_b128 v[154:157], v138 offset:1024
	ds_read_b128 v[162:165], v138 offset:2048
	ds_read_b128 v[166:169], v138 offset:3072
	v_add_u32_e32 v138, s53, v141
	ds_read_b128 v[170:173], v138
	ds_read_b128 v[184:187], v138 offset:1024
	ds_read_b128 v[188:191], v138 offset:2048
	ds_read_b128 v[192:195], v138 offset:3072
	s_add_u32 s22, s22, 0x40000
	s_addc_u32 s23, s23, 0
	s_mov_b32 m0, s45
	v_lshl_add_u64 v[196:197], s[22:23], 0, v[128:129]
	ds_read_b128 v[208:211], v149 offset:32768
	ds_read_b128 v[214:217], v149 offset:33792
	ds_read_b128 v[218:221], v149 offset:34816
	ds_read_b128 v[222:225], v149 offset:35840
	ds_read_b128 v[226:229], v149 offset:36864
	ds_read_b128 v[230:233], v149 offset:37888
	ds_read_b128 v[234:237], v149 offset:38912
	ds_read_b128 v[238:241], v149 offset:39936
	global_load_lds_dwordx4 v[196:197], off
	v_lshl_add_u64 v[196:197], s[22:23], 0, v[130:131]
	s_mov_b32 m0, s46
	s_nop 0
	global_load_lds_dwordx4 v[196:197], off
	s_waitcnt vmcnt(8)
	s_waitcnt lgkmcnt(0)
	s_barrier
	s_setprio 1
	s_waitcnt lgkmcnt(0)
	v_mfma_f32_16x16x32_bf16 v[124:127], v[150:153], v[208:211], v[124:127]
	v_mfma_f32_16x16x32_bf16 v[116:119], v[162:165], v[208:211], v[116:119]
	v_mfma_f32_16x16x32_bf16 v[108:111], v[150:153], v[218:221], v[108:111]
	v_mfma_f32_16x16x32_bf16 v[100:103], v[162:165], v[218:221], v[100:103]
	v_mfma_f32_16x16x32_bf16 v[92:95], v[150:153], v[226:229], v[92:95]
	v_mfma_f32_16x16x32_bf16 v[84:87], v[162:165], v[226:229], v[84:87]
	v_mfma_f32_16x16x32_bf16 v[76:79], v[150:153], v[234:237], v[76:79]
	v_mfma_f32_16x16x32_bf16 v[68:71], v[162:165], v[234:237], v[68:71]
	v_mfma_f32_16x16x32_bf16 v[124:127], v[154:157], v[214:217], v[124:127]
	v_mfma_f32_16x16x32_bf16 v[116:119], v[166:169], v[214:217], v[116:119]
	v_mfma_f32_16x16x32_bf16 v[108:111], v[154:157], v[222:225], v[108:111]
	v_mfma_f32_16x16x32_bf16 v[100:103], v[166:169], v[222:225], v[100:103]
	v_mfma_f32_16x16x32_bf16 v[92:95], v[154:157], v[230:233], v[92:95]
	v_mfma_f32_16x16x32_bf16 v[84:87], v[166:169], v[230:233], v[84:87]
	v_mfma_f32_16x16x32_bf16 v[76:79], v[154:157], v[238:241], v[76:79]
	v_mfma_f32_16x16x32_bf16 v[68:71], v[166:169], v[238:241], v[68:71]
	v_mfma_f32_16x16x32_bf16 v[120:123], v[170:173], v[208:211], v[120:123]
	v_mfma_f32_16x16x32_bf16 v[112:115], v[188:191], v[208:211], v[112:115]
	v_mfma_f32_16x16x32_bf16 v[104:107], v[170:173], v[218:221], v[104:107]
	v_mfma_f32_16x16x32_bf16 v[96:99], v[188:191], v[218:221], v[96:99]
	v_mfma_f32_16x16x32_bf16 v[88:91], v[170:173], v[226:229], v[88:91]
	v_mfma_f32_16x16x32_bf16 v[80:83], v[188:191], v[226:229], v[80:83]
	v_mfma_f32_16x16x32_bf16 v[72:75], v[170:173], v[234:237], v[72:75]
	v_mfma_f32_16x16x32_bf16 v[64:67], v[188:191], v[234:237], v[64:67]
	v_mfma_f32_16x16x32_bf16 v[120:123], v[184:187], v[214:217], v[120:123]
	v_mfma_f32_16x16x32_bf16 v[112:115], v[192:195], v[214:217], v[112:115]
	v_mfma_f32_16x16x32_bf16 v[104:107], v[184:187], v[222:225], v[104:107]
	v_mfma_f32_16x16x32_bf16 v[96:99], v[192:195], v[222:225], v[96:99]
	v_mfma_f32_16x16x32_bf16 v[88:91], v[184:187], v[230:233], v[88:91]
	v_mfma_f32_16x16x32_bf16 v[80:83], v[192:195], v[230:233], v[80:83]
	v_mfma_f32_16x16x32_bf16 v[72:75], v[184:187], v[238:241], v[72:75]
	v_mfma_f32_16x16x32_bf16 v[64:67], v[192:195], v[238:241], v[64:67]
	s_setprio 0
	s_barrier
; #define PG8_STAGE(bufoff, gbase, voff) do { _Pragma("unroll") for (int _i = 0; _i < 2; ++_i) \
;         __builtin_amdgcn_global_load_lds((const unsigned*)((const char*)(gbase) + (voff)[_i]), (PG8_LAS unsigned*)(lds + (bufoff) + ldsw + _i * 8192), 16, 0, 0); } while (0)
; #define PG8_LDA(dst, b, h) do { _Pragma("unroll") for (int m = 0; m < 4; ++m) _Pragma("unroll") for (int k = 0; k < 2; ++k) dst[m][k] = *(const PG8_LAS bf16x8*)(lds + PG8_SA(b, h) + aoff + m * 2048 + k * 1024); } while (0)
; #define PG8_MMA(ai, bj, At, Bt) do { __builtin_amdgcn_s_setprio(1); _Pragma("unroll") for (int m = 0; m < 4; ++m) _Pragma("unroll") for (int n = 0; n < 2; ++n) _Pragma("unroll") for (int k = 0; k < 2; ++k) \
;         acc[ai][bj][m][n] = __builtin_amdgcn_mfma_f32_16x16x32_bf16(Bt[n][k], At[m][k], acc[ai][bj][m][n], 0, 0, 0); __builtin_amdgcn_s_setprio(0); } while (0)
; #define PG8_WAIT_V(n) asm volatile("s_waitcnt vmcnt(" #n ")" ::: "memory")
; #define PG8_WAIT_L(n) asm volatile("s_waitcnt lgkmcnt(" #n ")" ::: "memory")
; #define PG8_BAR __builtin_amdgcn_s_barrier()
; #define PG8_SCHED __builtin_amdgcn_sched_barrier(0)
; template <class Epi, class Sched, bool ALIGN_EPI = false, bool SP2 = false>
; __device__ __forceinline__ void gemm_phase(PG8_LAS unsigned char* lds, const Gemm g, const Sched& S, const Epi& E, const int tid) {
;     ...
;             PG8_LDA(At, 1, 1); PG8_STAGE(PG8_SB(1, 0), b3, voffB); PG8_STAGE(PG8_SB(1, 1), b3 + hstep, voffB); PG8_STAGE(PG8_SA(1, 0), a3, voffA);
;             PG8_WAIT_V(8); PG8_WAIT_L(0); PG8_BAR; PG8_MMA(1, 0, At, B0); PG8_MMA(1, 1, At, B1); PG8_BAR; PG8_SCHED;
	s_add_i32 s22, s52, s34
	v_lshl_add_u64 v[158:159], v[158:159], 0, s[28:29]
	s_mov_b32 m0, s22
	ds_read_b128 v[208:211], v149 offset:49152
	ds_read_b128 v[214:217], v149 offset:50176
	ds_read_b128 v[218:221], v149 offset:51200
	ds_read_b128 v[222:225], v149 offset:52224
	ds_read_b128 v[226:229], v149 offset:53248
	ds_read_b128 v[230:233], v149 offset:54272
	ds_read_b128 v[234:237], v149 offset:55296
	ds_read_b128 v[238:241], v149 offset:56320
	global_load_lds_dwordx4 v[158:159], off
	s_add_i32 m0, s22, 0x2000
	s_add_u32 s20, s20, 0x40080
	v_lshl_add_u64 v[158:159], v[174:175], 0, s[28:29]
	s_addc_u32 s21, s21, 0
	s_add_i32 s22, s53, s34
	global_load_lds_dwordx4 v[158:159], off
	v_lshl_add_u64 v[158:159], s[20:21], 0, v[160:161]
	s_mov_b32 m0, s22
	s_nop 0
	global_load_lds_dwordx4 v[158:159], off
	v_lshl_add_u64 v[158:159], s[20:21], 0, v[132:133]
	s_add_i32 m0, s22, 0x2000
	s_nop 0
	global_load_lds_dwordx4 v[158:159], off
	v_lshl_add_u64 v[158:159], v[178:179], 0, s[28:29]
	s_mov_b32 m0, s49
	s_nop 0
	global_load_lds_dwordx4 v[158:159], off
	v_lshl_add_u64 v[158:159], v[180:181], 0, s[28:29]
	s_mov_b32 m0, s50
	s_nop 0
	global_load_lds_dwordx4 v[158:159], off
	s_waitcnt vmcnt(8)
	s_waitcnt lgkmcnt(0)
	s_barrier
	s_setprio 1
	s_waitcnt lgkmcnt(0)
	v_mfma_f32_16x16x32_bf16 v[60:63], v[150:153], v[208:211], v[60:63]
	v_mfma_f32_16x16x32_bf16 v[52:55], v[162:165], v[208:211], v[52:55]
	v_mfma_f32_16x16x32_bf16 v[44:47], v[150:153], v[218:221], v[44:47]
	v_mfma_f32_16x16x32_bf16 v[36:39], v[162:165], v[218:221], v[36:39]
	v_mfma_f32_16x16x32_bf16 v[28:31], v[150:153], v[226:229], v[28:31]
	v_mfma_f32_16x16x32_bf16 v[20:23], v[162:165], v[226:229], v[20:23]
	v_mfma_f32_16x16x32_bf16 v[12:15], v[150:153], v[234:237], v[12:15]
	v_mfma_f32_16x16x32_bf16 v[4:7], v[162:165], v[234:237], v[4:7]
	v_mfma_f32_16x16x32_bf16 v[60:63], v[154:157], v[214:217], v[60:63]
	v_mfma_f32_16x16x32_bf16 v[52:55], v[166:169], v[214:217], v[52:55]
	v_mfma_f32_16x16x32_bf16 v[44:47], v[154:157], v[222:225], v[44:47]
	v_mfma_f32_16x16x32_bf16 v[36:39], v[166:169], v[222:225], v[36:39]
	v_mfma_f32_16x16x32_bf16 v[28:31], v[154:157], v[230:233], v[28:31]
	v_mfma_f32_16x16x32_bf16 v[20:23], v[166:169], v[230:233], v[20:23]
	v_mfma_f32_16x16x32_bf16 v[12:15], v[154:157], v[238:241], v[12:15]
	v_mfma_f32_16x16x32_bf16 v[4:7], v[166:169], v[238:241], v[4:7]
	v_mfma_f32_16x16x32_bf16 v[56:59], v[170:173], v[208:211], v[56:59]
	v_mfma_f32_16x16x32_bf16 v[48:51], v[188:191], v[208:211], v[48:51]
	v_mfma_f32_16x16x32_bf16 v[40:43], v[170:173], v[218:221], v[40:43]
	v_mfma_f32_16x16x32_bf16 v[32:35], v[188:191], v[218:221], v[32:35]
	v_mfma_f32_16x16x32_bf16 v[24:27], v[170:173], v[226:229], v[24:27]
	v_mfma_f32_16x16x32_bf16 v[16:19], v[188:191], v[226:229], v[16:19]
	v_mfma_f32_16x16x32_bf16 v[8:11], v[170:173], v[234:237], v[8:11]
	v_mfma_f32_16x16x32_bf16 v[0:3], v[188:191], v[234:237], v[0:3]
	v_mfma_f32_16x16x32_bf16 v[56:59], v[184:187], v[214:217], v[56:59]
	v_mfma_f32_16x16x32_bf16 v[48:51], v[192:195], v[214:217], v[48:51]
	v_mfma_f32_16x16x32_bf16 v[40:43], v[184:187], v[222:225], v[40:43]
	v_mfma_f32_16x16x32_bf16 v[32:35], v[192:195], v[222:225], v[32:35]
	v_mfma_f32_16x16x32_bf16 v[24:27], v[184:187], v[230:233], v[24:27]
	v_mfma_f32_16x16x32_bf16 v[16:19], v[192:195], v[230:233], v[16:19]
	v_mfma_f32_16x16x32_bf16 v[8:11], v[184:187], v[238:241], v[8:11]
	v_mfma_f32_16x16x32_bf16 v[0:3], v[192:195], v[238:241], v[0:3]
	s_setprio 0
	s_barrier
	s_add_i32 s51, s51, 2
	s_add_u32 s18, s18, 0x100
	s_addc_u32 s19, s19, 0
	s_add_u32 s42, s42, 0x100
	s_addc_u32 s43, s43, 0
	s_cmp_gt_u32 s51, 13
	s_cbranch_scc0 .LBB0_517

; #define PG8_STAGE(bufoff, gbase, voff) do { _Pragma("unroll") for (int _i = 0; _i < 2; ++_i) \
;         __builtin_amdgcn_global_load_lds((const unsigned*)((const char*)(gbase) + (voff)[_i]), (PG8_LAS unsigned*)(lds + (bufoff) + ldsw + _i * 8192), 16, 0, 0); } while (0)
; #define PG8_LDA(dst, b, h) do { _Pragma("unroll") for (int m = 0; m < 4; ++m) _Pragma("unroll") for (int k = 0; k < 2; ++k) dst[m][k] = *(const PG8_LAS bf16x8*)(lds + PG8_SA(b, h) + aoff + m * 2048 + k * 1024); } while (0)
; #define PG8_LDB(dst, b, h) do { _Pragma("unroll") for (int n = 0; n < 2; ++n) _Pragma("unroll") for (int k = 0; k < 2; ++k) dst[n][k] = *(const PG8_LAS bf16x8*)(lds + PG8_SB(b, h) + boff + n * 2048 + k * 1024); } while (0)
; #define PG8_MMA(ai, bj, At, Bt) do { __builtin_amdgcn_s_setprio(1); _Pragma("unroll") for (int m = 0; m < 4; ++m) _Pragma("unroll") for (int n = 0; n < 2; ++n) _Pragma("unroll") for (int k = 0; k < 2; ++k) \
;         acc[ai][bj][m][n] = __builtin_amdgcn_mfma_f32_16x16x32_bf16(Bt[n][k], At[m][k], acc[ai][bj][m][n], 0, 0, 0); __builtin_amdgcn_s_setprio(0); } while (0)
; #define PG8_WAIT_V(n) asm volatile("s_waitcnt vmcnt(" #n ")" ::: "memory")
; #define PG8_BAR __builtin_amdgcn_s_barrier()
; template <class Epi, class Sched, bool ALIGN_EPI = false, bool SP2 = false>
; __device__ __forceinline__ void gemm_phase(PG8_LAS unsigned char* lds, const Gemm g, const Sched& S, const Epi& E, const int tid) {
;     ...
;         for (int t = 0; t < nt; t += 2) {
;             const bool last = (t == nt - 2);
;             const char* a1 = cA + (size_t)(t + 1) * kstep;
;             const char* a2 = last ? nA : cA + (size_t)(t + 2) * kstep; const char* b2 = last ? nB : cB + (size_t)(t + 2) * kstep;
;             const char* a3 = a2 + kstep; const char* b3 = b2 + kstep;
;             if (last && has_next) S.a_ready(nxt);
;             if constexpr (SP2) {
;             PG8_LDB(B0, 0, 0); PG8_LDB(B1, 0, 1); PG8_SCHED; PG8_LDA(At, 0, 0); PG8_STAGE(PG8_SA(1, 1), a1 + hstep, voffA);
;             PG8_WAIT_V(8); PG8_WAIT_L(0); PG8_BAR; PG8_MMA(0, 0, At, B0); PG8_MMA(0, 1, At, B1); PG8_BAR; PG8_SCHED;
;             PG8_LDA(At, 0, 1); PG8_STAGE(PG8_SB(0, 0), b2, voffB); PG8_STAGE(PG8_SB(0, 1), b2 + hstep, voffB); PG8_STAGE(PG8_SA(0, 0), a2, voffA);
;             PG8_WAIT_V(8); PG8_WAIT_L(0); PG8_BAR; PG8_MMA(1, 0, At, B0); PG8_MMA(1, 1, At, B1); PG8_BAR; PG8_SCHED;
.LBB0_620:
	s_add_u32 s44, s50, 0x80
	s_addc_u32 s45, s51, 0
	s_add_u32 s37, s48, 0x100
	s_addc_u32 s50, s49, 0
	s_mov_b32 s48, 0
	s_add_i32 s51, s48, 2
	s_add_u32 vcc_lo, s44, 0x80
	s_addc_u32 s49, s45, 0
	s_cmp_eq_u32 s82, s48
	s_cselect_b32 s49, s35, s49
	s_cselect_b32 s48, s34, vcc_lo
	v_add_u32_e32 v156, s59, v174
	s_cselect_b32 vcc_hi, s47, s50
	s_cselect_b32 vcc_lo, s46, s37
	s_add_i32 s90, 0, 0x14000
	s_waitcnt lgkmcnt(0)
	ds_read_b128 v[144:147], v156
	ds_read_b128 v[148:151], v156 offset:1024
	ds_read_b128 v[152:155], v156 offset:2048
	ds_read_b128 v[184:187], v156 offset:3072
	v_add_u32_e32 v156, s90, v174
	ds_read_b128 v[188:191], v156
	ds_read_b128 v[192:195], v156 offset:1024
	ds_read_b128 v[214:217], v156 offset:2048
	ds_read_b128 v[218:221], v156 offset:3072
	v_lshl_add_u64 v[156:157], s[44:45], 0, v[140:141]
	s_add_i32 m0, s66, 0xc000
	ds_read_b128 v[222:225], v175
	ds_read_b128 v[226:229], v175 offset:1024
	ds_read_b128 v[230:233], v175 offset:2048
	ds_read_b128 v[234:237], v175 offset:3072
	ds_read_b128 v[238:241], v175 offset:4096
	ds_read_b128 v[242:245], v175 offset:5120
	ds_read_b128 v[246:249], v175 offset:6144
	ds_read_b128 v[208:211], v175 offset:7168
	global_load_lds_dwordx4 v[156:157], off
	v_lshl_add_u64 v[156:157], s[44:45], 0, v[142:143]
	s_add_i32 m0, s66, 0xe000
	s_nop 0
	global_load_lds_dwordx4 v[156:157], off
	s_waitcnt vmcnt(8)
	s_waitcnt lgkmcnt(0)
	s_barrier
	s_setprio 1
	s_waitcnt lgkmcnt(0)
	v_mfma_f32_16x16x32_bf16 v[124:127], v[144:147], v[222:225], 0
	v_mfma_f32_16x16x32_bf16 v[120:123], v[152:155], v[222:225], 0
	v_mfma_f32_16x16x32_bf16 v[108:111], v[144:147], v[230:233], 0
	v_mfma_f32_16x16x32_bf16 v[104:107], v[152:155], v[230:233], 0
	v_mfma_f32_16x16x32_bf16 v[92:95], v[144:147], v[238:241], 0
	v_mfma_f32_16x16x32_bf16 v[88:91], v[152:155], v[238:241], 0
	v_mfma_f32_16x16x32_bf16 v[76:79], v[144:147], v[246:249], 0
	v_mfma_f32_16x16x32_bf16 v[72:75], v[152:155], v[246:249], 0
	v_mfma_f32_16x16x32_bf16 v[124:127], v[148:151], v[226:229], v[124:127]
	v_mfma_f32_16x16x32_bf16 v[120:123], v[184:187], v[226:229], v[120:123]
	v_mfma_f32_16x16x32_bf16 v[108:111], v[148:151], v[234:237], v[108:111]
	v_mfma_f32_16x16x32_bf16 v[104:107], v[184:187], v[234:237], v[104:107]
	v_mfma_f32_16x16x32_bf16 v[92:95], v[148:151], v[242:245], v[92:95]
	v_mfma_f32_16x16x32_bf16 v[88:91], v[184:187], v[242:245], v[88:91]
	v_mfma_f32_16x16x32_bf16 v[76:79], v[148:151], v[208:211], v[76:79]
	v_mfma_f32_16x16x32_bf16 v[72:75], v[184:187], v[208:211], v[72:75]
	v_mfma_f32_16x16x32_bf16 v[116:119], v[188:191], v[222:225], 0
	v_mfma_f32_16x16x32_bf16 v[112:115], v[214:217], v[222:225], 0
	v_mfma_f32_16x16x32_bf16 v[100:103], v[188:191], v[230:233], 0
	v_mfma_f32_16x16x32_bf16 v[96:99], v[214:217], v[230:233], 0
	v_mfma_f32_16x16x32_bf16 v[84:87], v[188:191], v[238:241], 0
	v_mfma_f32_16x16x32_bf16 v[80:83], v[214:217], v[238:241], 0
	v_mfma_f32_16x16x32_bf16 v[68:71], v[188:191], v[246:249], 0
	v_mfma_f32_16x16x32_bf16 v[64:67], v[214:217], v[246:249], 0
	v_mfma_f32_16x16x32_bf16 v[116:119], v[192:195], v[226:229], v[116:119]
	v_mfma_f32_16x16x32_bf16 v[112:115], v[218:221], v[226:229], v[112:115]
	v_mfma_f32_16x16x32_bf16 v[100:103], v[192:195], v[234:237], v[100:103]
	v_mfma_f32_16x16x32_bf16 v[96:99], v[218:221], v[234:237], v[96:99]
	v_mfma_f32_16x16x32_bf16 v[84:87], v[192:195], v[242:245], v[84:87]
	v_mfma_f32_16x16x32_bf16 v[80:83], v[218:221], v[242:245], v[80:83]
	v_mfma_f32_16x16x32_bf16 v[68:71], v[192:195], v[208:211], v[68:71]
	v_mfma_f32_16x16x32_bf16 v[64:67], v[218:221], v[208:211], v[64:67]
	s_setprio 0
	s_barrier
	s_add_i32 s91, s59, s65
	v_lshl_add_u64 v[156:157], vcc, 0, v[160:161]
	s_mov_b32 m0, s91
	ds_read_b128 v[208:211], v175 offset:16384
	ds_read_b128 v[222:225], v175 offset:17408
	ds_read_b128 v[226:229], v175 offset:18432
	ds_read_b128 v[230:233], v175 offset:19456
	ds_read_b128 v[234:237], v175 offset:20480
	ds_read_b128 v[238:241], v175 offset:21504
	ds_read_b128 v[242:245], v175 offset:22528
	ds_read_b128 v[246:249], v175 offset:23552
	global_load_lds_dwordx4 v[156:157], off
	s_add_i32 m0, s91, 0x2000
	v_lshl_add_u64 v[250:251], vcc, 0, v[136:137]
	s_add_u32 vcc_lo, vcc_lo, s94
	s_addc_u32 vcc_hi, vcc_hi, 0
	s_add_i32 s90, s90, s65
	global_load_lds_dwordx4 v[250:251], off
	v_lshl_add_u64 v[178:179], vcc, 0, v[160:161]
	s_mov_b32 m0, s90
	v_lshl_add_u64 v[180:181], vcc, 0, v[136:137]
	global_load_lds_dwordx4 v[178:179], off
	s_add_i32 m0, s90, 0x2000
	v_lshl_add_u64 v[204:205], s[48:49], 0, v[132:133]
	global_load_lds_dwordx4 v[180:181], off
	s_mov_b32 m0, s66
	v_lshl_add_u64 v[196:197], s[48:49], 0, v[134:135]
	global_load_lds_dwordx4 v[204:205], off
	s_mov_b32 m0, s67
	s_nop 0
	global_load_lds_dwordx4 v[196:197], off
	s_waitcnt vmcnt(8)
	s_waitcnt lgkmcnt(0)
	s_barrier
; #define PG8_STAGE(bufoff, gbase, voff) do { _Pragma("unroll") for (int _i = 0; _i < 2; ++_i) \
;         __builtin_amdgcn_global_load_lds((const unsigned*)((const char*)(gbase) + (voff)[_i]), (PG8_LAS unsigned*)(lds + (bufoff) + ldsw + _i * 8192), 16, 0, 0); } while (0)
; #define PG8_LDA(dst, b, h) do { _Pragma("unroll") for (int m = 0; m < 4; ++m) _Pragma("unroll") for (int k = 0; k < 2; ++k) dst[m][k] = *(const PG8_LAS bf16x8*)(lds + PG8_SA(b, h) + aoff + m * 2048 + k * 1024); } while (0)
; #define PG8_LDB(dst, b, h) do { _Pragma("unroll") for (int n = 0; n < 2; ++n) _Pragma("unroll") for (int k = 0; k < 2; ++k) dst[n][k] = *(const PG8_LAS bf16x8*)(lds + PG8_SB(b, h) + boff + n * 2048 + k * 1024); } while (0)
; #define PG8_MMA(ai, bj, At, Bt) do { __builtin_amdgcn_s_setprio(1); _Pragma("unroll") for (int m = 0; m < 4; ++m) _Pragma("unroll") for (int n = 0; n < 2; ++n) _Pragma("unroll") for (int k = 0; k < 2; ++k) \
;         acc[ai][bj][m][n] = __builtin_amdgcn_mfma_f32_16x16x32_bf16(Bt[n][k], At[m][k], acc[ai][bj][m][n], 0, 0, 0); __builtin_amdgcn_s_setprio(0); } while (0)
; #define PG8_WAIT_V(n) asm volatile("s_waitcnt vmcnt(" #n ")" ::: "memory")
; #define PG8_WAIT_L(n) asm volatile("s_waitcnt lgkmcnt(" #n ")" ::: "memory")
; #define PG8_BAR __builtin_amdgcn_s_barrier()
; #define PG8_SCHED __builtin_amdgcn_sched_barrier(0)
; template <class Epi, class Sched, bool ALIGN_EPI = false, bool SP2 = false>
; __device__ __forceinline__ void gemm_phase(PG8_LAS unsigned char* lds, const Gemm g, const Sched& S, const Epi& E, const int tid) {
;     ...
;             PG8_WAIT_V(8); PG8_WAIT_L(0); PG8_BAR; PG8_MMA(1, 0, At, B0); PG8_MMA(1, 1, At, B1); PG8_BAR; PG8_SCHED;
;             PG8_LDB(B0, 1, 0); PG8_LDB(B1, 1, 1); PG8_SCHED; PG8_LDA(At, 1, 0); PG8_STAGE(PG8_SA(0, 1), a2 + hstep, voffA);
;             PG8_WAIT_V(8); PG8_WAIT_L(0); PG8_BAR; PG8_MMA(0, 0, At, B0); PG8_MMA(0, 1, At, B1); PG8_BAR; PG8_SCHED;
	s_setprio 1
	s_waitcnt lgkmcnt(0)
	v_mfma_f32_16x16x32_bf16 v[60:63], v[144:147], v[208:211], 0
	v_mfma_f32_16x16x32_bf16 v[56:59], v[152:155], v[208:211], 0
	v_mfma_f32_16x16x32_bf16 v[44:47], v[144:147], v[226:229], 0
	v_mfma_f32_16x16x32_bf16 v[40:43], v[152:155], v[226:229], 0
	v_mfma_f32_16x16x32_bf16 v[28:31], v[144:147], v[234:237], 0
	v_mfma_f32_16x16x32_bf16 v[24:27], v[152:155], v[234:237], 0
	v_mfma_f32_16x16x32_bf16 v[12:15], v[144:147], v[242:245], 0
	v_mfma_f32_16x16x32_bf16 v[8:11], v[152:155], v[242:245], 0
	v_mfma_f32_16x16x32_bf16 v[60:63], v[148:151], v[222:225], v[60:63]
	v_mfma_f32_16x16x32_bf16 v[56:59], v[184:187], v[222:225], v[56:59]
	v_mfma_f32_16x16x32_bf16 v[44:47], v[148:151], v[230:233], v[44:47]
	v_mfma_f32_16x16x32_bf16 v[40:43], v[184:187], v[230:233], v[40:43]
	v_mfma_f32_16x16x32_bf16 v[28:31], v[148:151], v[238:241], v[28:31]
	v_mfma_f32_16x16x32_bf16 v[24:27], v[184:187], v[238:241], v[24:27]
	v_mfma_f32_16x16x32_bf16 v[12:15], v[148:151], v[246:249], v[12:15]
	v_mfma_f32_16x16x32_bf16 v[8:11], v[184:187], v[246:249], v[8:11]
	v_mfma_f32_16x16x32_bf16 v[52:55], v[188:191], v[208:211], 0
	v_mfma_f32_16x16x32_bf16 v[48:51], v[214:217], v[208:211], 0
	v_mfma_f32_16x16x32_bf16 v[36:39], v[188:191], v[226:229], 0
	v_mfma_f32_16x16x32_bf16 v[32:35], v[214:217], v[226:229], 0
	v_mfma_f32_16x16x32_bf16 v[20:23], v[188:191], v[234:237], 0
	v_mfma_f32_16x16x32_bf16 v[16:19], v[214:217], v[234:237], 0
	v_mfma_f32_16x16x32_bf16 v[4:7], v[188:191], v[242:245], 0
	v_mfma_f32_16x16x32_bf16 v[0:3], v[214:217], v[242:245], 0
	v_mfma_f32_16x16x32_bf16 v[52:55], v[192:195], v[222:225], v[52:55]
	v_mfma_f32_16x16x32_bf16 v[48:51], v[218:221], v[222:225], v[48:51]
	v_mfma_f32_16x16x32_bf16 v[36:39], v[192:195], v[230:233], v[36:39]
	v_mfma_f32_16x16x32_bf16 v[32:35], v[218:221], v[230:233], v[32:35]
	v_mfma_f32_16x16x32_bf16 v[20:23], v[192:195], v[238:241], v[20:23]
	v_mfma_f32_16x16x32_bf16 v[16:19], v[218:221], v[238:241], v[16:19]
	v_mfma_f32_16x16x32_bf16 v[4:7], v[192:195], v[246:249], v[4:7]
	v_mfma_f32_16x16x32_bf16 v[0:3], v[218:221], v[246:249], v[0:3]
	s_setprio 0
	s_barrier
	s_add_i32 s90, 0, 0x18000
	v_add_u32_e32 v183, s90, v174
	s_add_i32 s91, 0, 0x1c000
	ds_read_b128 v[144:147], v183
	ds_read_b128 v[148:151], v183 offset:1024
	ds_read_b128 v[152:155], v183 offset:2048
	ds_read_b128 v[184:187], v183 offset:3072
	v_add_u32_e32 v183, s91, v174
	ds_read_b128 v[188:191], v183
	ds_read_b128 v[192:195], v183 offset:1024
	ds_read_b128 v[208:211], v183 offset:2048
	ds_read_b128 v[214:217], v183 offset:3072
	s_add_u32 s48, s48, s94
	s_addc_u32 s49, s49, 0
	s_mov_b32 m0, s68
	v_lshl_add_u64 v[198:199], s[48:49], 0, v[132:133]
	ds_read_b128 v[218:221], v175 offset:32768
	ds_read_b128 v[222:225], v175 offset:33792
	ds_read_b128 v[226:229], v175 offset:34816
	ds_read_b128 v[230:233], v175 offset:35840
	ds_read_b128 v[234:237], v175 offset:36864
	ds_read_b128 v[238:241], v175 offset:37888
	ds_read_b128 v[242:245], v175 offset:38912
	ds_read_b128 v[246:249], v175 offset:39936
	global_load_lds_dwordx4 v[198:199], off
	v_lshl_add_u64 v[198:199], s[48:49], 0, v[134:135]
	s_mov_b32 m0, s69
	s_nop 0
	global_load_lds_dwordx4 v[198:199], off
	s_waitcnt vmcnt(8)
	s_waitcnt lgkmcnt(0)
	s_barrier
	s_setprio 1
	s_waitcnt lgkmcnt(0)
	v_mfma_f32_16x16x32_bf16 v[124:127], v[144:147], v[218:221], v[124:127]
	v_mfma_f32_16x16x32_bf16 v[120:123], v[152:155], v[218:221], v[120:123]
	v_mfma_f32_16x16x32_bf16 v[108:111], v[144:147], v[226:229], v[108:111]
	v_mfma_f32_16x16x32_bf16 v[104:107], v[152:155], v[226:229], v[104:107]
	v_mfma_f32_16x16x32_bf16 v[92:95], v[144:147], v[234:237], v[92:95]
	v_mfma_f32_16x16x32_bf16 v[88:91], v[152:155], v[234:237], v[88:91]
	v_mfma_f32_16x16x32_bf16 v[76:79], v[144:147], v[242:245], v[76:79]
	v_mfma_f32_16x16x32_bf16 v[72:75], v[152:155], v[242:245], v[72:75]
	v_mfma_f32_16x16x32_bf16 v[124:127], v[148:151], v[222:225], v[124:127]
	v_mfma_f32_16x16x32_bf16 v[120:123], v[184:187], v[222:225], v[120:123]
	v_mfma_f32_16x16x32_bf16 v[108:111], v[148:151], v[230:233], v[108:111]
	v_mfma_f32_16x16x32_bf16 v[104:107], v[184:187], v[230:233], v[104:107]
	v_mfma_f32_16x16x32_bf16 v[92:95], v[148:151], v[238:241], v[92:95]
	v_mfma_f32_16x16x32_bf16 v[88:91], v[184:187], v[238:241], v[88:91]
	v_mfma_f32_16x16x32_bf16 v[76:79], v[148:151], v[246:249], v[76:79]
	v_mfma_f32_16x16x32_bf16 v[72:75], v[184:187], v[246:249], v[72:75]
	v_mfma_f32_16x16x32_bf16 v[116:119], v[188:191], v[218:221], v[116:119]
	v_mfma_f32_16x16x32_bf16 v[112:115], v[208:211], v[218:221], v[112:115]
	v_mfma_f32_16x16x32_bf16 v[100:103], v[188:191], v[226:229], v[100:103]
	v_mfma_f32_16x16x32_bf16 v[96:99], v[208:211], v[226:229], v[96:99]
	v_mfma_f32_16x16x32_bf16 v[84:87], v[188:191], v[234:237], v[84:87]
	v_mfma_f32_16x16x32_bf16 v[80:83], v[208:211], v[234:237], v[80:83]
	v_mfma_f32_16x16x32_bf16 v[68:71], v[188:191], v[242:245], v[68:71]
	v_mfma_f32_16x16x32_bf16 v[64:67], v[208:211], v[242:245], v[64:67]
	v_mfma_f32_16x16x32_bf16 v[116:119], v[192:195], v[222:225], v[116:119]
	v_mfma_f32_16x16x32_bf16 v[112:115], v[214:217], v[222:225], v[112:115]
	v_mfma_f32_16x16x32_bf16 v[100:103], v[192:195], v[230:233], v[100:103]
	v_mfma_f32_16x16x32_bf16 v[96:99], v[214:217], v[230:233], v[96:99]
	v_mfma_f32_16x16x32_bf16 v[84:87], v[192:195], v[238:241], v[84:87]
	v_mfma_f32_16x16x32_bf16 v[80:83], v[214:217], v[238:241], v[80:83]
	v_mfma_f32_16x16x32_bf16 v[68:71], v[192:195], v[246:249], v[68:71]
	v_mfma_f32_16x16x32_bf16 v[64:67], v[214:217], v[246:249], v[64:67]
	s_setprio 0
	s_barrier
; #define PG8_STAGE(bufoff, gbase, voff) do { _Pragma("unroll") for (int _i = 0; _i < 2; ++_i) \
;         __builtin_amdgcn_global_load_lds((const unsigned*)((const char*)(gbase) + (voff)[_i]), (PG8_LAS unsigned*)(lds + (bufoff) + ldsw + _i * 8192), 16, 0, 0); } while (0)
; #define PG8_LDA(dst, b, h) do { _Pragma("unroll") for (int m = 0; m < 4; ++m) _Pragma("unroll") for (int k = 0; k < 2; ++k) dst[m][k] = *(const PG8_LAS bf16x8*)(lds + PG8_SA(b, h) + aoff + m * 2048 + k * 1024); } while (0)
; #define PG8_LDB(dst, b, h) do { _Pragma("unroll") for (int n = 0; n < 2; ++n) _Pragma("unroll") for (int k = 0; k < 2; ++k) dst[n][k] = *(const PG8_LAS bf16x8*)(lds + PG8_SB(b, h) + boff + n * 2048 + k * 1024); } while (0)
; #define PG8_MMA(ai, bj, At, Bt) do { __builtin_amdgcn_s_setprio(1); _Pragma("unroll") for (int m = 0; m < 4; ++m) _Pragma("unroll") for (int n = 0; n < 2; ++n) _Pragma("unroll") for (int k = 0; k < 2; ++k) \
;         acc[ai][bj][m][n] = __builtin_amdgcn_mfma_f32_16x16x32_bf16(Bt[n][k], At[m][k], acc[ai][bj][m][n], 0, 0, 0); __builtin_amdgcn_s_setprio(0); } while (0)
; #define PG8_WAIT_V(n) asm volatile("s_waitcnt vmcnt(" #n ")" ::: "memory")
; #define PG8_WAIT_L(n) asm volatile("s_waitcnt lgkmcnt(" #n ")" ::: "memory")
; #define PG8_BAR __builtin_amdgcn_s_barrier()
; template <class Epi, class Sched, bool ALIGN_EPI = false, bool SP2 = false>
; __device__ __forceinline__ void gemm_phase(PG8_LAS unsigned char* lds, const Gemm g, const Sched& S, const Epi& E, const int tid) {
;     ...
;         for (int t = 0; t < nt; t += 2) {
;             const bool last = (t == nt - 2);
;             const char* a1 = cA + (size_t)(t + 1) * kstep;
;             const char* a2 = last ? nA : cA + (size_t)(t + 2) * kstep; const char* b2 = last ? nB : cB + (size_t)(t + 2) * kstep;
;             const char* a3 = a2 + kstep; const char* b3 = b2 + kstep;
;             if (last && has_next) S.a_ready(nxt);
;             if constexpr (SP2) {
;             PG8_LDB(B0, 0, 0); PG8_LDB(B1, 0, 1); PG8_SCHED; PG8_LDA(At, 0, 0); PG8_STAGE(PG8_SA(1, 1), a1 + hstep, voffA);
;     ...
;             PG8_LDA(At, 1, 1); PG8_STAGE(PG8_SB(1, 0), b3, voffB); PG8_STAGE(PG8_SB(1, 1), b3 + hstep, voffB); PG8_STAGE(PG8_SA(1, 0), a3, voffA);
;             PG8_WAIT_V(8); PG8_WAIT_L(0); PG8_BAR; PG8_MMA(1, 0, At, B0); PG8_MMA(1, 1, At, B1); PG8_BAR; PG8_SCHED;
	s_add_i32 s48, s90, s65
	v_lshl_add_u64 v[156:157], v[156:157], 0, s[28:29]
	s_mov_b32 m0, s48
	ds_read_b128 v[218:221], v175 offset:49152
	ds_read_b128 v[222:225], v175 offset:50176
	ds_read_b128 v[226:229], v175 offset:51200
	ds_read_b128 v[230:233], v175 offset:52224
	ds_read_b128 v[234:237], v175 offset:53248
	ds_read_b128 v[238:241], v175 offset:54272
	ds_read_b128 v[242:245], v175 offset:55296
	ds_read_b128 v[246:249], v175 offset:56320
	global_load_lds_dwordx4 v[156:157], off
	v_lshl_add_u64 v[156:157], v[250:251], 0, s[28:29]
	s_add_i32 m0, s48, 0x2000
	s_add_i32 s48, s91, s65
	global_load_lds_dwordx4 v[156:157], off
	v_lshl_add_u64 v[156:157], v[178:179], 0, s[28:29]
	s_mov_b32 m0, s48
	s_nop 0
	global_load_lds_dwordx4 v[156:157], off
	v_lshl_add_u64 v[156:157], v[180:181], 0, s[28:29]
	s_add_i32 m0, s48, 0x2000
	s_nop 0
	global_load_lds_dwordx4 v[156:157], off
	v_lshl_add_u64 v[156:157], v[204:205], 0, s[28:29]
	s_mov_b32 m0, s70
	s_nop 0
	global_load_lds_dwordx4 v[156:157], off
	v_lshl_add_u64 v[156:157], v[196:197], 0, s[28:29]
	s_mov_b32 m0, s71
	s_nop 0
	global_load_lds_dwordx4 v[156:157], off
	s_waitcnt vmcnt(8)
	s_waitcnt lgkmcnt(0)
	s_barrier
	s_setprio 1
	s_waitcnt lgkmcnt(0)
	v_mfma_f32_16x16x32_bf16 v[60:63], v[144:147], v[218:221], v[60:63]
	v_mfma_f32_16x16x32_bf16 v[56:59], v[152:155], v[218:221], v[56:59]
	v_mfma_f32_16x16x32_bf16 v[44:47], v[144:147], v[226:229], v[44:47]
	v_mfma_f32_16x16x32_bf16 v[40:43], v[152:155], v[226:229], v[40:43]
	v_mfma_f32_16x16x32_bf16 v[28:31], v[144:147], v[234:237], v[28:31]
	v_mfma_f32_16x16x32_bf16 v[24:27], v[152:155], v[234:237], v[24:27]
	v_mfma_f32_16x16x32_bf16 v[12:15], v[144:147], v[242:245], v[12:15]
	v_mfma_f32_16x16x32_bf16 v[8:11], v[152:155], v[242:245], v[8:11]
	v_mfma_f32_16x16x32_bf16 v[60:63], v[148:151], v[222:225], v[60:63]
	v_mfma_f32_16x16x32_bf16 v[56:59], v[184:187], v[222:225], v[56:59]
	v_mfma_f32_16x16x32_bf16 v[44:47], v[148:151], v[230:233], v[44:47]
	v_mfma_f32_16x16x32_bf16 v[40:43], v[184:187], v[230:233], v[40:43]
	v_mfma_f32_16x16x32_bf16 v[28:31], v[148:151], v[238:241], v[28:31]
	v_mfma_f32_16x16x32_bf16 v[24:27], v[184:187], v[238:241], v[24:27]
	v_mfma_f32_16x16x32_bf16 v[12:15], v[148:151], v[246:249], v[12:15]
	v_mfma_f32_16x16x32_bf16 v[8:11], v[184:187], v[246:249], v[8:11]
	v_mfma_f32_16x16x32_bf16 v[52:55], v[188:191], v[218:221], v[52:55]
	v_mfma_f32_16x16x32_bf16 v[48:51], v[208:211], v[218:221], v[48:51]
	v_mfma_f32_16x16x32_bf16 v[36:39], v[188:191], v[226:229], v[36:39]
	v_mfma_f32_16x16x32_bf16 v[32:35], v[208:211], v[226:229], v[32:35]
	v_mfma_f32_16x16x32_bf16 v[20:23], v[188:191], v[234:237], v[20:23]
	v_mfma_f32_16x16x32_bf16 v[16:19], v[208:211], v[234:237], v[16:19]
	v_mfma_f32_16x16x32_bf16 v[4:7], v[188:191], v[242:245], v[4:7]
	v_mfma_f32_16x16x32_bf16 v[0:3], v[208:211], v[242:245], v[0:3]
	v_mfma_f32_16x16x32_bf16 v[52:55], v[192:195], v[222:225], v[52:55]
	v_mfma_f32_16x16x32_bf16 v[48:51], v[214:217], v[222:225], v[48:51]
	v_mfma_f32_16x16x32_bf16 v[36:39], v[192:195], v[230:233], v[36:39]
	v_mfma_f32_16x16x32_bf16 v[32:35], v[214:217], v[230:233], v[32:35]
	v_mfma_f32_16x16x32_bf16 v[20:23], v[192:195], v[238:241], v[20:23]
	v_mfma_f32_16x16x32_bf16 v[16:19], v[214:217], v[238:241], v[16:19]
	v_mfma_f32_16x16x32_bf16 v[4:7], v[192:195], v[246:249], v[4:7]
	v_mfma_f32_16x16x32_bf16 v[0:3], v[214:217], v[246:249], v[0:3]
	s_setprio 0
	s_barrier
	s_add_u32 s44, s44, 0x100
	s_addc_u32 s45, s45, 0
	s_add_u32 s37, s37, 0x100
	s_addc_u32 s50, s50, 0
	s_cmp_ge_u32 s51, s80
	s_mov_b32 s48, s51
	s_cbranch_scc1 .Lmy_kdone_3
.LBB0_621:
	s_add_i32 s51, s48, 2
	s_add_u32 vcc_lo, s44, 0x80
	s_addc_u32 s49, s45, 0
	s_cmp_eq_u32 s82, s48
	s_cselect_b32 s49, s35, s49
	s_cselect_b32 s48, s34, vcc_lo
	v_add_u32_e32 v156, s59, v174
	s_cselect_b32 vcc_hi, s47, s50
	s_cselect_b32 vcc_lo, s46, s37
	s_add_i32 s90, 0, 0x14000
	s_waitcnt lgkmcnt(0)
	ds_read_b128 v[144:147], v156
	ds_read_b128 v[148:151], v156 offset:1024
	ds_read_b128 v[152:155], v156 offset:2048
	ds_read_b128 v[184:187], v156 offset:3072
	v_add_u32_e32 v156, s90, v174
	ds_read_b128 v[188:191], v156
	ds_read_b128 v[192:195], v156 offset:1024
	ds_read_b128 v[214:217], v156 offset:2048
	ds_read_b128 v[218:221], v156 offset:3072
	v_lshl_add_u64 v[156:157], s[44:45], 0, v[140:141]
	s_add_i32 m0, s66, 0xc000
	ds_read_b128 v[222:225], v175
	ds_read_b128 v[226:229], v175 offset:1024
	ds_read_b128 v[230:233], v175 offset:2048
	ds_read_b128 v[234:237], v175 offset:3072
	ds_read_b128 v[238:241], v175 offset:4096
	ds_read_b128 v[242:245], v175 offset:5120
	ds_read_b128 v[246:249], v175 offset:6144
	ds_read_b128 v[208:211], v175 offset:7168
	global_load_lds_dwordx4 v[156:157], off
	v_lshl_add_u64 v[156:157], s[44:45], 0, v[142:143]
	s_add_i32 m0, s66, 0xe000
	s_nop 0
	global_load_lds_dwordx4 v[156:157], off
	s_waitcnt vmcnt(8)
	s_waitcnt lgkmcnt(0)
	s_barrier
; #define PG8_STAGE(bufoff, gbase, voff) do { _Pragma("unroll") for (int _i = 0; _i < 2; ++_i) \
;         __builtin_amdgcn_global_load_lds((const unsigned*)((const char*)(gbase) + (voff)[_i]), (PG8_LAS unsigned*)(lds + (bufoff) + ldsw + _i * 8192), 16, 0, 0); } while (0)
; #define PG8_LDA(dst, b, h) do { _Pragma("unroll") for (int m = 0; m < 4; ++m) _Pragma("unroll") for (int k = 0; k < 2; ++k) dst[m][k] = *(const PG8_LAS bf16x8*)(lds + PG8_SA(b, h) + aoff + m * 2048 + k * 1024); } while (0)
; #define PG8_MMA(ai, bj, At, Bt) do { __builtin_amdgcn_s_setprio(1); _Pragma("unroll") for (int m = 0; m < 4; ++m) _Pragma("unroll") for (int n = 0; n < 2; ++n) _Pragma("unroll") for (int k = 0; k < 2; ++k) \
;         acc[ai][bj][m][n] = __builtin_amdgcn_mfma_f32_16x16x32_bf16(Bt[n][k], At[m][k], acc[ai][bj][m][n], 0, 0, 0); __builtin_amdgcn_s_setprio(0); } while (0)
; #define PG8_WAIT_V(n) asm volatile("s_waitcnt vmcnt(" #n ")" ::: "memory")
; #define PG8_WAIT_L(n) asm volatile("s_waitcnt lgkmcnt(" #n ")" ::: "memory")
; #define PG8_BAR __builtin_amdgcn_s_barrier()
; #define PG8_SCHED __builtin_amdgcn_sched_barrier(0)
; template <class Epi, class Sched, bool ALIGN_EPI = false, bool SP2 = false>
; __device__ __forceinline__ void gemm_phase(PG8_LAS unsigned char* lds, const Gemm g, const Sched& S, const Epi& E, const int tid) {
;     ...
;             PG8_WAIT_V(8); PG8_WAIT_L(0); PG8_BAR; PG8_MMA(0, 0, At, B0); PG8_MMA(0, 1, At, B1); PG8_BAR; PG8_SCHED;
;             PG8_LDA(At, 0, 1); PG8_STAGE(PG8_SB(0, 0), b2, voffB); PG8_STAGE(PG8_SB(0, 1), b2 + hstep, voffB); PG8_STAGE(PG8_SA(0, 0), a2, voffA);
;             PG8_WAIT_V(8); PG8_WAIT_L(0); PG8_BAR; PG8_MMA(1, 0, At, B0); PG8_MMA(1, 1, At, B1); PG8_BAR; PG8_SCHED;
	s_setprio 1
	s_waitcnt lgkmcnt(0)
	v_mfma_f32_16x16x32_bf16 v[124:127], v[144:147], v[222:225], v[124:127]
	v_mfma_f32_16x16x32_bf16 v[120:123], v[152:155], v[222:225], v[120:123]
	v_mfma_f32_16x16x32_bf16 v[108:111], v[144:147], v[230:233], v[108:111]
	v_mfma_f32_16x16x32_bf16 v[104:107], v[152:155], v[230:233], v[104:107]
	v_mfma_f32_16x16x32_bf16 v[92:95], v[144:147], v[238:241], v[92:95]
	v_mfma_f32_16x16x32_bf16 v[88:91], v[152:155], v[238:241], v[88:91]
	v_mfma_f32_16x16x32_bf16 v[76:79], v[144:147], v[246:249], v[76:79]
	v_mfma_f32_16x16x32_bf16 v[72:75], v[152:155], v[246:249], v[72:75]
	v_mfma_f32_16x16x32_bf16 v[124:127], v[148:151], v[226:229], v[124:127]
	v_mfma_f32_16x16x32_bf16 v[120:123], v[184:187], v[226:229], v[120:123]
	v_mfma_f32_16x16x32_bf16 v[108:111], v[148:151], v[234:237], v[108:111]
	v_mfma_f32_16x16x32_bf16 v[104:107], v[184:187], v[234:237], v[104:107]
	v_mfma_f32_16x16x32_bf16 v[92:95], v[148:151], v[242:245], v[92:95]
	v_mfma_f32_16x16x32_bf16 v[88:91], v[184:187], v[242:245], v[88:91]
	v_mfma_f32_16x16x32_bf16 v[76:79], v[148:151], v[208:211], v[76:79]
	v_mfma_f32_16x16x32_bf16 v[72:75], v[184:187], v[208:211], v[72:75]
	v_mfma_f32_16x16x32_bf16 v[116:119], v[188:191], v[222:225], v[116:119]
	v_mfma_f32_16x16x32_bf16 v[112:115], v[214:217], v[222:225], v[112:115]
	v_mfma_f32_16x16x32_bf16 v[100:103], v[188:191], v[230:233], v[100:103]
	v_mfma_f32_16x16x32_bf16 v[96:99], v[214:217], v[230:233], v[96:99]
	v_mfma_f32_16x16x32_bf16 v[84:87], v[188:191], v[238:241], v[84:87]
	v_mfma_f32_16x16x32_bf16 v[80:83], v[214:217], v[238:241], v[80:83]
	v_mfma_f32_16x16x32_bf16 v[68:71], v[188:191], v[246:249], v[68:71]
	v_mfma_f32_16x16x32_bf16 v[64:67], v[214:217], v[246:249], v[64:67]
	v_mfma_f32_16x16x32_bf16 v[116:119], v[192:195], v[226:229], v[116:119]
	v_mfma_f32_16x16x32_bf16 v[112:115], v[218:221], v[226:229], v[112:115]
	v_mfma_f32_16x16x32_bf16 v[100:103], v[192:195], v[234:237], v[100:103]
	v_mfma_f32_16x16x32_bf16 v[96:99], v[218:221], v[234:237], v[96:99]
	v_mfma_f32_16x16x32_bf16 v[84:87], v[192:195], v[242:245], v[84:87]
	v_mfma_f32_16x16x32_bf16 v[80:83], v[218:221], v[242:245], v[80:83]
	v_mfma_f32_16x16x32_bf16 v[68:71], v[192:195], v[208:211], v[68:71]
	v_mfma_f32_16x16x32_bf16 v[64:67], v[218:221], v[208:211], v[64:67]
	s_setprio 0
	s_barrier
	s_add_i32 s91, s59, s65
	v_lshl_add_u64 v[156:157], vcc, 0, v[160:161]
	s_mov_b32 m0, s91
	ds_read_b128 v[208:211], v175 offset:16384
	ds_read_b128 v[222:225], v175 offset:17408
	ds_read_b128 v[226:229], v175 offset:18432
	ds_read_b128 v[230:233], v175 offset:19456
	ds_read_b128 v[234:237], v175 offset:20480
	ds_read_b128 v[238:241], v175 offset:21504
	ds_read_b128 v[242:245], v175 offset:22528
	ds_read_b128 v[246:249], v175 offset:23552
	global_load_lds_dwordx4 v[156:157], off
	s_add_i32 m0, s91, 0x2000
	v_lshl_add_u64 v[250:251], vcc, 0, v[136:137]
	s_add_u32 vcc_lo, vcc_lo, s94
	s_addc_u32 vcc_hi, vcc_hi, 0
	s_add_i32 s90, s90, s65
	global_load_lds_dwordx4 v[250:251], off
	v_lshl_add_u64 v[178:179], vcc, 0, v[160:161]
	s_mov_b32 m0, s90
	v_lshl_add_u64 v[180:181], vcc, 0, v[136:137]
	global_load_lds_dwordx4 v[178:179], off
	s_add_i32 m0, s90, 0x2000
	v_lshl_add_u64 v[204:205], s[48:49], 0, v[132:133]
	global_load_lds_dwordx4 v[180:181], off
	s_mov_b32 m0, s66
	v_lshl_add_u64 v[196:197], s[48:49], 0, v[134:135]
	global_load_lds_dwordx4 v[204:205], off
	s_mov_b32 m0, s67
	s_nop 0
	global_load_lds_dwordx4 v[196:197], off
	s_waitcnt vmcnt(8)
	s_waitcnt lgkmcnt(0)
	s_barrier
	s_setprio 1
	s_waitcnt lgkmcnt(0)
	v_mfma_f32_16x16x32_bf16 v[60:63], v[144:147], v[208:211], v[60:63]
	v_mfma_f32_16x16x32_bf16 v[56:59], v[152:155], v[208:211], v[56:59]
	v_mfma_f32_16x16x32_bf16 v[44:47], v[144:147], v[226:229], v[44:47]
	v_mfma_f32_16x16x32_bf16 v[40:43], v[152:155], v[226:229], v[40:43]
	v_mfma_f32_16x16x32_bf16 v[28:31], v[144:147], v[234:237], v[28:31]
	v_mfma_f32_16x16x32_bf16 v[24:27], v[152:155], v[234:237], v[24:27]
	v_mfma_f32_16x16x32_bf16 v[12:15], v[144:147], v[242:245], v[12:15]
	v_mfma_f32_16x16x32_bf16 v[8:11], v[152:155], v[242:245], v[8:11]
	v_mfma_f32_16x16x32_bf16 v[60:63], v[148:151], v[222:225], v[60:63]
	v_mfma_f32_16x16x32_bf16 v[56:59], v[184:187], v[222:225], v[56:59]
	v_mfma_f32_16x16x32_bf16 v[44:47], v[148:151], v[230:233], v[44:47]
	v_mfma_f32_16x16x32_bf16 v[40:43], v[184:187], v[230:233], v[40:43]
	v_mfma_f32_16x16x32_bf16 v[28:31], v[148:151], v[238:241], v[28:31]
	v_mfma_f32_16x16x32_bf16 v[24:27], v[184:187], v[238:241], v[24:27]
	v_mfma_f32_16x16x32_bf16 v[12:15], v[148:151], v[246:249], v[12:15]
	v_mfma_f32_16x16x32_bf16 v[8:11], v[184:187], v[246:249], v[8:11]
	v_mfma_f32_16x16x32_bf16 v[52:55], v[188:191], v[208:211], v[52:55]
	v_mfma_f32_16x16x32_bf16 v[48:51], v[214:217], v[208:211], v[48:51]
	v_mfma_f32_16x16x32_bf16 v[36:39], v[188:191], v[226:229], v[36:39]
	v_mfma_f32_16x16x32_bf16 v[32:35], v[214:217], v[226:229], v[32:35]
	v_mfma_f32_16x16x32_bf16 v[20:23], v[188:191], v[234:237], v[20:23]
	v_mfma_f32_16x16x32_bf16 v[16:19], v[214:217], v[234:237], v[16:19]
	v_mfma_f32_16x16x32_bf16 v[4:7], v[188:191], v[242:245], v[4:7]
	v_mfma_f32_16x16x32_bf16 v[0:3], v[214:217], v[242:245], v[0:3]
	v_mfma_f32_16x16x32_bf16 v[52:55], v[192:195], v[222:225], v[52:55]
	v_mfma_f32_16x16x32_bf16 v[48:51], v[218:221], v[222:225], v[48:51]
	v_mfma_f32_16x16x32_bf16 v[36:39], v[192:195], v[230:233], v[36:39]
	v_mfma_f32_16x16x32_bf16 v[32:35], v[218:221], v[230:233], v[32:35]
	v_mfma_f32_16x16x32_bf16 v[20:23], v[192:195], v[238:241], v[20:23]
	v_mfma_f32_16x16x32_bf16 v[16:19], v[218:221], v[238:241], v[16:19]
	v_mfma_f32_16x16x32_bf16 v[4:7], v[192:195], v[246:249], v[4:7]
	v_mfma_f32_16x16x32_bf16 v[0:3], v[218:221], v[246:249], v[0:3]
	s_setprio 0
	s_barrier
; #define PG8_STAGE(bufoff, gbase, voff) do { _Pragma("unroll") for (int _i = 0; _i < 2; ++_i) \
;         __builtin_amdgcn_global_load_lds((const unsigned*)((const char*)(gbase) + (voff)[_i]), (PG8_LAS unsigned*)(lds + (bufoff) + ldsw + _i * 8192), 16, 0, 0); } while (0)
; #define PG8_LDA(dst, b, h) do { _Pragma("unroll") for (int m = 0; m < 4; ++m) _Pragma("unroll") for (int k = 0; k < 2; ++k) dst[m][k] = *(const PG8_LAS bf16x8*)(lds + PG8_SA(b, h) + aoff + m * 2048 + k * 1024); } while (0)
; #define PG8_LDB(dst, b, h) do { _Pragma("unroll") for (int n = 0; n < 2; ++n) _Pragma("unroll") for (int k = 0; k < 2; ++k) dst[n][k] = *(const PG8_LAS bf16x8*)(lds + PG8_SB(b, h) + boff + n * 2048 + k * 1024); } while (0)
; #define PG8_MMA(ai, bj, At, Bt) do { __builtin_amdgcn_s_setprio(1); _Pragma("unroll") for (int m = 0; m < 4; ++m) _Pragma("unroll") for (int n = 0; n < 2; ++n) _Pragma("unroll") for (int k = 0; k < 2; ++k) \
;         acc[ai][bj][m][n] = __builtin_amdgcn_mfma_f32_16x16x32_bf16(Bt[n][k], At[m][k], acc[ai][bj][m][n], 0, 0, 0); __builtin_amdgcn_s_setprio(0); } while (0)
; #define PG8_WAIT_V(n) asm volatile("s_waitcnt vmcnt(" #n ")" ::: "memory")
; #define PG8_WAIT_L(n) asm volatile("s_waitcnt lgkmcnt(" #n ")" ::: "memory")
; #define PG8_BAR __builtin_amdgcn_s_barrier()
; #define PG8_SCHED __builtin_amdgcn_sched_barrier(0)
; template <class Epi, class Sched, bool ALIGN_EPI = false, bool SP2 = false>
; __device__ __forceinline__ void gemm_phase(PG8_LAS unsigned char* lds, const Gemm g, const Sched& S, const Epi& E, const int tid) {
;     ...
;             PG8_LDB(B0, 1, 0); PG8_LDB(B1, 1, 1); PG8_SCHED; PG8_LDA(At, 1, 0); PG8_STAGE(PG8_SA(0, 1), a2 + hstep, voffA);
;             PG8_WAIT_V(8); PG8_WAIT_L(0); PG8_BAR; PG8_MMA(0, 0, At, B0); PG8_MMA(0, 1, At, B1); PG8_BAR; PG8_SCHED;
;             PG8_LDA(At, 1, 1); PG8_STAGE(PG8_SB(1, 0), b3, voffB); PG8_STAGE(PG8_SB(1, 1), b3 + hstep, voffB); PG8_STAGE(PG8_SA(1, 0), a3, voffA);
;             PG8_WAIT_V(8); PG8_WAIT_L(0); PG8_BAR; PG8_MMA(1, 0, At, B0); PG8_MMA(1, 1, At, B1); PG8_BAR; PG8_SCHED;
	s_add_i32 s90, 0, 0x18000
	v_add_u32_e32 v183, s90, v174
	s_add_i32 s91, 0, 0x1c000
	ds_read_b128 v[144:147], v183
	ds_read_b128 v[148:151], v183 offset:1024
	ds_read_b128 v[152:155], v183 offset:2048
	ds_read_b128 v[184:187], v183 offset:3072
	v_add_u32_e32 v183, s91, v174
	ds_read_b128 v[188:191], v183
	ds_read_b128 v[192:195], v183 offset:1024
	ds_read_b128 v[208:211], v183 offset:2048
	ds_read_b128 v[214:217], v183 offset:3072
	s_add_u32 s48, s48, s94
	s_addc_u32 s49, s49, 0
	s_mov_b32 m0, s68
	v_lshl_add_u64 v[198:199], s[48:49], 0, v[132:133]
	ds_read_b128 v[218:221], v175 offset:32768
	ds_read_b128 v[222:225], v175 offset:33792
	ds_read_b128 v[226:229], v175 offset:34816
	ds_read_b128 v[230:233], v175 offset:35840
	ds_read_b128 v[234:237], v175 offset:36864
	ds_read_b128 v[238:241], v175 offset:37888
	ds_read_b128 v[242:245], v175 offset:38912
	ds_read_b128 v[246:249], v175 offset:39936
	global_load_lds_dwordx4 v[198:199], off
	v_lshl_add_u64 v[198:199], s[48:49], 0, v[134:135]
	s_mov_b32 m0, s69
	s_nop 0
	global_load_lds_dwordx4 v[198:199], off
	s_waitcnt vmcnt(8)
	s_waitcnt lgkmcnt(0)
	s_barrier
	s_setprio 1
	s_waitcnt lgkmcnt(0)
	v_mfma_f32_16x16x32_bf16 v[124:127], v[144:147], v[218:221], v[124:127]
	v_mfma_f32_16x16x32_bf16 v[120:123], v[152:155], v[218:221], v[120:123]
	v_mfma_f32_16x16x32_bf16 v[108:111], v[144:147], v[226:229], v[108:111]
	v_mfma_f32_16x16x32_bf16 v[104:107], v[152:155], v[226:229], v[104:107]
	v_mfma_f32_16x16x32_bf16 v[92:95], v[144:147], v[234:237], v[92:95]
	v_mfma_f32_16x16x32_bf16 v[88:91], v[152:155], v[234:237], v[88:91]
	v_mfma_f32_16x16x32_bf16 v[76:79], v[144:147], v[242:245], v[76:79]
	v_mfma_f32_16x16x32_bf16 v[72:75], v[152:155], v[242:245], v[72:75]
	v_mfma_f32_16x16x32_bf16 v[124:127], v[148:151], v[222:225], v[124:127]
	v_mfma_f32_16x16x32_bf16 v[120:123], v[184:187], v[222:225], v[120:123]
	v_mfma_f32_16x16x32_bf16 v[108:111], v[148:151], v[230:233], v[108:111]
	v_mfma_f32_16x16x32_bf16 v[104:107], v[184:187], v[230:233], v[104:107]
	v_mfma_f32_16x16x32_bf16 v[92:95], v[148:151], v[238:241], v[92:95]
	v_mfma_f32_16x16x32_bf16 v[88:91], v[184:187], v[238:241], v[88:91]
	v_mfma_f32_16x16x32_bf16 v[76:79], v[148:151], v[246:249], v[76:79]
	v_mfma_f32_16x16x32_bf16 v[72:75], v[184:187], v[246:249], v[72:75]
	v_mfma_f32_16x16x32_bf16 v[116:119], v[188:191], v[218:221], v[116:119]
	v_mfma_f32_16x16x32_bf16 v[112:115], v[208:211], v[218:221], v[112:115]
	v_mfma_f32_16x16x32_bf16 v[100:103], v[188:191], v[226:229], v[100:103]
	v_mfma_f32_16x16x32_bf16 v[96:99], v[208:211], v[226:229], v[96:99]
	v_mfma_f32_16x16x32_bf16 v[84:87], v[188:191], v[234:237], v[84:87]
	v_mfma_f32_16x16x32_bf16 v[80:83], v[208:211], v[234:237], v[80:83]
	v_mfma_f32_16x16x32_bf16 v[68:71], v[188:191], v[242:245], v[68:71]
	v_mfma_f32_16x16x32_bf16 v[64:67], v[208:211], v[242:245], v[64:67]
	v_mfma_f32_16x16x32_bf16 v[116:119], v[192:195], v[222:225], v[116:119]
	v_mfma_f32_16x16x32_bf16 v[112:115], v[214:217], v[222:225], v[112:115]
	v_mfma_f32_16x16x32_bf16 v[100:103], v[192:195], v[230:233], v[100:103]
	v_mfma_f32_16x16x32_bf16 v[96:99], v[214:217], v[230:233], v[96:99]
	v_mfma_f32_16x16x32_bf16 v[84:87], v[192:195], v[238:241], v[84:87]
	v_mfma_f32_16x16x32_bf16 v[80:83], v[214:217], v[238:241], v[80:83]
	v_mfma_f32_16x16x32_bf16 v[68:71], v[192:195], v[246:249], v[68:71]
	v_mfma_f32_16x16x32_bf16 v[64:67], v[214:217], v[246:249], v[64:67]
	s_setprio 0
	s_barrier
	s_add_i32 s48, s90, s65
	v_lshl_add_u64 v[156:157], v[156:157], 0, s[28:29]
	s_mov_b32 m0, s48
	ds_read_b128 v[218:221], v175 offset:49152
	ds_read_b128 v[222:225], v175 offset:50176
	ds_read_b128 v[226:229], v175 offset:51200
	ds_read_b128 v[230:233], v175 offset:52224
	ds_read_b128 v[234:237], v175 offset:53248
	ds_read_b128 v[238:241], v175 offset:54272
	ds_read_b128 v[242:245], v175 offset:55296
	ds_read_b128 v[246:249], v175 offset:56320
	global_load_lds_dwordx4 v[156:157], off
	v_lshl_add_u64 v[156:157], v[250:251], 0, s[28:29]
	s_add_i32 m0, s48, 0x2000
	s_add_i32 s48, s91, s65
	global_load_lds_dwordx4 v[156:157], off
	v_lshl_add_u64 v[156:157], v[178:179], 0, s[28:29]
	s_mov_b32 m0, s48
	s_nop 0
	global_load_lds_dwordx4 v[156:157], off
	v_lshl_add_u64 v[156:157], v[180:181], 0, s[28:29]
	s_add_i32 m0, s48, 0x2000
	s_nop 0
	global_load_lds_dwordx4 v[156:157], off
	v_lshl_add_u64 v[156:157], v[204:205], 0, s[28:29]
	s_mov_b32 m0, s70
	s_nop 0
	global_load_lds_dwordx4 v[156:157], off
	v_lshl_add_u64 v[156:157], v[196:197], 0, s[28:29]
	s_mov_b32 m0, s71
	s_nop 0
	global_load_lds_dwordx4 v[156:157], off
	s_waitcnt vmcnt(8)
	s_waitcnt lgkmcnt(0)
	s_barrier
	s_setprio 1
	s_waitcnt lgkmcnt(0)
	v_mfma_f32_16x16x32_bf16 v[60:63], v[144:147], v[218:221], v[60:63]
	v_mfma_f32_16x16x32_bf16 v[56:59], v[152:155], v[218:221], v[56:59]
	v_mfma_f32_16x16x32_bf16 v[44:47], v[144:147], v[226:229], v[44:47]
	v_mfma_f32_16x16x32_bf16 v[40:43], v[152:155], v[226:229], v[40:43]
	v_mfma_f32_16x16x32_bf16 v[28:31], v[144:147], v[234:237], v[28:31]
	v_mfma_f32_16x16x32_bf16 v[24:27], v[152:155], v[234:237], v[24:27]
	v_mfma_f32_16x16x32_bf16 v[12:15], v[144:147], v[242:245], v[12:15]
	v_mfma_f32_16x16x32_bf16 v[8:11], v[152:155], v[242:245], v[8:11]
	v_mfma_f32_16x16x32_bf16 v[60:63], v[148:151], v[222:225], v[60:63]
	v_mfma_f32_16x16x32_bf16 v[56:59], v[184:187], v[222:225], v[56:59]
	v_mfma_f32_16x16x32_bf16 v[44:47], v[148:151], v[230:233], v[44:47]
	v_mfma_f32_16x16x32_bf16 v[40:43], v[184:187], v[230:233], v[40:43]
	v_mfma_f32_16x16x32_bf16 v[28:31], v[148:151], v[238:241], v[28:31]
	v_mfma_f32_16x16x32_bf16 v[24:27], v[184:187], v[238:241], v[24:27]
	v_mfma_f32_16x16x32_bf16 v[12:15], v[148:151], v[246:249], v[12:15]
	v_mfma_f32_16x16x32_bf16 v[8:11], v[184:187], v[246:249], v[8:11]
	v_mfma_f32_16x16x32_bf16 v[52:55], v[188:191], v[218:221], v[52:55]
	v_mfma_f32_16x16x32_bf16 v[48:51], v[208:211], v[218:221], v[48:51]
	v_mfma_f32_16x16x32_bf16 v[36:39], v[188:191], v[226:229], v[36:39]
	v_mfma_f32_16x16x32_bf16 v[32:35], v[208:211], v[226:229], v[32:35]
	v_mfma_f32_16x16x32_bf16 v[20:23], v[188:191], v[234:237], v[20:23]
	v_mfma_f32_16x16x32_bf16 v[16:19], v[208:211], v[234:237], v[16:19]
	v_mfma_f32_16x16x32_bf16 v[4:7], v[188:191], v[242:245], v[4:7]
	v_mfma_f32_16x16x32_bf16 v[0:3], v[208:211], v[242:245], v[0:3]
	v_mfma_f32_16x16x32_bf16 v[52:55], v[192:195], v[222:225], v[52:55]
	v_mfma_f32_16x16x32_bf16 v[48:51], v[214:217], v[222:225], v[48:51]
	v_mfma_f32_16x16x32_bf16 v[36:39], v[192:195], v[230:233], v[36:39]
	v_mfma_f32_16x16x32_bf16 v[32:35], v[214:217], v[230:233], v[32:35]
	v_mfma_f32_16x16x32_bf16 v[20:23], v[192:195], v[238:241], v[20:23]
	v_mfma_f32_16x16x32_bf16 v[16:19], v[214:217], v[238:241], v[16:19]
	v_mfma_f32_16x16x32_bf16 v[4:7], v[192:195], v[246:249], v[4:7]
	v_mfma_f32_16x16x32_bf16 v[0:3], v[214:217], v[246:249], v[0:3]
	s_setprio 0
	s_barrier
	s_add_u32 s44, s44, 0x100
	s_addc_u32 s45, s45, 0
	s_add_u32 s37, s37, 0x100
	s_addc_u32 s50, s50, 0
	s_cmp_ge_u32 s51, s80
	s_mov_b32 s48, s51
	s_cbranch_scc0 .LBB0_621
